# write-through (sc1) for the bulk stores of the prologue (weight transposes, XN rows) and of the S5-GLU/GDN-output phase, so the following seams have little dirty L2 to write back
# baseline (speedup 1.0000x reference)
.LBB0_8:
	s_waitcnt vmcnt(30)
	v_mul_f32_e32 v23, v74, v23
	v_mul_f32_e32 v2, v2, v25
	s_waitcnt vmcnt(1)
	v_mul_f32_e32 v26, v132, v133
	v_mul_f32_e32 v27, v131, v129
	v_mul_f32_e32 v28, v128, v130
	v_mul_f32_e32 v29, v126, v124
	v_mul_f32_e32 v123, v123, v125
	v_mul_f32_e32 v120, v122, v120
	v_mul_f32_e32 v119, v119, v121
	v_mul_f32_e32 v116, v118, v116
	v_mul_f32_e32 v115, v115, v117
	v_mul_f32_e32 v112, v114, v112
	v_mul_f32_e32 v111, v111, v113
	v_mul_f32_e32 v108, v110, v108
	v_mul_f32_e32 v107, v107, v109
	v_mul_f32_e32 v104, v106, v104
	v_mul_f32_e32 v103, v103, v105
	v_mul_f32_e32 v100, v102, v100
	v_mul_f32_e32 v99, v99, v101
	v_mul_f32_e32 v96, v98, v96
	v_mul_f32_e32 v95, v95, v97
	v_mul_f32_e32 v92, v94, v92
	v_mul_f32_e32 v91, v91, v93
	v_mul_f32_e32 v88, v90, v88
	v_mul_f32_e32 v87, v87, v89
	v_mul_f32_e32 v84, v86, v84
	v_mul_f32_e32 v83, v83, v85
	v_mul_f32_e32 v80, v82, v80
	v_mul_f32_e32 v79, v79, v81
	v_mul_f32_e32 v76, v78, v76
	v_mul_f32_e32 v75, v75, v77
	s_waitcnt vmcnt(0)
	v_mul_f32_e32 v24, v24, v127
	ds_write2_b32 v30, v2, v23 offset1:66
	ds_write2_b32 v30, v75, v76 offset0:132 offset1:198
	ds_write2_b32 v36, v79, v80 offset0:8 offset1:74
	ds_write2_b32 v36, v83, v84 offset0:140 offset1:206
	ds_write2_b32 v37, v87, v88 offset0:16 offset1:82
	ds_write2_b32 v37, v91, v92 offset0:148 offset1:214
	ds_write2_b32 v38, v95, v96 offset0:24 offset1:90
	ds_write2_b32 v38, v99, v100 offset0:156 offset1:222
	ds_write2_b32 v39, v103, v104 offset0:32 offset1:98
	ds_write2_b32 v39, v107, v108 offset0:164 offset1:230
	ds_write2_b32 v40, v111, v112 offset0:40 offset1:106
	ds_write2_b32 v40, v115, v116 offset0:172 offset1:238
	ds_write2_b32 v41, v119, v120 offset0:48 offset1:114
	ds_write2_b32 v41, v123, v29 offset0:180 offset1:246
	ds_write2_b32 v42, v28, v27 offset0:56 offset1:122
	ds_write2_b32 v42, v26, v24 offset0:188 offset1:254
	s_waitcnt lgkmcnt(0)
	ds_read2_b32 v[28:29], v32 offset1:8
	ds_read2_b32 v[76:77], v32 offset0:33 offset1:41
	ds_read2_b32 v[78:79], v32 offset0:66 offset1:74
	ds_read2_b32 v[80:81], v32 offset0:99 offset1:107
	ds_read2_b32 v[82:83], v32 offset0:132 offset1:140
	s_waitcnt lgkmcnt(4)
	v_bfe_u32 v2, v28, 16, 1
	v_add3_u32 v2, v28, v2, s58
	s_waitcnt lgkmcnt(3)
	v_bfe_u32 v23, v76, 16, 1
	v_lshrrev_b32_e32 v2, 16, v2
	v_add3_u32 v23, v76, v23, s58
	ds_read2_b32 v[84:85], v32 offset0:165 offset1:173
	v_and_or_b32 v24, v23, s59, v2
	s_waitcnt lgkmcnt(3)
	v_bfe_u32 v2, v78, 16, 1
	v_add3_u32 v2, v78, v2, s58
	s_waitcnt lgkmcnt(2)
	v_bfe_u32 v23, v80, 16, 1
	ds_read2_b32 v[86:87], v32 offset0:198 offset1:206
	v_lshrrev_b32_e32 v2, 16, v2
	v_add3_u32 v23, v80, v23, s58
	ds_read2_b32 v[88:89], v32 offset0:231 offset1:239
	v_and_or_b32 v25, v23, s59, v2
	s_waitcnt lgkmcnt(3)
	v_bfe_u32 v2, v82, 16, 1
	v_add3_u32 v2, v82, v2, s58
	s_waitcnt lgkmcnt(2)
	v_bfe_u32 v23, v84, 16, 1
	v_lshrrev_b32_e32 v2, 16, v2
	v_add3_u32 v23, v84, v23, s58
	v_and_or_b32 v26, v23, s59, v2
	s_waitcnt lgkmcnt(1)
	v_bfe_u32 v2, v86, 16, 1
	v_add3_u32 v2, v86, v2, s58
	s_waitcnt lgkmcnt(0)
	v_bfe_u32 v23, v88, 16, 1
	v_lshrrev_b32_e32 v2, 16, v2
	v_add3_u32 v23, v88, v23, s58
	v_add_u32_e32 v90, s4, v31
	s_ashr_i32 s9, s8, 31
	v_and_or_b32 v27, v23, s59, v2
	v_ashrrev_i32_e32 v91, 31, v90
	v_bfe_u32 v2, v29, 16, 1
	v_lshl_add_u64 v[74:75], s[8:9], 1, v[20:21]
	v_lshlrev_b64 v[92:93], 11, v[90:91]
	v_add3_u32 v2, v29, v2, s58
	v_bfe_u32 v23, v77, 16, 1
	v_lshl_add_u64 v[92:93], v[74:75], 0, v[92:93]
	v_lshrrev_b32_e32 v2, 16, v2
	v_add3_u32 v23, v77, v23, s58
	global_store_dwordx4 v[92:93], v[24:27], off sc1
	v_add_u32_e32 v28, 8, v90
	v_ashrrev_i32_e32 v29, 31, v28
	v_and_or_b32 v24, v23, s59, v2
	v_bfe_u32 v2, v79, 16, 1
	v_add3_u32 v2, v79, v2, s58
	v_bfe_u32 v23, v81, 16, 1
	v_lshrrev_b32_e32 v2, 16, v2
	v_add3_u32 v23, v81, v23, s58
	v_and_or_b32 v25, v23, s59, v2
	v_bfe_u32 v2, v83, 16, 1
	v_add3_u32 v2, v83, v2, s58
	v_bfe_u32 v23, v85, 16, 1
	v_lshrrev_b32_e32 v2, 16, v2
	v_add3_u32 v23, v85, v23, s58
	v_and_or_b32 v26, v23, s59, v2
	v_bfe_u32 v2, v87, 16, 1
	v_add3_u32 v2, v87, v2, s58
	v_bfe_u32 v23, v89, 16, 1
	v_lshrrev_b32_e32 v2, 16, v2
	v_add3_u32 v23, v89, v23, s58
	v_lshlrev_b64 v[28:29], 11, v[28:29]
	v_and_or_b32 v27, v23, s59, v2
	ds_read2_b32 v[76:77], v32 offset0:16 offset1:24
	v_lshl_add_u64 v[28:29], v[74:75], 0, v[28:29]
	global_store_dwordx4 v[28:29], v[24:27], off sc1
	ds_read2_b32 v[28:29], v32 offset0:49 offset1:57
	ds_read2_b32 v[78:79], v32 offset0:82 offset1:90
	ds_read2_b32 v[80:81], v32 offset0:115 offset1:123
	s_waitcnt lgkmcnt(3)
	v_bfe_u32 v2, v76, 16, 1
	v_add3_u32 v2, v76, v2, s58
	s_waitcnt lgkmcnt(2)
	v_bfe_u32 v23, v28, 16, 1
	ds_read2_b32 v[82:83], v32 offset0:148 offset1:156
	v_lshrrev_b32_e32 v2, 16, v2
	v_add3_u32 v23, v28, v23, s58
	ds_read2_b32 v[84:85], v32 offset0:181 offset1:189
	v_and_or_b32 v24, v23, s59, v2
	s_waitcnt lgkmcnt(3)
	v_bfe_u32 v2, v78, 16, 1
	v_add3_u32 v2, v78, v2, s58
	s_waitcnt lgkmcnt(2)
	v_bfe_u32 v23, v80, 16, 1
	ds_read2_b32 v[86:87], v32 offset0:214 offset1:222
	v_lshrrev_b32_e32 v2, 16, v2
	v_add3_u32 v23, v80, v23, s58
	ds_read2_b32 v[88:89], v32 offset0:247 offset1:255
	v_and_or_b32 v25, v23, s59, v2
	s_waitcnt lgkmcnt(3)
	v_bfe_u32 v2, v82, 16, 1
	v_add3_u32 v2, v82, v2, s58
	s_waitcnt lgkmcnt(2)
	v_bfe_u32 v23, v84, 16, 1
	v_lshrrev_b32_e32 v2, 16, v2
	v_add3_u32 v23, v84, v23, s58
	v_and_or_b32 v26, v23, s59, v2
	s_waitcnt lgkmcnt(1)
	v_bfe_u32 v2, v86, 16, 1
	v_add3_u32 v2, v86, v2, s58
	s_waitcnt lgkmcnt(0)
	v_bfe_u32 v23, v88, 16, 1
	v_lshrrev_b32_e32 v2, 16, v2
	v_add3_u32 v23, v88, v23, s58
	v_add_u32_e32 v92, 16, v90
	v_and_or_b32 v27, v23, s59, v2
	v_ashrrev_i32_e32 v93, 31, v92
	v_bfe_u32 v2, v77, 16, 1
	v_lshlrev_b64 v[92:93], 11, v[92:93]
	v_add3_u32 v2, v77, v2, s58
	v_bfe_u32 v23, v29, 16, 1
	v_lshl_add_u64 v[92:93], v[74:75], 0, v[92:93]
	v_lshrrev_b32_e32 v2, 16, v2
	v_add3_u32 v23, v29, v23, s58
	global_store_dwordx4 v[92:93], v[24:27], off sc1
	v_add_u32_e32 v28, 24, v90
	v_ashrrev_i32_e32 v29, 31, v28
	v_and_or_b32 v24, v23, s59, v2
	v_bfe_u32 v2, v79, 16, 1
	v_add3_u32 v2, v79, v2, s58
	v_bfe_u32 v23, v81, 16, 1
	v_lshrrev_b32_e32 v2, 16, v2
	v_add3_u32 v23, v81, v23, s58
	v_and_or_b32 v25, v23, s59, v2
	v_bfe_u32 v2, v83, 16, 1
	v_add3_u32 v2, v83, v2, s58
	v_bfe_u32 v23, v85, 16, 1
	v_lshrrev_b32_e32 v2, 16, v2
	v_add3_u32 v23, v85, v23, s58
	v_and_or_b32 v26, v23, s59, v2
	v_bfe_u32 v2, v87, 16, 1
	v_add3_u32 v2, v87, v2, s58
	v_bfe_u32 v23, v89, 16, 1
	v_lshrrev_b32_e32 v2, 16, v2
	v_add3_u32 v23, v89, v23, s58
	v_lshlrev_b64 v[28:29], 11, v[28:29]
	v_and_or_b32 v27, v23, s59, v2
	v_lshl_add_u64 v[28:29], v[74:75], 0, v[28:29]
	global_store_dwordx4 v[28:29], v[24:27], off sc1
	s_waitcnt lgkmcnt(0)

.LBB0_10:
	s_cmpk_gt_i32 s74, 0x6ff
	s_mov_b64 s[0:1], -1
	s_cbranch_scc0 .LBB0_232
	s_cmpk_gt_u32 s74, 0x8ff
	s_cbranch_scc0 .LBB0_229
	s_cmpk_gt_u32 s74, 0x10ff
	s_cbranch_scc0 .LBB0_162
	s_cmpk_gt_u32 s74, 0x18ff
	s_cbranch_scc0 .LBB0_159
	s_cmpk_gt_u32 s74, 0x1fff
	s_cbranch_scc0 .LBB0_92
	s_cmpk_gt_u32 s74, 0x201f
	s_cbranch_scc0 .LBB0_89
	s_cmpk_gt_u32 s74, 0x221f
	s_cbranch_scc0 .LBB0_86
	s_cmpk_gt_u32 s74, 0x2a1f
	s_cbranch_scc0 .LBB0_19
	s_load_dwordx2 s[4:5], s[92:93], 0x100
	s_and_b32 s0, s14, 0x3e0
	s_and_b32 s1, s16, 0x1ffc0
	s_lshl_b32 s6, s0, 2
	v_or_b32_e32 v2, s1, v1
	s_waitcnt lgkmcnt(0)
	s_add_u32 s4, s4, s6
	s_addc_u32 s5, s5, 0
	v_mov_b32_e32 v23, v3
	v_lshl_add_u64 v[24:25], s[4:5], 0, v[22:23]
	v_lshlrev_b32_e32 v2, 12, v2
	v_lshl_add_u64 v[24:25], v[24:25], 0, v[2:3]
	v_add_co_u32_e32 v26, vcc, s20, v24
	s_lshl_b32 s12, s1, 1
	s_nop 0
	v_addc_co_u32_e32 v27, vcc, 0, v25, vcc
	v_add_co_u32_e32 v28, vcc, s21, v24
	s_nop 1
	v_addc_co_u32_e32 v29, vcc, 0, v25, vcc
	v_add_co_u32_e32 v74, vcc, s22, v24
	s_nop 1
	v_addc_co_u32_e32 v75, vcc, 0, v25, vcc
	v_add_co_u32_e32 v76, vcc, s23, v24
	s_nop 1
	v_addc_co_u32_e32 v77, vcc, 0, v25, vcc
	v_add_co_u32_e32 v78, vcc, s30, v24
	s_nop 1
	v_addc_co_u32_e32 v79, vcc, 0, v25, vcc
	v_add_co_u32_e32 v80, vcc, s31, v24
	s_nop 1
	v_addc_co_u32_e32 v81, vcc, 0, v25, vcc
	v_add_co_u32_e32 v82, vcc, s33, v24
	s_nop 1
	v_addc_co_u32_e32 v83, vcc, 0, v25, vcc
	global_load_dword v2, v[24:25], off
	global_load_dword v23, v[26:27], off
	global_load_dword v86, v[28:29], off
	global_load_dword v87, v[74:75], off
	global_load_dword v88, v[76:77], off
	global_load_dword v89, v[78:79], off
	global_load_dword v90, v[80:81], off
	global_load_dword v91, v[82:83], off
	v_add_co_u32_e32 v26, vcc, s34, v24
	s_nop 1
	v_addc_co_u32_e32 v27, vcc, 0, v25, vcc
	v_add_co_u32_e32 v28, vcc, s35, v24
	s_nop 1
	v_addc_co_u32_e32 v29, vcc, 0, v25, vcc
	v_add_co_u32_e32 v74, vcc, s36, v24
	s_nop 1
	v_addc_co_u32_e32 v75, vcc, 0, v25, vcc
	v_add_co_u32_e32 v76, vcc, s37, v24
	s_nop 1
	v_addc_co_u32_e32 v77, vcc, 0, v25, vcc
	v_add_co_u32_e32 v78, vcc, s38, v24
	s_nop 1
	v_addc_co_u32_e32 v79, vcc, 0, v25, vcc
	v_add_co_u32_e32 v80, vcc, s39, v24
	s_nop 1
	v_addc_co_u32_e32 v81, vcc, 0, v25, vcc
	v_add_co_u32_e32 v82, vcc, s40, v24
	s_nop 1
	v_addc_co_u32_e32 v83, vcc, 0, v25, vcc
	v_add_co_u32_e32 v84, vcc, s41, v24
	s_nop 1
	v_addc_co_u32_e32 v85, vcc, 0, v25, vcc
	global_load_dword v92, v[26:27], off
	global_load_dword v93, v[28:29], off
	global_load_dword v94, v[74:75], off
	global_load_dword v95, v[76:77], off
	global_load_dword v96, v[78:79], off
	global_load_dword v97, v[80:81], off
	global_load_dword v98, v[82:83], off
	global_load_dword v99, v[84:85], off
	v_add_co_u32_e32 v26, vcc, s42, v24
	s_nop 1
	v_addc_co_u32_e32 v27, vcc, 0, v25, vcc
	v_add_co_u32_e32 v28, vcc, s43, v24
	s_nop 1
	v_addc_co_u32_e32 v29, vcc, 0, v25, vcc
	v_add_co_u32_e32 v74, vcc, s44, v24
	s_nop 1
	v_addc_co_u32_e32 v75, vcc, 0, v25, vcc
	v_add_co_u32_e32 v76, vcc, s45, v24
	s_nop 1
	v_addc_co_u32_e32 v77, vcc, 0, v25, vcc
	v_add_co_u32_e32 v78, vcc, s46, v24
	s_nop 1
	v_addc_co_u32_e32 v79, vcc, 0, v25, vcc
	v_add_co_u32_e32 v80, vcc, s47, v24
	s_nop 1
	v_addc_co_u32_e32 v81, vcc, 0, v25, vcc
	v_add_co_u32_e32 v82, vcc, s48, v24
	s_nop 1
	v_addc_co_u32_e32 v83, vcc, 0, v25, vcc
	v_add_co_u32_e32 v84, vcc, s49, v24
	s_nop 1
	v_addc_co_u32_e32 v85, vcc, 0, v25, vcc
	global_load_dword v100, v[26:27], off
	global_load_dword v101, v[28:29], off
	global_load_dword v102, v[74:75], off
	global_load_dword v103, v[76:77], off
	global_load_dword v104, v[78:79], off
	global_load_dword v105, v[80:81], off
	global_load_dword v106, v[82:83], off
	s_nop 0
	global_load_dword v84, v[84:85], off
	v_add_co_u32_e32 v26, vcc, s50, v24
	s_nop 1
	v_addc_co_u32_e32 v27, vcc, 0, v25, vcc
	v_add_co_u32_e32 v28, vcc, s51, v24
	s_nop 1
	v_addc_co_u32_e32 v29, vcc, 0, v25, vcc
	v_add_co_u32_e32 v74, vcc, s52, v24
	s_nop 1
	v_addc_co_u32_e32 v75, vcc, 0, v25, vcc
	v_add_co_u32_e32 v76, vcc, s53, v24
	s_nop 1
	v_addc_co_u32_e32 v77, vcc, 0, v25, vcc
	v_add_co_u32_e32 v78, vcc, s54, v24
	s_nop 1
	v_addc_co_u32_e32 v79, vcc, 0, v25, vcc
	v_add_co_u32_e32 v80, vcc, s55, v24
	s_nop 1
	v_addc_co_u32_e32 v81, vcc, 0, v25, vcc
	v_add_co_u32_e32 v82, vcc, s56, v24
	s_nop 1
	v_addc_co_u32_e32 v83, vcc, 0, v25, vcc
	v_add_co_u32_e32 v24, vcc, s57, v24
	s_nop 1
	v_addc_co_u32_e32 v25, vcc, 0, v25, vcc
	global_load_dword v26, v[26:27], off
	s_nop 0
	global_load_dword v27, v[28:29], off
	s_nop 0
	global_load_dword v28, v[74:75], off
	global_load_dword v29, v[76:77], off
	s_nop 0
	global_load_dword v74, v[78:79], off
	global_load_dword v75, v[80:81], off
	global_load_dword v76, v[82:83], off
	s_nop 0
	global_load_dword v24, v[24:25], off
	s_waitcnt vmcnt(30)
	ds_write2_b32 v30, v2, v23 offset1:66
	s_waitcnt vmcnt(28)
	ds_write2_b32 v30, v86, v87 offset0:132 offset1:198
	s_waitcnt vmcnt(26)
	ds_write2_b32 v36, v88, v89 offset0:8 offset1:74
	s_waitcnt vmcnt(24)
	ds_write2_b32 v36, v90, v91 offset0:140 offset1:206
	s_waitcnt vmcnt(22)
	ds_write2_b32 v37, v92, v93 offset0:16 offset1:82
	s_waitcnt vmcnt(20)
	ds_write2_b32 v37, v94, v95 offset0:148 offset1:214
	s_waitcnt vmcnt(18)
	ds_write2_b32 v38, v96, v97 offset0:24 offset1:90
	s_waitcnt vmcnt(16)
	ds_write2_b32 v38, v98, v99 offset0:156 offset1:222
	s_waitcnt vmcnt(14)
	ds_write2_b32 v39, v100, v101 offset0:32 offset1:98
	s_waitcnt vmcnt(12)
	ds_write2_b32 v39, v102, v103 offset0:164 offset1:230
	s_waitcnt vmcnt(10)
	ds_write2_b32 v40, v104, v105 offset0:40 offset1:106
	s_waitcnt vmcnt(8)
	ds_write2_b32 v40, v106, v84 offset0:172 offset1:238
	s_waitcnt vmcnt(6)
	ds_write2_b32 v41, v26, v27 offset0:48 offset1:114
	s_waitcnt vmcnt(4)
	ds_write2_b32 v41, v28, v29 offset0:180 offset1:246
	s_waitcnt vmcnt(2)
	ds_write2_b32 v42, v74, v75 offset0:56 offset1:122
	s_waitcnt vmcnt(0)
	ds_write2_b32 v42, v76, v24 offset0:188 offset1:254
	s_waitcnt lgkmcnt(0)
	ds_read2_b32 v[28:29], v32 offset1:8
	ds_read2_b32 v[76:77], v32 offset0:33 offset1:41
	ds_read2_b32 v[78:79], v32 offset0:66 offset1:74
	ds_read2_b32 v[80:81], v32 offset0:99 offset1:107
	ds_read2_b32 v[82:83], v32 offset0:132 offset1:140
	s_waitcnt lgkmcnt(4)
	v_bfe_u32 v2, v28, 16, 1
	v_add3_u32 v2, v28, v2, s58
	s_waitcnt lgkmcnt(3)
	v_bfe_u32 v23, v76, 16, 1
	v_lshrrev_b32_e32 v2, 16, v2
	v_add3_u32 v23, v76, v23, s58
	ds_read2_b32 v[84:85], v32 offset0:165 offset1:173
	v_and_or_b32 v24, v23, s59, v2
	s_waitcnt lgkmcnt(3)
	v_bfe_u32 v2, v78, 16, 1
	v_add3_u32 v2, v78, v2, s58
	s_waitcnt lgkmcnt(2)
	v_bfe_u32 v23, v80, 16, 1
	ds_read2_b32 v[86:87], v32 offset0:198 offset1:206
	v_lshrrev_b32_e32 v2, 16, v2
	v_add3_u32 v23, v80, v23, s58
	ds_read2_b32 v[88:89], v32 offset0:231 offset1:239
	v_and_or_b32 v25, v23, s59, v2
	s_waitcnt lgkmcnt(3)
	v_bfe_u32 v2, v82, 16, 1
	v_add3_u32 v2, v82, v2, s58
	s_waitcnt lgkmcnt(2)
	v_bfe_u32 v23, v84, 16, 1
	v_lshrrev_b32_e32 v2, 16, v2
	v_add3_u32 v23, v84, v23, s58
	v_and_or_b32 v26, v23, s59, v2
	s_waitcnt lgkmcnt(1)
	v_bfe_u32 v2, v86, 16, 1
	v_add3_u32 v2, v86, v2, s58
	s_waitcnt lgkmcnt(0)
	v_bfe_u32 v23, v88, 16, 1
	v_lshrrev_b32_e32 v2, 16, v2
	v_add3_u32 v23, v88, v23, s58
	v_and_or_b32 v27, v23, s59, v2
	v_or_b32_e32 v2, s0, v31
	v_lshl_add_u64 v[74:75], v[4:5], 0, s[12:13]
	v_lshlrev_b32_e32 v2, 13, v2
	v_lshl_add_u64 v[90:91], v[74:75], 0, v[2:3]
	v_bfe_u32 v2, v29, 16, 1
	v_add3_u32 v2, v29, v2, s58
	v_bfe_u32 v23, v77, 16, 1
	v_lshrrev_b32_e32 v2, 16, v2
	v_add3_u32 v23, v77, v23, s58
	global_store_dwordx4 v[90:91], v[24:27], off sc1
	ds_read2_b32 v[28:29], v32 offset0:16 offset1:24
	s_nop 0
	v_and_or_b32 v24, v23, s59, v2
	v_bfe_u32 v2, v79, 16, 1
	v_add3_u32 v2, v79, v2, s58
	v_bfe_u32 v23, v81, 16, 1
	v_lshrrev_b32_e32 v2, 16, v2
	v_add3_u32 v23, v81, v23, s58
	v_and_or_b32 v25, v23, s59, v2
	v_bfe_u32 v2, v83, 16, 1
	v_add3_u32 v2, v83, v2, s58
	v_bfe_u32 v23, v85, 16, 1
	v_lshrrev_b32_e32 v2, 16, v2
	v_add3_u32 v23, v85, v23, s58
	v_and_or_b32 v26, v23, s59, v2
	v_bfe_u32 v2, v87, 16, 1
	v_add3_u32 v2, v87, v2, s58
	v_bfe_u32 v23, v89, 16, 1
	v_lshrrev_b32_e32 v2, 16, v2
	v_add3_u32 v23, v89, v23, s58
	v_and_or_b32 v27, v23, s59, v2
	v_or_b32_e32 v2, s0, v33
	v_lshlrev_b32_e32 v2, 13, v2
	v_lshl_add_u64 v[76:77], v[74:75], 0, v[2:3]
	global_store_dwordx4 v[76:77], v[24:27], off sc1
	ds_read2_b32 v[76:77], v32 offset0:49 offset1:57
	ds_read2_b32 v[78:79], v32 offset0:82 offset1:90
	ds_read2_b32 v[80:81], v32 offset0:115 offset1:123
	s_waitcnt lgkmcnt(3)
	v_bfe_u32 v2, v28, 16, 1
	v_add3_u32 v2, v28, v2, s58
	s_waitcnt lgkmcnt(2)
	v_bfe_u32 v23, v76, 16, 1
	ds_read2_b32 v[82:83], v32 offset0:148 offset1:156
	v_lshrrev_b32_e32 v2, 16, v2
	v_add3_u32 v23, v76, v23, s58
	ds_read2_b32 v[84:85], v32 offset0:181 offset1:189
	v_and_or_b32 v24, v23, s59, v2
	s_waitcnt lgkmcnt(3)
	v_bfe_u32 v2, v78, 16, 1
	v_add3_u32 v2, v78, v2, s58
	s_waitcnt lgkmcnt(2)
	v_bfe_u32 v23, v80, 16, 1
	ds_read2_b32 v[86:87], v32 offset0:214 offset1:222
	v_lshrrev_b32_e32 v2, 16, v2
	v_add3_u32 v23, v80, v23, s58
	ds_read2_b32 v[88:89], v32 offset0:247 offset1:255
	v_and_or_b32 v25, v23, s59, v2
	s_waitcnt lgkmcnt(3)
	v_bfe_u32 v2, v82, 16, 1
	v_add3_u32 v2, v82, v2, s58
	s_waitcnt lgkmcnt(2)
	v_bfe_u32 v23, v84, 16, 1
	v_lshrrev_b32_e32 v2, 16, v2
	v_add3_u32 v23, v84, v23, s58
	v_and_or_b32 v26, v23, s59, v2
	s_waitcnt lgkmcnt(1)
	v_bfe_u32 v2, v86, 16, 1
	v_add3_u32 v2, v86, v2, s58
	s_waitcnt lgkmcnt(0)
	v_bfe_u32 v23, v88, 16, 1
	v_lshrrev_b32_e32 v2, 16, v2
	v_add3_u32 v23, v88, v23, s58
	v_and_or_b32 v27, v23, s59, v2
	v_or_b32_e32 v2, s0, v34
	v_lshlrev_b32_e32 v2, 13, v2
	v_lshl_add_u64 v[90:91], v[74:75], 0, v[2:3]
	v_bfe_u32 v2, v29, 16, 1
	v_add3_u32 v2, v29, v2, s58
	v_bfe_u32 v23, v77, 16, 1
	v_lshrrev_b32_e32 v2, 16, v2
	v_add3_u32 v23, v77, v23, s58
	global_store_dwordx4 v[90:91], v[24:27], off sc1
	s_nop 1
	v_and_or_b32 v24, v23, s59, v2
	v_bfe_u32 v2, v79, 16, 1
	v_add3_u32 v2, v79, v2, s58
	v_bfe_u32 v23, v81, 16, 1
	v_lshrrev_b32_e32 v2, 16, v2
	v_add3_u32 v23, v81, v23, s58
	v_and_or_b32 v25, v23, s59, v2
	v_bfe_u32 v2, v83, 16, 1
	v_add3_u32 v2, v83, v2, s58
	v_bfe_u32 v23, v85, 16, 1
	v_lshrrev_b32_e32 v2, 16, v2
	v_add3_u32 v23, v85, v23, s58
	v_and_or_b32 v26, v23, s59, v2
	v_bfe_u32 v2, v87, 16, 1
	v_add3_u32 v2, v87, v2, s58
	v_bfe_u32 v23, v89, 16, 1
	v_lshrrev_b32_e32 v2, 16, v2
	v_add3_u32 v23, v89, v23, s58
	v_and_or_b32 v27, v23, s59, v2
	v_or_b32_e32 v2, s0, v35
	v_lshlrev_b32_e32 v2, 13, v2
	v_lshl_add_u64 v[28:29], v[74:75], 0, v[2:3]
	global_store_dwordx4 v[28:29], v[24:27], off sc1
	s_waitcnt lgkmcnt(0)
	s_mov_b64 s[0:1], 0

.LBB0_84:
	s_waitcnt vmcnt(30)
	v_mul_f32_e32 v26, v28, v26
	v_mul_f32_e32 v23, v23, v27
	s_waitcnt vmcnt(1)
	v_mul_f32_e32 v24, v132, v133
	v_mul_f32_e32 v25, v131, v129
	v_mul_f32_e32 v29, v127, v130
	v_mul_f32_e32 v75, v126, v124
	v_mul_f32_e32 v123, v123, v125
	v_mul_f32_e32 v120, v122, v120
	v_mul_f32_e32 v119, v119, v121
	v_mul_f32_e32 v116, v118, v116
	v_mul_f32_e32 v115, v115, v117
	v_mul_f32_e32 v112, v114, v112
	v_mul_f32_e32 v111, v111, v113
	v_mul_f32_e32 v108, v110, v108
	v_mul_f32_e32 v107, v107, v109
	v_mul_f32_e32 v104, v106, v104
	v_mul_f32_e32 v103, v103, v105
	v_mul_f32_e32 v100, v102, v100
	v_mul_f32_e32 v99, v99, v101
	v_mul_f32_e32 v96, v98, v96
	v_mul_f32_e32 v95, v95, v97
	v_mul_f32_e32 v92, v94, v92
	v_mul_f32_e32 v91, v91, v93
	v_mul_f32_e32 v88, v90, v88
	v_mul_f32_e32 v87, v87, v89
	v_mul_f32_e32 v84, v86, v84
	v_mul_f32_e32 v83, v83, v85
	v_mul_f32_e32 v80, v82, v80
	v_mul_f32_e32 v79, v79, v81
	v_mul_f32_e32 v76, v78, v76
	v_mul_f32_e32 v74, v74, v77
	s_waitcnt vmcnt(0)
	v_mul_f32_e32 v2, v2, v128
	ds_write2_b32 v30, v23, v26 offset1:66
	ds_write2_b32 v30, v74, v76 offset0:132 offset1:198
	ds_write2_b32 v36, v79, v80 offset0:8 offset1:74
	ds_write2_b32 v36, v83, v84 offset0:140 offset1:206
	ds_write2_b32 v37, v87, v88 offset0:16 offset1:82
	ds_write2_b32 v37, v91, v92 offset0:148 offset1:214
	ds_write2_b32 v38, v95, v96 offset0:24 offset1:90
	ds_write2_b32 v38, v99, v100 offset0:156 offset1:222
	ds_write2_b32 v39, v103, v104 offset0:32 offset1:98
	ds_write2_b32 v39, v107, v108 offset0:164 offset1:230
	ds_write2_b32 v40, v111, v112 offset0:40 offset1:106
	ds_write2_b32 v40, v115, v116 offset0:172 offset1:238
	ds_write2_b32 v41, v119, v120 offset0:48 offset1:114
	ds_write2_b32 v41, v123, v75 offset0:180 offset1:246
	ds_write2_b32 v42, v29, v25 offset0:56 offset1:122
	ds_write2_b32 v42, v24, v2 offset0:188 offset1:254
	s_waitcnt lgkmcnt(0)
	ds_read2_b32 v[28:29], v32 offset1:8
	ds_read2_b32 v[76:77], v32 offset0:33 offset1:41
	ds_read2_b32 v[78:79], v32 offset0:66 offset1:74
	ds_read2_b32 v[80:81], v32 offset0:99 offset1:107
	ds_read2_b32 v[82:83], v32 offset0:132 offset1:140
	s_waitcnt lgkmcnt(4)
	v_bfe_u32 v2, v28, 16, 1
	v_add3_u32 v2, v28, v2, s58
	s_waitcnt lgkmcnt(3)
	v_bfe_u32 v23, v76, 16, 1
	v_lshrrev_b32_e32 v2, 16, v2
	v_add3_u32 v23, v76, v23, s58
	ds_read2_b32 v[84:85], v32 offset0:165 offset1:173
	v_and_or_b32 v24, v23, s59, v2
	s_waitcnt lgkmcnt(3)
	v_bfe_u32 v2, v78, 16, 1
	v_add3_u32 v2, v78, v2, s58
	s_waitcnt lgkmcnt(2)
	v_bfe_u32 v23, v80, 16, 1
	ds_read2_b32 v[86:87], v32 offset0:198 offset1:206
	v_lshrrev_b32_e32 v2, 16, v2
	v_add3_u32 v23, v80, v23, s58
	ds_read2_b32 v[88:89], v32 offset0:231 offset1:239
	v_and_or_b32 v25, v23, s59, v2
	s_waitcnt lgkmcnt(3)
	v_bfe_u32 v2, v82, 16, 1
	v_add3_u32 v2, v82, v2, s58
	s_waitcnt lgkmcnt(2)
	v_bfe_u32 v23, v84, 16, 1
	v_lshrrev_b32_e32 v2, 16, v2
	v_add3_u32 v23, v84, v23, s58
	v_and_or_b32 v26, v23, s59, v2
	s_waitcnt lgkmcnt(1)
	v_bfe_u32 v2, v86, 16, 1
	v_add3_u32 v2, v86, v2, s58
	s_waitcnt lgkmcnt(0)
	v_bfe_u32 v23, v88, 16, 1
	v_lshrrev_b32_e32 v2, 16, v2
	v_add3_u32 v23, v88, v23, s58
	s_lshl_b32 s12, s5, 1
	v_and_or_b32 v27, v23, s59, v2
	v_or_b32_e32 v2, s4, v31
	v_lshl_add_u64 v[74:75], v[6:7], 0, s[12:13]
	v_lshlrev_b32_e32 v2, 11, v2
	v_lshl_add_u64 v[90:91], v[74:75], 0, v[2:3]
	v_bfe_u32 v2, v29, 16, 1
	v_add3_u32 v2, v29, v2, s58
	v_bfe_u32 v23, v77, 16, 1
	v_lshrrev_b32_e32 v2, 16, v2
	v_add3_u32 v23, v77, v23, s58
	global_store_dwordx4 v[90:91], v[24:27], off sc1
	ds_read2_b32 v[28:29], v32 offset0:16 offset1:24
	s_nop 0
	v_and_or_b32 v24, v23, s59, v2
	v_bfe_u32 v2, v79, 16, 1
	v_add3_u32 v2, v79, v2, s58
	v_bfe_u32 v23, v81, 16, 1
	v_lshrrev_b32_e32 v2, 16, v2
	v_add3_u32 v23, v81, v23, s58
	v_and_or_b32 v25, v23, s59, v2
	v_bfe_u32 v2, v83, 16, 1
	v_add3_u32 v2, v83, v2, s58
	v_bfe_u32 v23, v85, 16, 1
	v_lshrrev_b32_e32 v2, 16, v2
	v_add3_u32 v23, v85, v23, s58
	v_and_or_b32 v26, v23, s59, v2
	v_bfe_u32 v2, v87, 16, 1
	v_add3_u32 v2, v87, v2, s58
	v_bfe_u32 v23, v89, 16, 1
	v_lshrrev_b32_e32 v2, 16, v2
	v_add3_u32 v23, v89, v23, s58
	v_and_or_b32 v27, v23, s59, v2
	v_or_b32_e32 v2, s4, v33
	v_lshlrev_b32_e32 v2, 11, v2
	v_lshl_add_u64 v[76:77], v[74:75], 0, v[2:3]
	global_store_dwordx4 v[76:77], v[24:27], off sc1
	ds_read2_b32 v[76:77], v32 offset0:49 offset1:57
	ds_read2_b32 v[78:79], v32 offset0:82 offset1:90
	ds_read2_b32 v[80:81], v32 offset0:115 offset1:123
	s_waitcnt lgkmcnt(3)
	v_bfe_u32 v2, v28, 16, 1
	v_add3_u32 v2, v28, v2, s58
	s_waitcnt lgkmcnt(2)
	v_bfe_u32 v23, v76, 16, 1
	ds_read2_b32 v[82:83], v32 offset0:148 offset1:156
	v_lshrrev_b32_e32 v2, 16, v2
	v_add3_u32 v23, v76, v23, s58
	ds_read2_b32 v[84:85], v32 offset0:181 offset1:189
	v_and_or_b32 v24, v23, s59, v2
	s_waitcnt lgkmcnt(3)
	v_bfe_u32 v2, v78, 16, 1
	v_add3_u32 v2, v78, v2, s58
	s_waitcnt lgkmcnt(2)
	v_bfe_u32 v23, v80, 16, 1
	ds_read2_b32 v[86:87], v32 offset0:214 offset1:222
	v_lshrrev_b32_e32 v2, 16, v2
	v_add3_u32 v23, v80, v23, s58
	ds_read2_b32 v[88:89], v32 offset0:247 offset1:255
	v_and_or_b32 v25, v23, s59, v2
	s_waitcnt lgkmcnt(3)
	v_bfe_u32 v2, v82, 16, 1
	v_add3_u32 v2, v82, v2, s58
	s_waitcnt lgkmcnt(2)
	v_bfe_u32 v23, v84, 16, 1
	v_lshrrev_b32_e32 v2, 16, v2
	v_add3_u32 v23, v84, v23, s58
	v_and_or_b32 v26, v23, s59, v2
	s_waitcnt lgkmcnt(1)
	v_bfe_u32 v2, v86, 16, 1
	v_add3_u32 v2, v86, v2, s58
	s_waitcnt lgkmcnt(0)
	v_bfe_u32 v23, v88, 16, 1
	v_lshrrev_b32_e32 v2, 16, v2
	v_add3_u32 v23, v88, v23, s58
	v_and_or_b32 v27, v23, s59, v2
	v_or_b32_e32 v2, s4, v34
	v_lshlrev_b32_e32 v2, 11, v2
	v_lshl_add_u64 v[90:91], v[74:75], 0, v[2:3]
	v_bfe_u32 v2, v29, 16, 1
	v_add3_u32 v2, v29, v2, s58
	v_bfe_u32 v23, v77, 16, 1
	v_lshrrev_b32_e32 v2, 16, v2
	v_add3_u32 v23, v77, v23, s58
	global_store_dwordx4 v[90:91], v[24:27], off sc1
	s_nop 1
	v_and_or_b32 v24, v23, s59, v2
	v_bfe_u32 v2, v79, 16, 1
	v_add3_u32 v2, v79, v2, s58
	v_bfe_u32 v23, v81, 16, 1
	v_lshrrev_b32_e32 v2, 16, v2
	v_add3_u32 v23, v81, v23, s58
	v_and_or_b32 v25, v23, s59, v2
	v_bfe_u32 v2, v83, 16, 1
	v_add3_u32 v2, v83, v2, s58
	v_bfe_u32 v23, v85, 16, 1
	v_lshrrev_b32_e32 v2, 16, v2
	v_add3_u32 v23, v85, v23, s58
	v_and_or_b32 v26, v23, s59, v2
	v_bfe_u32 v2, v87, 16, 1
	v_add3_u32 v2, v87, v2, s58
	v_bfe_u32 v23, v89, 16, 1
	v_lshrrev_b32_e32 v2, 16, v2
	v_add3_u32 v23, v89, v23, s58
	v_and_or_b32 v27, v23, s59, v2
	v_or_b32_e32 v2, s4, v35
	v_lshlrev_b32_e32 v2, 11, v2
	v_lshl_add_u64 v[28:29], v[74:75], 0, v[2:3]
	global_store_dwordx4 v[28:29], v[24:27], off sc1
	s_waitcnt lgkmcnt(0)

.LBB0_86:
	s_andn2_b64 vcc, exec, s[0:1]
	s_cbranch_vccnz .LBB0_88
	s_load_dwordx2 s[4:5], s[92:93], 0xe8
	s_add_i32 s0, s16, 0x1400
	s_and_b32 s1, s0, 0x1ffc0
	s_and_b32 s0, s14, 0x3e0
	s_lshl_b32 s6, s0, 2
	s_waitcnt lgkmcnt(0)
	s_add_u32 s4, s4, s6
	v_or_b32_e32 v2, s1, v1
	s_addc_u32 s5, s5, 0
	v_mov_b32_e32 v23, v3
	v_lshl_add_u64 v[24:25], s[4:5], 0, v[22:23]
	v_lshlrev_b32_e32 v2, 12, v2
	v_lshl_add_u64 v[24:25], v[24:25], 0, v[2:3]
	v_add_co_u32_e32 v26, vcc, s20, v24
	s_lshl_b32 s12, s1, 1
	s_nop 0
	v_addc_co_u32_e32 v27, vcc, 0, v25, vcc
	v_add_co_u32_e32 v28, vcc, s21, v24
	s_nop 1
	v_addc_co_u32_e32 v29, vcc, 0, v25, vcc
	v_add_co_u32_e32 v74, vcc, s22, v24
	s_nop 1
	v_addc_co_u32_e32 v75, vcc, 0, v25, vcc
	v_add_co_u32_e32 v76, vcc, s23, v24
	s_nop 1
	v_addc_co_u32_e32 v77, vcc, 0, v25, vcc
	v_add_co_u32_e32 v78, vcc, s30, v24
	s_nop 1
	v_addc_co_u32_e32 v79, vcc, 0, v25, vcc
	v_add_co_u32_e32 v80, vcc, s31, v24
	s_nop 1
	v_addc_co_u32_e32 v81, vcc, 0, v25, vcc
	v_add_co_u32_e32 v82, vcc, s33, v24
	s_nop 1
	v_addc_co_u32_e32 v83, vcc, 0, v25, vcc
	global_load_dword v2, v[24:25], off
	global_load_dword v23, v[26:27], off
	global_load_dword v86, v[28:29], off
	global_load_dword v87, v[74:75], off
	global_load_dword v88, v[76:77], off
	global_load_dword v89, v[78:79], off
	global_load_dword v90, v[80:81], off
	global_load_dword v91, v[82:83], off
	v_add_co_u32_e32 v26, vcc, s34, v24
	s_nop 1
	v_addc_co_u32_e32 v27, vcc, 0, v25, vcc
	v_add_co_u32_e32 v28, vcc, s35, v24
	s_nop 1
	v_addc_co_u32_e32 v29, vcc, 0, v25, vcc
	v_add_co_u32_e32 v74, vcc, s36, v24
	s_nop 1
	v_addc_co_u32_e32 v75, vcc, 0, v25, vcc
	v_add_co_u32_e32 v76, vcc, s37, v24
	s_nop 1
	v_addc_co_u32_e32 v77, vcc, 0, v25, vcc
	v_add_co_u32_e32 v78, vcc, s38, v24
	s_nop 1
	v_addc_co_u32_e32 v79, vcc, 0, v25, vcc
	v_add_co_u32_e32 v80, vcc, s39, v24
	s_nop 1
	v_addc_co_u32_e32 v81, vcc, 0, v25, vcc
	v_add_co_u32_e32 v82, vcc, s40, v24
	s_nop 1
	v_addc_co_u32_e32 v83, vcc, 0, v25, vcc
	v_add_co_u32_e32 v84, vcc, s41, v24
	s_nop 1
	v_addc_co_u32_e32 v85, vcc, 0, v25, vcc
	global_load_dword v92, v[26:27], off
	global_load_dword v93, v[28:29], off
	global_load_dword v94, v[74:75], off
	global_load_dword v95, v[76:77], off
	global_load_dword v96, v[78:79], off
	global_load_dword v97, v[80:81], off
	global_load_dword v98, v[82:83], off
	global_load_dword v99, v[84:85], off
	v_add_co_u32_e32 v26, vcc, s42, v24
	s_nop 1
	v_addc_co_u32_e32 v27, vcc, 0, v25, vcc
	v_add_co_u32_e32 v28, vcc, s43, v24
	s_nop 1
	v_addc_co_u32_e32 v29, vcc, 0, v25, vcc
	v_add_co_u32_e32 v74, vcc, s44, v24
	s_nop 1
	v_addc_co_u32_e32 v75, vcc, 0, v25, vcc
	v_add_co_u32_e32 v76, vcc, s45, v24
	s_nop 1
	v_addc_co_u32_e32 v77, vcc, 0, v25, vcc
	v_add_co_u32_e32 v78, vcc, s46, v24
	s_nop 1
	v_addc_co_u32_e32 v79, vcc, 0, v25, vcc
	v_add_co_u32_e32 v80, vcc, s47, v24
	s_nop 1
	v_addc_co_u32_e32 v81, vcc, 0, v25, vcc
	v_add_co_u32_e32 v82, vcc, s48, v24
	s_nop 1
	v_addc_co_u32_e32 v83, vcc, 0, v25, vcc
	v_add_co_u32_e32 v84, vcc, s49, v24
	s_nop 1
	v_addc_co_u32_e32 v85, vcc, 0, v25, vcc
	global_load_dword v100, v[26:27], off
	global_load_dword v101, v[28:29], off
	global_load_dword v102, v[74:75], off
	global_load_dword v103, v[76:77], off
	global_load_dword v104, v[78:79], off
	global_load_dword v105, v[80:81], off
	global_load_dword v106, v[82:83], off
	s_nop 0
	global_load_dword v84, v[84:85], off
	v_add_co_u32_e32 v26, vcc, s50, v24
	s_nop 1
	v_addc_co_u32_e32 v27, vcc, 0, v25, vcc
	v_add_co_u32_e32 v28, vcc, s51, v24
	s_nop 1
	v_addc_co_u32_e32 v29, vcc, 0, v25, vcc
	v_add_co_u32_e32 v74, vcc, s52, v24
	s_nop 1
	v_addc_co_u32_e32 v75, vcc, 0, v25, vcc
	v_add_co_u32_e32 v76, vcc, s53, v24
	s_nop 1
	v_addc_co_u32_e32 v77, vcc, 0, v25, vcc
	v_add_co_u32_e32 v78, vcc, s54, v24
	s_nop 1
	v_addc_co_u32_e32 v79, vcc, 0, v25, vcc
	v_add_co_u32_e32 v80, vcc, s55, v24
	s_nop 1
	v_addc_co_u32_e32 v81, vcc, 0, v25, vcc
	v_add_co_u32_e32 v82, vcc, s56, v24
	s_nop 1
	v_addc_co_u32_e32 v83, vcc, 0, v25, vcc
	v_add_co_u32_e32 v24, vcc, s57, v24
	s_nop 1
	v_addc_co_u32_e32 v25, vcc, 0, v25, vcc
	global_load_dword v26, v[26:27], off
	s_nop 0
	global_load_dword v27, v[28:29], off
	s_nop 0
	global_load_dword v28, v[74:75], off
	global_load_dword v29, v[76:77], off
	s_nop 0
	global_load_dword v74, v[78:79], off
	global_load_dword v75, v[80:81], off
	global_load_dword v76, v[82:83], off
	s_nop 0
	global_load_dword v24, v[24:25], off
	s_waitcnt vmcnt(30)
	ds_write2_b32 v30, v2, v23 offset1:66
	s_waitcnt vmcnt(28)
	ds_write2_b32 v30, v86, v87 offset0:132 offset1:198
	s_waitcnt vmcnt(26)
	ds_write2_b32 v36, v88, v89 offset0:8 offset1:74
	s_waitcnt vmcnt(24)
	ds_write2_b32 v36, v90, v91 offset0:140 offset1:206
	s_waitcnt vmcnt(22)
	ds_write2_b32 v37, v92, v93 offset0:16 offset1:82
	s_waitcnt vmcnt(20)
	ds_write2_b32 v37, v94, v95 offset0:148 offset1:214
	s_waitcnt vmcnt(18)
	ds_write2_b32 v38, v96, v97 offset0:24 offset1:90
	s_waitcnt vmcnt(16)
	ds_write2_b32 v38, v98, v99 offset0:156 offset1:222
	s_waitcnt vmcnt(14)
	ds_write2_b32 v39, v100, v101 offset0:32 offset1:98
	s_waitcnt vmcnt(12)
	ds_write2_b32 v39, v102, v103 offset0:164 offset1:230
	s_waitcnt vmcnt(10)
	ds_write2_b32 v40, v104, v105 offset0:40 offset1:106
	s_waitcnt vmcnt(8)
	ds_write2_b32 v40, v106, v84 offset0:172 offset1:238
	s_waitcnt vmcnt(6)
	ds_write2_b32 v41, v26, v27 offset0:48 offset1:114
	s_waitcnt vmcnt(4)
	ds_write2_b32 v41, v28, v29 offset0:180 offset1:246
	s_waitcnt vmcnt(2)
	ds_write2_b32 v42, v74, v75 offset0:56 offset1:122
	s_waitcnt vmcnt(0)
	ds_write2_b32 v42, v76, v24 offset0:188 offset1:254
	s_waitcnt lgkmcnt(0)
	ds_read2_b32 v[28:29], v32 offset1:8
	ds_read2_b32 v[76:77], v32 offset0:33 offset1:41
	ds_read2_b32 v[78:79], v32 offset0:66 offset1:74
	ds_read2_b32 v[80:81], v32 offset0:99 offset1:107
	ds_read2_b32 v[82:83], v32 offset0:132 offset1:140
	s_waitcnt lgkmcnt(4)
	v_bfe_u32 v2, v28, 16, 1
	v_add3_u32 v2, v28, v2, s58
	s_waitcnt lgkmcnt(3)
	v_bfe_u32 v23, v76, 16, 1
	v_lshrrev_b32_e32 v2, 16, v2
	v_add3_u32 v23, v76, v23, s58
	ds_read2_b32 v[84:85], v32 offset0:165 offset1:173
	v_and_or_b32 v24, v23, s59, v2
	s_waitcnt lgkmcnt(3)
	v_bfe_u32 v2, v78, 16, 1
	v_add3_u32 v2, v78, v2, s58
	s_waitcnt lgkmcnt(2)
	v_bfe_u32 v23, v80, 16, 1
	ds_read2_b32 v[86:87], v32 offset0:198 offset1:206
	v_lshrrev_b32_e32 v2, 16, v2
	v_add3_u32 v23, v80, v23, s58
	ds_read2_b32 v[88:89], v32 offset0:231 offset1:239
	v_and_or_b32 v25, v23, s59, v2
	s_waitcnt lgkmcnt(3)
	v_bfe_u32 v2, v82, 16, 1
	v_add3_u32 v2, v82, v2, s58
	s_waitcnt lgkmcnt(2)
	v_bfe_u32 v23, v84, 16, 1
	v_lshrrev_b32_e32 v2, 16, v2
	v_add3_u32 v23, v84, v23, s58
	v_and_or_b32 v26, v23, s59, v2
	s_waitcnt lgkmcnt(1)
	v_bfe_u32 v2, v86, 16, 1
	v_add3_u32 v2, v86, v2, s58
	s_waitcnt lgkmcnt(0)
	v_bfe_u32 v23, v88, 16, 1
	v_lshrrev_b32_e32 v2, 16, v2
	v_add3_u32 v23, v88, v23, s58
	v_and_or_b32 v27, v23, s59, v2
	v_or_b32_e32 v2, s0, v31
	v_lshl_add_u64 v[74:75], v[8:9], 0, s[12:13]
	v_lshlrev_b32_e32 v2, 11, v2
	v_lshl_add_u64 v[90:91], v[74:75], 0, v[2:3]
	v_bfe_u32 v2, v29, 16, 1
	v_add3_u32 v2, v29, v2, s58
	v_bfe_u32 v23, v77, 16, 1
	v_lshrrev_b32_e32 v2, 16, v2
	v_add3_u32 v23, v77, v23, s58
	global_store_dwordx4 v[90:91], v[24:27], off sc1
	ds_read2_b32 v[28:29], v32 offset0:16 offset1:24
	s_nop 0
	v_and_or_b32 v24, v23, s59, v2
	v_bfe_u32 v2, v79, 16, 1
	v_add3_u32 v2, v79, v2, s58
	v_bfe_u32 v23, v81, 16, 1
	v_lshrrev_b32_e32 v2, 16, v2
	v_add3_u32 v23, v81, v23, s58
	v_and_or_b32 v25, v23, s59, v2
	v_bfe_u32 v2, v83, 16, 1
	v_add3_u32 v2, v83, v2, s58
	v_bfe_u32 v23, v85, 16, 1
	v_lshrrev_b32_e32 v2, 16, v2
	v_add3_u32 v23, v85, v23, s58
	v_and_or_b32 v26, v23, s59, v2
	v_bfe_u32 v2, v87, 16, 1
	v_add3_u32 v2, v87, v2, s58
	v_bfe_u32 v23, v89, 16, 1
	v_lshrrev_b32_e32 v2, 16, v2
	v_add3_u32 v23, v89, v23, s58
	v_and_or_b32 v27, v23, s59, v2
	v_or_b32_e32 v2, s0, v33
	v_lshlrev_b32_e32 v2, 11, v2
	v_lshl_add_u64 v[76:77], v[74:75], 0, v[2:3]
	global_store_dwordx4 v[76:77], v[24:27], off sc1
	ds_read2_b32 v[76:77], v32 offset0:49 offset1:57
	ds_read2_b32 v[78:79], v32 offset0:82 offset1:90
	ds_read2_b32 v[80:81], v32 offset0:115 offset1:123
	s_waitcnt lgkmcnt(3)
	v_bfe_u32 v2, v28, 16, 1
	v_add3_u32 v2, v28, v2, s58
	s_waitcnt lgkmcnt(2)
	v_bfe_u32 v23, v76, 16, 1
	ds_read2_b32 v[82:83], v32 offset0:148 offset1:156
	v_lshrrev_b32_e32 v2, 16, v2
	v_add3_u32 v23, v76, v23, s58
	ds_read2_b32 v[84:85], v32 offset0:181 offset1:189
	v_and_or_b32 v24, v23, s59, v2
	s_waitcnt lgkmcnt(3)
	v_bfe_u32 v2, v78, 16, 1
	v_add3_u32 v2, v78, v2, s58
	s_waitcnt lgkmcnt(2)
	v_bfe_u32 v23, v80, 16, 1
	ds_read2_b32 v[86:87], v32 offset0:214 offset1:222
	v_lshrrev_b32_e32 v2, 16, v2
	v_add3_u32 v23, v80, v23, s58
	ds_read2_b32 v[88:89], v32 offset0:247 offset1:255
	v_and_or_b32 v25, v23, s59, v2
	s_waitcnt lgkmcnt(3)
	v_bfe_u32 v2, v82, 16, 1
	v_add3_u32 v2, v82, v2, s58
	s_waitcnt lgkmcnt(2)
	v_bfe_u32 v23, v84, 16, 1
	v_lshrrev_b32_e32 v2, 16, v2
	v_add3_u32 v23, v84, v23, s58
	v_and_or_b32 v26, v23, s59, v2
	s_waitcnt lgkmcnt(1)
	v_bfe_u32 v2, v86, 16, 1
	v_add3_u32 v2, v86, v2, s58
	s_waitcnt lgkmcnt(0)
	v_bfe_u32 v23, v88, 16, 1
	v_lshrrev_b32_e32 v2, 16, v2
	v_add3_u32 v23, v88, v23, s58
	v_and_or_b32 v27, v23, s59, v2
	v_or_b32_e32 v2, s0, v34
	v_lshlrev_b32_e32 v2, 11, v2
	v_lshl_add_u64 v[90:91], v[74:75], 0, v[2:3]
	v_bfe_u32 v2, v29, 16, 1
	v_add3_u32 v2, v29, v2, s58
	v_bfe_u32 v23, v77, 16, 1
	v_lshrrev_b32_e32 v2, 16, v2
	v_add3_u32 v23, v77, v23, s58
	global_store_dwordx4 v[90:91], v[24:27], off sc1
	s_nop 1
	v_and_or_b32 v24, v23, s59, v2
	v_bfe_u32 v2, v79, 16, 1
	v_add3_u32 v2, v79, v2, s58
	v_bfe_u32 v23, v81, 16, 1
	v_lshrrev_b32_e32 v2, 16, v2
	v_add3_u32 v23, v81, v23, s58
	v_and_or_b32 v25, v23, s59, v2
	v_bfe_u32 v2, v83, 16, 1
	v_add3_u32 v2, v83, v2, s58
	v_bfe_u32 v23, v85, 16, 1
	v_lshrrev_b32_e32 v2, 16, v2
	v_add3_u32 v23, v85, v23, s58
	v_and_or_b32 v26, v23, s59, v2
	v_bfe_u32 v2, v87, 16, 1
	v_add3_u32 v2, v87, v2, s58
	v_bfe_u32 v23, v89, 16, 1
	v_lshrrev_b32_e32 v2, 16, v2
	v_add3_u32 v23, v89, v23, s58
	v_and_or_b32 v27, v23, s59, v2
	v_or_b32_e32 v2, s0, v35
	v_lshlrev_b32_e32 v2, 11, v2
	v_lshl_add_u64 v[28:29], v[74:75], 0, v[2:3]
	global_store_dwordx4 v[28:29], v[24:27], off sc1
	s_waitcnt lgkmcnt(0)

.LBB0_89:
	s_andn2_b64 vcc, exec, s[0:1]
	s_cbranch_vccnz .LBB0_91
	s_load_dwordx2 s[4:5], s[92:93], 0xd8
	s_and_b32 s0, s14, 0xe0
	s_and_b32 s1, s18, 0x7c0
	s_lshl_b32 s6, s0, 2
	v_or_b32_e32 v2, s1, v1
	s_waitcnt lgkmcnt(0)
	s_add_u32 s4, s4, s6
	s_addc_u32 s5, s5, 0
	v_mov_b32_e32 v23, v3
	v_lshl_add_u64 v[24:25], s[4:5], 0, v[22:23]
	v_lshlrev_b32_e32 v2, 10, v2
	v_lshl_add_u64 v[24:25], v[24:25], 0, v[2:3]
	v_add_co_u32_e32 v26, vcc, s60, v24
	s_lshl_b32 s12, s1, 1
	s_nop 0
	v_addc_co_u32_e32 v27, vcc, 0, v25, vcc
	v_add_co_u32_e32 v28, vcc, s20, v24
	s_nop 1
	v_addc_co_u32_e32 v29, vcc, 0, v25, vcc
	v_add_co_u32_e32 v74, vcc, s61, v24
	s_nop 1
	v_addc_co_u32_e32 v75, vcc, 0, v25, vcc
	v_add_co_u32_e32 v76, vcc, s21, v24
	s_nop 1
	v_addc_co_u32_e32 v77, vcc, 0, v25, vcc
	global_load_dword v2, v[28:29], off offset:-4096
	global_load_dword v23, v[28:29], off
	global_load_dword v88, v[28:29], off offset:2048
	global_load_dword v89, v[76:77], off offset:-4096
	global_load_dword v90, v[76:77], off
	v_add_co_u32_e32 v28, vcc, s62, v24
	s_nop 1
	v_addc_co_u32_e32 v29, vcc, 0, v25, vcc
	v_add_co_u32_e32 v78, vcc, s22, v24
	s_nop 1
	v_addc_co_u32_e32 v79, vcc, 0, v25, vcc
	v_add_co_u32_e32 v80, vcc, s63, v24
	s_nop 1
	v_addc_co_u32_e32 v81, vcc, 0, v25, vcc
	v_add_co_u32_e32 v82, vcc, s23, v24
	s_nop 1
	v_addc_co_u32_e32 v83, vcc, 0, v25, vcc
	v_add_co_u32_e32 v84, vcc, s64, v24
	s_nop 1
	v_addc_co_u32_e32 v85, vcc, 0, v25, vcc
	v_add_co_u32_e32 v86, vcc, s30, v24
	s_nop 1
	v_addc_co_u32_e32 v87, vcc, 0, v25, vcc
	global_load_dword v91, v[76:77], off offset:2048
	global_load_dword v92, v[78:79], off offset:-4096
	global_load_dword v93, v[78:79], off
	global_load_dword v94, v[78:79], off offset:2048
	global_load_dword v95, v[82:83], off offset:-4096
	global_load_dword v96, v[82:83], off
	s_nop 0
	global_load_dword v82, v[82:83], off offset:2048
	s_nop 0
	global_load_dword v83, v[86:87], off offset:-4096
	v_add_co_u32_e32 v76, vcc, s65, v24
	s_nop 1
	v_addc_co_u32_e32 v77, vcc, 0, v25, vcc
	v_add_co_u32_e32 v78, vcc, s31, v24
	global_load_dword v97, v[24:25], off
	global_load_dword v98, v[24:25], off offset:2048
	global_load_dword v99, v[26:27], off offset:2048
	s_nop 0
	global_load_dword v74, v[74:75], off offset:2048
	s_nop 0
	global_load_dword v75, v[28:29], off offset:2048
	s_nop 0
	global_load_dword v80, v[80:81], off offset:2048
	s_nop 0
	global_load_dword v81, v[84:85], off offset:2048
	s_nop 0
	global_load_dword v76, v[76:77], off offset:2048
	v_addc_co_u32_e32 v79, vcc, 0, v25, vcc
	v_add_co_u32_e32 v26, vcc, s66, v24
	s_nop 1
	v_addc_co_u32_e32 v27, vcc, 0, v25, vcc
	v_add_co_u32_e32 v28, vcc, s33, v24
	s_nop 1
	v_addc_co_u32_e32 v29, vcc, 0, v25, vcc
	v_add_co_u32_e32 v24, vcc, s67, v24
	global_load_dword v77, v[86:87], off
	global_load_dword v84, v[86:87], off offset:2048
	global_load_dword v85, v[78:79], off offset:-4096
	s_nop 0
	global_load_dword v86, v[78:79], off
	s_nop 0
	global_load_dword v78, v[78:79], off offset:2048
	s_nop 0
	global_load_dword v79, v[28:29], off offset:-4096
	global_load_dword v87, v[28:29], off
	s_nop 0
	global_load_dword v28, v[28:29], off offset:2048
	v_addc_co_u32_e32 v25, vcc, 0, v25, vcc
	global_load_dword v26, v[26:27], off offset:2048
	s_nop 0
	global_load_dword v27, v[24:25], off
	s_nop 0
	global_load_dword v24, v[24:25], off offset:2048
	s_waitcnt vmcnt(17)
	ds_write2_b32 v30, v97, v98 offset1:66
	s_waitcnt vmcnt(16)
	ds_write2_b32 v30, v2, v99 offset0:132 offset1:198
	ds_write2_b32 v36, v23, v88 offset0:8 offset1:74
	s_waitcnt vmcnt(15)
	ds_write2_b32 v36, v89, v74 offset0:140 offset1:206
	ds_write2_b32 v37, v90, v91 offset0:16 offset1:82
	s_waitcnt vmcnt(14)
	ds_write2_b32 v37, v92, v75 offset0:148 offset1:214
	ds_write2_b32 v38, v93, v94 offset0:24 offset1:90
	s_waitcnt vmcnt(13)
	ds_write2_b32 v38, v95, v80 offset0:156 offset1:222
	ds_write2_b32 v39, v96, v82 offset0:32 offset1:98
	s_waitcnt vmcnt(12)
	ds_write2_b32 v39, v83, v81 offset0:164 offset1:230
	s_waitcnt vmcnt(9)
	ds_write2_b32 v40, v77, v84 offset0:40 offset1:106
	s_waitcnt vmcnt(8)
	ds_write2_b32 v40, v85, v76 offset0:172 offset1:238
	s_waitcnt vmcnt(6)
	ds_write2_b32 v41, v86, v78 offset0:48 offset1:114
	s_waitcnt vmcnt(2)
	ds_write2_b32 v41, v79, v26 offset0:180 offset1:246
	ds_write2_b32 v42, v87, v28 offset0:56 offset1:122
	s_waitcnt vmcnt(0)
	ds_write2_b32 v42, v27, v24 offset0:188 offset1:254
	s_waitcnt lgkmcnt(0)
	ds_read2_b32 v[28:29], v32 offset1:8
	ds_read2_b32 v[76:77], v32 offset0:33 offset1:41
	ds_read2_b32 v[78:79], v32 offset0:66 offset1:74
	ds_read2_b32 v[80:81], v32 offset0:99 offset1:107
	ds_read2_b32 v[82:83], v32 offset0:132 offset1:140
	s_waitcnt lgkmcnt(4)
	v_bfe_u32 v2, v28, 16, 1
	v_add3_u32 v2, v28, v2, s58
	s_waitcnt lgkmcnt(3)
	v_bfe_u32 v23, v76, 16, 1
	v_lshrrev_b32_e32 v2, 16, v2
	v_add3_u32 v23, v76, v23, s58
	ds_read2_b32 v[84:85], v32 offset0:165 offset1:173
	v_and_or_b32 v24, v23, s59, v2
	s_waitcnt lgkmcnt(3)
	v_bfe_u32 v2, v78, 16, 1
	v_add3_u32 v2, v78, v2, s58
	s_waitcnt lgkmcnt(2)
	v_bfe_u32 v23, v80, 16, 1
	ds_read2_b32 v[86:87], v32 offset0:198 offset1:206
	v_lshrrev_b32_e32 v2, 16, v2
	v_add3_u32 v23, v80, v23, s58
	ds_read2_b32 v[88:89], v32 offset0:231 offset1:239
	v_and_or_b32 v25, v23, s59, v2
	s_waitcnt lgkmcnt(3)
	v_bfe_u32 v2, v82, 16, 1
	v_add3_u32 v2, v82, v2, s58
	s_waitcnt lgkmcnt(2)
	v_bfe_u32 v23, v84, 16, 1
	v_lshrrev_b32_e32 v2, 16, v2
	v_add3_u32 v23, v84, v23, s58
	v_and_or_b32 v26, v23, s59, v2
	s_waitcnt lgkmcnt(1)
	v_bfe_u32 v2, v86, 16, 1
	v_add3_u32 v2, v86, v2, s58
	s_waitcnt lgkmcnt(0)
	v_bfe_u32 v23, v88, 16, 1
	v_lshrrev_b32_e32 v2, 16, v2
	v_add3_u32 v23, v88, v23, s58
	v_and_or_b32 v27, v23, s59, v2
	v_or_b32_e32 v2, s0, v31
	v_lshl_add_u64 v[74:75], v[10:11], 0, s[12:13]
	v_lshlrev_b32_e32 v2, 9, v2
	v_lshl_add_u64 v[90:91], v[74:75], 0, v[2:3]
	v_bfe_u32 v2, v29, 16, 1
	v_add3_u32 v2, v29, v2, s58
	v_bfe_u32 v23, v77, 16, 1
	v_lshrrev_b32_e32 v2, 16, v2
	v_add3_u32 v23, v77, v23, s58
	global_store_dwordx4 v[90:91], v[24:27], off sc1
	ds_read2_b32 v[28:29], v32 offset0:16 offset1:24
	s_nop 0
	v_and_or_b32 v24, v23, s59, v2
	v_bfe_u32 v2, v79, 16, 1
	v_add3_u32 v2, v79, v2, s58
	v_bfe_u32 v23, v81, 16, 1
	v_lshrrev_b32_e32 v2, 16, v2
	v_add3_u32 v23, v81, v23, s58
	v_and_or_b32 v25, v23, s59, v2
	v_bfe_u32 v2, v83, 16, 1
	v_add3_u32 v2, v83, v2, s58
	v_bfe_u32 v23, v85, 16, 1
	v_lshrrev_b32_e32 v2, 16, v2
	v_add3_u32 v23, v85, v23, s58
	v_and_or_b32 v26, v23, s59, v2
	v_bfe_u32 v2, v87, 16, 1
	v_add3_u32 v2, v87, v2, s58
	v_bfe_u32 v23, v89, 16, 1
	v_lshrrev_b32_e32 v2, 16, v2
	v_add3_u32 v23, v89, v23, s58
	v_and_or_b32 v27, v23, s59, v2
	v_or_b32_e32 v2, s0, v33
	v_lshlrev_b32_e32 v2, 9, v2
	v_lshl_add_u64 v[76:77], v[74:75], 0, v[2:3]
	global_store_dwordx4 v[76:77], v[24:27], off sc1
	ds_read2_b32 v[76:77], v32 offset0:49 offset1:57
	ds_read2_b32 v[78:79], v32 offset0:82 offset1:90
	ds_read2_b32 v[80:81], v32 offset0:115 offset1:123
	s_waitcnt lgkmcnt(3)
	v_bfe_u32 v2, v28, 16, 1
	v_add3_u32 v2, v28, v2, s58
	s_waitcnt lgkmcnt(2)
	v_bfe_u32 v23, v76, 16, 1
	ds_read2_b32 v[82:83], v32 offset0:148 offset1:156
	v_lshrrev_b32_e32 v2, 16, v2
	v_add3_u32 v23, v76, v23, s58
	ds_read2_b32 v[84:85], v32 offset0:181 offset1:189
	v_and_or_b32 v24, v23, s59, v2
	s_waitcnt lgkmcnt(3)
	v_bfe_u32 v2, v78, 16, 1
	v_add3_u32 v2, v78, v2, s58
	s_waitcnt lgkmcnt(2)
	v_bfe_u32 v23, v80, 16, 1
	ds_read2_b32 v[86:87], v32 offset0:214 offset1:222
	v_lshrrev_b32_e32 v2, 16, v2
	v_add3_u32 v23, v80, v23, s58
	ds_read2_b32 v[88:89], v32 offset0:247 offset1:255
	v_and_or_b32 v25, v23, s59, v2
	s_waitcnt lgkmcnt(3)
	v_bfe_u32 v2, v82, 16, 1
	v_add3_u32 v2, v82, v2, s58
	s_waitcnt lgkmcnt(2)
	v_bfe_u32 v23, v84, 16, 1
	v_lshrrev_b32_e32 v2, 16, v2
	v_add3_u32 v23, v84, v23, s58
	v_and_or_b32 v26, v23, s59, v2
	s_waitcnt lgkmcnt(1)
	v_bfe_u32 v2, v86, 16, 1
	v_add3_u32 v2, v86, v2, s58
	s_waitcnt lgkmcnt(0)
	v_bfe_u32 v23, v88, 16, 1
	v_lshrrev_b32_e32 v2, 16, v2
	v_add3_u32 v23, v88, v23, s58
	v_and_or_b32 v27, v23, s59, v2
	v_or_b32_e32 v2, s0, v34
	v_lshlrev_b32_e32 v2, 9, v2
	v_lshl_add_u64 v[90:91], v[74:75], 0, v[2:3]
	v_bfe_u32 v2, v29, 16, 1
	v_add3_u32 v2, v29, v2, s58
	v_bfe_u32 v23, v77, 16, 1
	v_lshrrev_b32_e32 v2, 16, v2
	v_add3_u32 v23, v77, v23, s58
	global_store_dwordx4 v[90:91], v[24:27], off sc1
	s_nop 1
	v_and_or_b32 v24, v23, s59, v2
	v_bfe_u32 v2, v79, 16, 1
	v_add3_u32 v2, v79, v2, s58
	v_bfe_u32 v23, v81, 16, 1
	v_lshrrev_b32_e32 v2, 16, v2
	v_add3_u32 v23, v81, v23, s58
	v_and_or_b32 v25, v23, s59, v2
	v_bfe_u32 v2, v83, 16, 1
	v_add3_u32 v2, v83, v2, s58
	v_bfe_u32 v23, v85, 16, 1
	v_lshrrev_b32_e32 v2, 16, v2
	v_add3_u32 v23, v85, v23, s58
	v_and_or_b32 v26, v23, s59, v2
	v_bfe_u32 v2, v87, 16, 1
	v_add3_u32 v2, v87, v2, s58
	v_bfe_u32 v23, v89, 16, 1
	v_lshrrev_b32_e32 v2, 16, v2
	v_add3_u32 v23, v89, v23, s58
	v_and_or_b32 v27, v23, s59, v2
	v_or_b32_e32 v2, s0, v35
	v_lshlrev_b32_e32 v2, 9, v2
	v_lshl_add_u64 v[28:29], v[74:75], 0, v[2:3]
	global_store_dwordx4 v[28:29], v[24:27], off sc1
	s_waitcnt lgkmcnt(0)

.LBB0_157:
	s_waitcnt vmcnt(30)
	v_mul_f32_e32 v23, v27, v23
	v_mul_f32_e32 v2, v2, v26
	s_waitcnt vmcnt(1)
	v_mul_f32_e32 v25, v131, v132
	v_mul_f32_e32 v28, v130, v128
	v_mul_f32_e32 v76, v127, v129
	v_mul_f32_e32 v123, v125, v123
	v_mul_f32_e32 v122, v122, v124
	v_mul_f32_e32 v119, v121, v119
	v_mul_f32_e32 v118, v118, v120
	v_mul_f32_e32 v115, v117, v115
	v_mul_f32_e32 v114, v114, v116
	v_mul_f32_e32 v111, v113, v111
	v_mul_f32_e32 v110, v110, v112
	v_mul_f32_e32 v107, v109, v107
	v_mul_f32_e32 v106, v106, v108
	v_mul_f32_e32 v103, v105, v103
	v_mul_f32_e32 v102, v102, v104
	v_mul_f32_e32 v99, v101, v99
	v_mul_f32_e32 v98, v98, v100
	v_mul_f32_e32 v95, v97, v95
	v_mul_f32_e32 v94, v94, v96
	v_mul_f32_e32 v91, v93, v91
	v_mul_f32_e32 v90, v90, v92
	v_mul_f32_e32 v87, v89, v87
	v_mul_f32_e32 v86, v86, v88
	v_mul_f32_e32 v83, v85, v83
	v_mul_f32_e32 v82, v82, v84
	v_mul_f32_e32 v79, v81, v79
	v_mul_f32_e32 v78, v78, v80
	v_mul_f32_e32 v74, v77, v74
	v_mul_f32_e32 v29, v29, v75
	s_waitcnt vmcnt(0)
	v_mul_f32_e32 v24, v24, v126
	ds_write2_b32 v30, v2, v23 offset1:66
	ds_write2_b32 v30, v29, v74 offset0:132 offset1:198
	ds_write2_b32 v36, v78, v79 offset0:8 offset1:74
	ds_write2_b32 v36, v82, v83 offset0:140 offset1:206
	ds_write2_b32 v37, v86, v87 offset0:16 offset1:82
	ds_write2_b32 v37, v90, v91 offset0:148 offset1:214
	ds_write2_b32 v38, v94, v95 offset0:24 offset1:90
	ds_write2_b32 v38, v98, v99 offset0:156 offset1:222
	ds_write2_b32 v39, v102, v103 offset0:32 offset1:98
	ds_write2_b32 v39, v106, v107 offset0:164 offset1:230
	ds_write2_b32 v40, v110, v111 offset0:40 offset1:106
	ds_write2_b32 v40, v114, v115 offset0:172 offset1:238
	ds_write2_b32 v41, v118, v119 offset0:48 offset1:114
	ds_write2_b32 v41, v122, v123 offset0:180 offset1:246
	ds_write2_b32 v42, v76, v28 offset0:56 offset1:122
	ds_write2_b32 v42, v25, v24 offset0:188 offset1:254
	s_waitcnt lgkmcnt(0)
	ds_read2_b32 v[28:29], v32 offset1:8
	ds_read2_b32 v[76:77], v32 offset0:33 offset1:41
	ds_read2_b32 v[78:79], v32 offset0:66 offset1:74
	ds_read2_b32 v[80:81], v32 offset0:99 offset1:107
	ds_read2_b32 v[82:83], v32 offset0:132 offset1:140
	s_waitcnt lgkmcnt(4)
	v_bfe_u32 v2, v28, 16, 1
	v_add3_u32 v2, v28, v2, s58
	s_waitcnt lgkmcnt(3)
	v_bfe_u32 v23, v76, 16, 1
	v_lshrrev_b32_e32 v2, 16, v2
	v_add3_u32 v23, v76, v23, s58
	ds_read2_b32 v[84:85], v32 offset0:165 offset1:173
	v_and_or_b32 v24, v23, s59, v2
	s_waitcnt lgkmcnt(3)
	v_bfe_u32 v2, v78, 16, 1
	v_add3_u32 v2, v78, v2, s58
	s_waitcnt lgkmcnt(2)
	v_bfe_u32 v23, v80, 16, 1
	ds_read2_b32 v[86:87], v32 offset0:198 offset1:206
	v_lshrrev_b32_e32 v2, 16, v2
	v_add3_u32 v23, v80, v23, s58
	ds_read2_b32 v[88:89], v32 offset0:231 offset1:239
	v_and_or_b32 v25, v23, s59, v2
	s_waitcnt lgkmcnt(3)
	v_bfe_u32 v2, v82, 16, 1
	v_add3_u32 v2, v82, v2, s58
	s_waitcnt lgkmcnt(2)
	v_bfe_u32 v23, v84, 16, 1
	v_lshrrev_b32_e32 v2, 16, v2
	v_add3_u32 v23, v84, v23, s58
	v_and_or_b32 v26, v23, s59, v2
	s_waitcnt lgkmcnt(1)
	v_bfe_u32 v2, v86, 16, 1
	v_add3_u32 v2, v86, v2, s58
	s_waitcnt lgkmcnt(0)
	v_bfe_u32 v23, v88, 16, 1
	s_and_b32 s0, 0xffff, s5
	v_lshrrev_b32_e32 v2, 16, v2
	v_add3_u32 v23, v88, v23, s58
	s_lshl_b32 s12, s0, 1
	v_and_or_b32 v27, v23, s59, v2
	v_or_b32_e32 v2, s4, v31
	v_lshl_add_u64 v[74:75], v[12:13], 0, s[12:13]
	v_lshlrev_b32_e32 v2, 11, v2
	v_lshl_add_u64 v[90:91], v[74:75], 0, v[2:3]
	v_bfe_u32 v2, v29, 16, 1
	v_add3_u32 v2, v29, v2, s58
	v_bfe_u32 v23, v77, 16, 1
	v_lshrrev_b32_e32 v2, 16, v2
	v_add3_u32 v23, v77, v23, s58
	global_store_dwordx4 v[90:91], v[24:27], off sc1
	ds_read2_b32 v[28:29], v32 offset0:16 offset1:24
	s_nop 0
	v_and_or_b32 v24, v23, s59, v2
	v_bfe_u32 v2, v79, 16, 1
	v_add3_u32 v2, v79, v2, s58
	v_bfe_u32 v23, v81, 16, 1
	v_lshrrev_b32_e32 v2, 16, v2
	v_add3_u32 v23, v81, v23, s58
	v_and_or_b32 v25, v23, s59, v2
	v_bfe_u32 v2, v83, 16, 1
	v_add3_u32 v2, v83, v2, s58
	v_bfe_u32 v23, v85, 16, 1
	v_lshrrev_b32_e32 v2, 16, v2
	v_add3_u32 v23, v85, v23, s58
	v_and_or_b32 v26, v23, s59, v2
	v_bfe_u32 v2, v87, 16, 1
	v_add3_u32 v2, v87, v2, s58
	v_bfe_u32 v23, v89, 16, 1
	v_lshrrev_b32_e32 v2, 16, v2
	v_add3_u32 v23, v89, v23, s58
	v_and_or_b32 v27, v23, s59, v2
	v_or_b32_e32 v2, s4, v33
	v_lshlrev_b32_e32 v2, 11, v2
	v_lshl_add_u64 v[76:77], v[74:75], 0, v[2:3]
	global_store_dwordx4 v[76:77], v[24:27], off sc1
	ds_read2_b32 v[76:77], v32 offset0:49 offset1:57
	ds_read2_b32 v[78:79], v32 offset0:82 offset1:90
	ds_read2_b32 v[80:81], v32 offset0:115 offset1:123
	s_waitcnt lgkmcnt(3)
	v_bfe_u32 v2, v28, 16, 1
	v_add3_u32 v2, v28, v2, s58
	s_waitcnt lgkmcnt(2)
	v_bfe_u32 v23, v76, 16, 1
	ds_read2_b32 v[82:83], v32 offset0:148 offset1:156
	v_lshrrev_b32_e32 v2, 16, v2
	v_add3_u32 v23, v76, v23, s58
	ds_read2_b32 v[84:85], v32 offset0:181 offset1:189
	v_and_or_b32 v24, v23, s59, v2
	s_waitcnt lgkmcnt(3)
	v_bfe_u32 v2, v78, 16, 1
	v_add3_u32 v2, v78, v2, s58
	s_waitcnt lgkmcnt(2)
	v_bfe_u32 v23, v80, 16, 1
	ds_read2_b32 v[86:87], v32 offset0:214 offset1:222
	v_lshrrev_b32_e32 v2, 16, v2
	v_add3_u32 v23, v80, v23, s58
	ds_read2_b32 v[88:89], v32 offset0:247 offset1:255
	v_and_or_b32 v25, v23, s59, v2
	s_waitcnt lgkmcnt(3)
	v_bfe_u32 v2, v82, 16, 1
	v_add3_u32 v2, v82, v2, s58
	s_waitcnt lgkmcnt(2)
	v_bfe_u32 v23, v84, 16, 1
	v_lshrrev_b32_e32 v2, 16, v2
	v_add3_u32 v23, v84, v23, s58
	v_and_or_b32 v26, v23, s59, v2
	s_waitcnt lgkmcnt(1)
	v_bfe_u32 v2, v86, 16, 1
	v_add3_u32 v2, v86, v2, s58
	s_waitcnt lgkmcnt(0)
	v_bfe_u32 v23, v88, 16, 1
	v_lshrrev_b32_e32 v2, 16, v2
	v_add3_u32 v23, v88, v23, s58
	v_and_or_b32 v27, v23, s59, v2
	v_or_b32_e32 v2, s4, v34
	v_lshlrev_b32_e32 v2, 11, v2
	v_lshl_add_u64 v[90:91], v[74:75], 0, v[2:3]
	v_bfe_u32 v2, v29, 16, 1
	v_add3_u32 v2, v29, v2, s58
	v_bfe_u32 v23, v77, 16, 1
	v_lshrrev_b32_e32 v2, 16, v2
	v_add3_u32 v23, v77, v23, s58
	global_store_dwordx4 v[90:91], v[24:27], off sc1
	s_nop 1
	v_and_or_b32 v24, v23, s59, v2
	v_bfe_u32 v2, v79, 16, 1
	v_add3_u32 v2, v79, v2, s58
	v_bfe_u32 v23, v81, 16, 1
	v_lshrrev_b32_e32 v2, 16, v2
	v_add3_u32 v23, v81, v23, s58
	v_and_or_b32 v25, v23, s59, v2
	v_bfe_u32 v2, v83, 16, 1
	v_add3_u32 v2, v83, v2, s58
	v_bfe_u32 v23, v85, 16, 1
	v_lshrrev_b32_e32 v2, 16, v2
	v_add3_u32 v23, v85, v23, s58
	v_and_or_b32 v26, v23, s59, v2
	v_bfe_u32 v2, v87, 16, 1
	v_add3_u32 v2, v87, v2, s58
	v_bfe_u32 v23, v89, 16, 1
	v_lshrrev_b32_e32 v2, 16, v2
	v_add3_u32 v23, v89, v23, s58
	v_and_or_b32 v27, v23, s59, v2
	v_or_b32_e32 v2, s4, v35
	v_lshlrev_b32_e32 v2, 11, v2
	v_lshl_add_u64 v[28:29], v[74:75], 0, v[2:3]
	global_store_dwordx4 v[28:29], v[24:27], off sc1
	s_waitcnt lgkmcnt(0)

.LBB0_159:
	s_andn2_b64 vcc, exec, s[0:1]
	s_cbranch_vccnz .LBB0_161
	s_load_dwordx2 s[4:5], s[92:93], 0x60
	s_add_i32 s0, s16, 0x3240
	s_and_b32 s1, s0, 0x1ffc0
	s_and_b32 s0, s14, 0x3e0
	s_lshl_b32 s6, s0, 2
	s_waitcnt lgkmcnt(0)
	s_add_u32 s4, s4, s6
	v_or_b32_e32 v2, s1, v1
	s_addc_u32 s5, s5, 0
	v_mov_b32_e32 v23, v3
	v_lshl_add_u64 v[24:25], s[4:5], 0, v[22:23]
	v_lshlrev_b32_e32 v2, 12, v2
	v_lshl_add_u64 v[24:25], v[24:25], 0, v[2:3]
	v_add_co_u32_e32 v26, vcc, s20, v24
	s_lshl_b32 s12, s1, 1
	s_nop 0
	v_addc_co_u32_e32 v27, vcc, 0, v25, vcc
	v_add_co_u32_e32 v28, vcc, s21, v24
	s_nop 1
	v_addc_co_u32_e32 v29, vcc, 0, v25, vcc
	v_add_co_u32_e32 v74, vcc, s22, v24
	s_nop 1
	v_addc_co_u32_e32 v75, vcc, 0, v25, vcc
	v_add_co_u32_e32 v76, vcc, s23, v24
	s_nop 1
	v_addc_co_u32_e32 v77, vcc, 0, v25, vcc
	v_add_co_u32_e32 v78, vcc, s30, v24
	s_nop 1
	v_addc_co_u32_e32 v79, vcc, 0, v25, vcc
	v_add_co_u32_e32 v80, vcc, s31, v24
	s_nop 1
	v_addc_co_u32_e32 v81, vcc, 0, v25, vcc
	v_add_co_u32_e32 v82, vcc, s33, v24
	s_nop 1
	v_addc_co_u32_e32 v83, vcc, 0, v25, vcc
	global_load_dword v2, v[24:25], off
	global_load_dword v23, v[26:27], off
	global_load_dword v86, v[28:29], off
	global_load_dword v87, v[74:75], off
	global_load_dword v88, v[76:77], off
	global_load_dword v89, v[78:79], off
	global_load_dword v90, v[80:81], off
	global_load_dword v91, v[82:83], off
	v_add_co_u32_e32 v26, vcc, s34, v24
	s_nop 1
	v_addc_co_u32_e32 v27, vcc, 0, v25, vcc
	v_add_co_u32_e32 v28, vcc, s35, v24
	s_nop 1
	v_addc_co_u32_e32 v29, vcc, 0, v25, vcc
	v_add_co_u32_e32 v74, vcc, s36, v24
	s_nop 1
	v_addc_co_u32_e32 v75, vcc, 0, v25, vcc
	v_add_co_u32_e32 v76, vcc, s37, v24
	s_nop 1
	v_addc_co_u32_e32 v77, vcc, 0, v25, vcc
	v_add_co_u32_e32 v78, vcc, s38, v24
	s_nop 1
	v_addc_co_u32_e32 v79, vcc, 0, v25, vcc
	v_add_co_u32_e32 v80, vcc, s39, v24
	s_nop 1
	v_addc_co_u32_e32 v81, vcc, 0, v25, vcc
	v_add_co_u32_e32 v82, vcc, s40, v24
	s_nop 1
	v_addc_co_u32_e32 v83, vcc, 0, v25, vcc
	v_add_co_u32_e32 v84, vcc, s41, v24
	s_nop 1
	v_addc_co_u32_e32 v85, vcc, 0, v25, vcc
	global_load_dword v92, v[26:27], off
	global_load_dword v93, v[28:29], off
	global_load_dword v94, v[74:75], off
	global_load_dword v95, v[76:77], off
	global_load_dword v96, v[78:79], off
	global_load_dword v97, v[80:81], off
	global_load_dword v98, v[82:83], off
	global_load_dword v99, v[84:85], off
	v_add_co_u32_e32 v26, vcc, s42, v24
	s_nop 1
	v_addc_co_u32_e32 v27, vcc, 0, v25, vcc
	v_add_co_u32_e32 v28, vcc, s43, v24
	s_nop 1
	v_addc_co_u32_e32 v29, vcc, 0, v25, vcc
	v_add_co_u32_e32 v74, vcc, s44, v24
	s_nop 1
	v_addc_co_u32_e32 v75, vcc, 0, v25, vcc
	v_add_co_u32_e32 v76, vcc, s45, v24
	s_nop 1
	v_addc_co_u32_e32 v77, vcc, 0, v25, vcc
	v_add_co_u32_e32 v78, vcc, s46, v24
	s_nop 1
	v_addc_co_u32_e32 v79, vcc, 0, v25, vcc
	v_add_co_u32_e32 v80, vcc, s47, v24
	s_nop 1
	v_addc_co_u32_e32 v81, vcc, 0, v25, vcc
	v_add_co_u32_e32 v82, vcc, s48, v24
	s_nop 1
	v_addc_co_u32_e32 v83, vcc, 0, v25, vcc
	v_add_co_u32_e32 v84, vcc, s49, v24
	s_nop 1
	v_addc_co_u32_e32 v85, vcc, 0, v25, vcc
	global_load_dword v100, v[26:27], off
	global_load_dword v101, v[28:29], off
	global_load_dword v102, v[74:75], off
	global_load_dword v103, v[76:77], off
	global_load_dword v104, v[78:79], off
	global_load_dword v105, v[80:81], off
	global_load_dword v106, v[82:83], off
	s_nop 0
	global_load_dword v84, v[84:85], off
	v_add_co_u32_e32 v26, vcc, s50, v24
	s_nop 1
	v_addc_co_u32_e32 v27, vcc, 0, v25, vcc
	v_add_co_u32_e32 v28, vcc, s51, v24
	s_nop 1
	v_addc_co_u32_e32 v29, vcc, 0, v25, vcc
	v_add_co_u32_e32 v74, vcc, s52, v24
	s_nop 1
	v_addc_co_u32_e32 v75, vcc, 0, v25, vcc
	v_add_co_u32_e32 v76, vcc, s53, v24
	s_nop 1
	v_addc_co_u32_e32 v77, vcc, 0, v25, vcc
	v_add_co_u32_e32 v78, vcc, s54, v24
	s_nop 1
	v_addc_co_u32_e32 v79, vcc, 0, v25, vcc
	v_add_co_u32_e32 v80, vcc, s55, v24
	s_nop 1
	v_addc_co_u32_e32 v81, vcc, 0, v25, vcc
	v_add_co_u32_e32 v82, vcc, s56, v24
	s_nop 1
	v_addc_co_u32_e32 v83, vcc, 0, v25, vcc
	v_add_co_u32_e32 v24, vcc, s57, v24
	s_nop 1
	v_addc_co_u32_e32 v25, vcc, 0, v25, vcc
	global_load_dword v26, v[26:27], off
	s_nop 0
	global_load_dword v27, v[28:29], off
	s_nop 0
	global_load_dword v28, v[74:75], off
	global_load_dword v29, v[76:77], off
	s_nop 0
	global_load_dword v74, v[78:79], off
	global_load_dword v75, v[80:81], off
	global_load_dword v76, v[82:83], off
	s_nop 0
	global_load_dword v24, v[24:25], off
	s_waitcnt vmcnt(30)
	ds_write2_b32 v30, v2, v23 offset1:66
	s_waitcnt vmcnt(28)
	ds_write2_b32 v30, v86, v87 offset0:132 offset1:198
	s_waitcnt vmcnt(26)
	ds_write2_b32 v36, v88, v89 offset0:8 offset1:74
	s_waitcnt vmcnt(24)
	ds_write2_b32 v36, v90, v91 offset0:140 offset1:206
	s_waitcnt vmcnt(22)
	ds_write2_b32 v37, v92, v93 offset0:16 offset1:82
	s_waitcnt vmcnt(20)
	ds_write2_b32 v37, v94, v95 offset0:148 offset1:214
	s_waitcnt vmcnt(18)
	ds_write2_b32 v38, v96, v97 offset0:24 offset1:90
	s_waitcnt vmcnt(16)
	ds_write2_b32 v38, v98, v99 offset0:156 offset1:222
	s_waitcnt vmcnt(14)
	ds_write2_b32 v39, v100, v101 offset0:32 offset1:98
	s_waitcnt vmcnt(12)
	ds_write2_b32 v39, v102, v103 offset0:164 offset1:230
	s_waitcnt vmcnt(10)
	ds_write2_b32 v40, v104, v105 offset0:40 offset1:106
	s_waitcnt vmcnt(8)
	ds_write2_b32 v40, v106, v84 offset0:172 offset1:238
	s_waitcnt vmcnt(6)
	ds_write2_b32 v41, v26, v27 offset0:48 offset1:114
	s_waitcnt vmcnt(4)
	ds_write2_b32 v41, v28, v29 offset0:180 offset1:246
	s_waitcnt vmcnt(2)
	ds_write2_b32 v42, v74, v75 offset0:56 offset1:122
	s_waitcnt vmcnt(0)
	ds_write2_b32 v42, v76, v24 offset0:188 offset1:254
	s_waitcnt lgkmcnt(0)
	ds_read2_b32 v[28:29], v32 offset1:8
	ds_read2_b32 v[76:77], v32 offset0:33 offset1:41
	ds_read2_b32 v[78:79], v32 offset0:66 offset1:74
	ds_read2_b32 v[80:81], v32 offset0:99 offset1:107
	ds_read2_b32 v[82:83], v32 offset0:132 offset1:140
	s_waitcnt lgkmcnt(4)
	v_bfe_u32 v2, v28, 16, 1
	v_add3_u32 v2, v28, v2, s58
	s_waitcnt lgkmcnt(3)
	v_bfe_u32 v23, v76, 16, 1
	v_lshrrev_b32_e32 v2, 16, v2
	v_add3_u32 v23, v76, v23, s58
	ds_read2_b32 v[84:85], v32 offset0:165 offset1:173
	v_and_or_b32 v24, v23, s59, v2
	s_waitcnt lgkmcnt(3)
	v_bfe_u32 v2, v78, 16, 1
	v_add3_u32 v2, v78, v2, s58
	s_waitcnt lgkmcnt(2)
	v_bfe_u32 v23, v80, 16, 1
	ds_read2_b32 v[86:87], v32 offset0:198 offset1:206
	v_lshrrev_b32_e32 v2, 16, v2
	v_add3_u32 v23, v80, v23, s58
	ds_read2_b32 v[88:89], v32 offset0:231 offset1:239
	v_and_or_b32 v25, v23, s59, v2
	s_waitcnt lgkmcnt(3)
	v_bfe_u32 v2, v82, 16, 1
	v_add3_u32 v2, v82, v2, s58
	s_waitcnt lgkmcnt(2)
	v_bfe_u32 v23, v84, 16, 1
	v_lshrrev_b32_e32 v2, 16, v2
	v_add3_u32 v23, v84, v23, s58
	v_and_or_b32 v26, v23, s59, v2
	s_waitcnt lgkmcnt(1)
	v_bfe_u32 v2, v86, 16, 1
	v_add3_u32 v2, v86, v2, s58
	s_waitcnt lgkmcnt(0)
	v_bfe_u32 v23, v88, 16, 1
	v_lshrrev_b32_e32 v2, 16, v2
	v_add3_u32 v23, v88, v23, s58
	v_and_or_b32 v27, v23, s59, v2
	v_or_b32_e32 v2, s0, v31
	v_lshl_add_u64 v[74:75], v[14:15], 0, s[12:13]
	v_lshlrev_b32_e32 v2, 13, v2
	v_lshl_add_u64 v[90:91], v[74:75], 0, v[2:3]
	v_bfe_u32 v2, v29, 16, 1
	v_add3_u32 v2, v29, v2, s58
	v_bfe_u32 v23, v77, 16, 1
	v_lshrrev_b32_e32 v2, 16, v2
	v_add3_u32 v23, v77, v23, s58
	global_store_dwordx4 v[90:91], v[24:27], off sc1
	ds_read2_b32 v[28:29], v32 offset0:16 offset1:24
	s_nop 0
	v_and_or_b32 v24, v23, s59, v2
	v_bfe_u32 v2, v79, 16, 1
	v_add3_u32 v2, v79, v2, s58
	v_bfe_u32 v23, v81, 16, 1
	v_lshrrev_b32_e32 v2, 16, v2
	v_add3_u32 v23, v81, v23, s58
	v_and_or_b32 v25, v23, s59, v2
	v_bfe_u32 v2, v83, 16, 1
	v_add3_u32 v2, v83, v2, s58
	v_bfe_u32 v23, v85, 16, 1
	v_lshrrev_b32_e32 v2, 16, v2
	v_add3_u32 v23, v85, v23, s58
	v_and_or_b32 v26, v23, s59, v2
	v_bfe_u32 v2, v87, 16, 1
	v_add3_u32 v2, v87, v2, s58
	v_bfe_u32 v23, v89, 16, 1
	v_lshrrev_b32_e32 v2, 16, v2
	v_add3_u32 v23, v89, v23, s58
	v_and_or_b32 v27, v23, s59, v2
	v_or_b32_e32 v2, s0, v33
	v_lshlrev_b32_e32 v2, 13, v2
	v_lshl_add_u64 v[76:77], v[74:75], 0, v[2:3]
	global_store_dwordx4 v[76:77], v[24:27], off sc1
	ds_read2_b32 v[76:77], v32 offset0:49 offset1:57
	ds_read2_b32 v[78:79], v32 offset0:82 offset1:90
	ds_read2_b32 v[80:81], v32 offset0:115 offset1:123
	s_waitcnt lgkmcnt(3)
	v_bfe_u32 v2, v28, 16, 1
	v_add3_u32 v2, v28, v2, s58
	s_waitcnt lgkmcnt(2)
	v_bfe_u32 v23, v76, 16, 1
	ds_read2_b32 v[82:83], v32 offset0:148 offset1:156
	v_lshrrev_b32_e32 v2, 16, v2
	v_add3_u32 v23, v76, v23, s58
	ds_read2_b32 v[84:85], v32 offset0:181 offset1:189
	v_and_or_b32 v24, v23, s59, v2
	s_waitcnt lgkmcnt(3)
	v_bfe_u32 v2, v78, 16, 1
	v_add3_u32 v2, v78, v2, s58
	s_waitcnt lgkmcnt(2)
	v_bfe_u32 v23, v80, 16, 1
	ds_read2_b32 v[86:87], v32 offset0:214 offset1:222
	v_lshrrev_b32_e32 v2, 16, v2
	v_add3_u32 v23, v80, v23, s58
	ds_read2_b32 v[88:89], v32 offset0:247 offset1:255
	v_and_or_b32 v25, v23, s59, v2
	s_waitcnt lgkmcnt(3)
	v_bfe_u32 v2, v82, 16, 1
	v_add3_u32 v2, v82, v2, s58
	s_waitcnt lgkmcnt(2)
	v_bfe_u32 v23, v84, 16, 1
	v_lshrrev_b32_e32 v2, 16, v2
	v_add3_u32 v23, v84, v23, s58
	v_and_or_b32 v26, v23, s59, v2
	s_waitcnt lgkmcnt(1)
	v_bfe_u32 v2, v86, 16, 1
	v_add3_u32 v2, v86, v2, s58
	s_waitcnt lgkmcnt(0)
	v_bfe_u32 v23, v88, 16, 1
	v_lshrrev_b32_e32 v2, 16, v2
	v_add3_u32 v23, v88, v23, s58
	v_and_or_b32 v27, v23, s59, v2
	v_or_b32_e32 v2, s0, v34
	v_lshlrev_b32_e32 v2, 13, v2
	v_lshl_add_u64 v[90:91], v[74:75], 0, v[2:3]
	v_bfe_u32 v2, v29, 16, 1
	v_add3_u32 v2, v29, v2, s58
	v_bfe_u32 v23, v77, 16, 1
	v_lshrrev_b32_e32 v2, 16, v2
	v_add3_u32 v23, v77, v23, s58
	global_store_dwordx4 v[90:91], v[24:27], off sc1
	s_nop 1
	v_and_or_b32 v24, v23, s59, v2
	v_bfe_u32 v2, v79, 16, 1
	v_add3_u32 v2, v79, v2, s58
	v_bfe_u32 v23, v81, 16, 1
	v_lshrrev_b32_e32 v2, 16, v2
	v_add3_u32 v23, v81, v23, s58
	v_and_or_b32 v25, v23, s59, v2
	v_bfe_u32 v2, v83, 16, 1
	v_add3_u32 v2, v83, v2, s58
	v_bfe_u32 v23, v85, 16, 1
	v_lshrrev_b32_e32 v2, 16, v2
	v_add3_u32 v23, v85, v23, s58
	v_and_or_b32 v26, v23, s59, v2
	v_bfe_u32 v2, v87, 16, 1
	v_add3_u32 v2, v87, v2, s58
	v_bfe_u32 v23, v89, 16, 1
	v_lshrrev_b32_e32 v2, 16, v2
	v_add3_u32 v23, v89, v23, s58
	v_and_or_b32 v27, v23, s59, v2
	v_or_b32_e32 v2, s0, v35
	v_lshlrev_b32_e32 v2, 13, v2
	v_lshl_add_u64 v[28:29], v[74:75], 0, v[2:3]
	global_store_dwordx4 v[28:29], v[24:27], off sc1
	s_waitcnt lgkmcnt(0)

.LBB0_227:
	s_waitcnt vmcnt(30)
	v_mul_f32_e32 v26, v28, v26
	v_mul_f32_e32 v23, v23, v27
	s_waitcnt vmcnt(1)
	v_mul_f32_e32 v24, v132, v133
	v_mul_f32_e32 v25, v131, v129
	v_mul_f32_e32 v29, v127, v130
	v_mul_f32_e32 v75, v126, v124
	v_mul_f32_e32 v123, v123, v125
	v_mul_f32_e32 v120, v122, v120
	v_mul_f32_e32 v119, v119, v121
	v_mul_f32_e32 v116, v118, v116
	v_mul_f32_e32 v115, v115, v117
	v_mul_f32_e32 v112, v114, v112
	v_mul_f32_e32 v111, v111, v113
	v_mul_f32_e32 v108, v110, v108
	v_mul_f32_e32 v107, v107, v109
	v_mul_f32_e32 v104, v106, v104
	v_mul_f32_e32 v103, v103, v105
	v_mul_f32_e32 v100, v102, v100
	v_mul_f32_e32 v99, v99, v101
	v_mul_f32_e32 v96, v98, v96
	v_mul_f32_e32 v95, v95, v97
	v_mul_f32_e32 v92, v94, v92
	v_mul_f32_e32 v91, v91, v93
	v_mul_f32_e32 v88, v90, v88
	v_mul_f32_e32 v87, v87, v89
	v_mul_f32_e32 v84, v86, v84
	v_mul_f32_e32 v83, v83, v85
	v_mul_f32_e32 v80, v82, v80
	v_mul_f32_e32 v79, v79, v81
	v_mul_f32_e32 v76, v78, v76
	v_mul_f32_e32 v74, v74, v77
	s_waitcnt vmcnt(0)
	v_mul_f32_e32 v2, v2, v128
	ds_write2_b32 v30, v23, v26 offset1:66
	ds_write2_b32 v30, v74, v76 offset0:132 offset1:198
	ds_write2_b32 v36, v79, v80 offset0:8 offset1:74
	ds_write2_b32 v36, v83, v84 offset0:140 offset1:206
	ds_write2_b32 v37, v87, v88 offset0:16 offset1:82
	ds_write2_b32 v37, v91, v92 offset0:148 offset1:214
	ds_write2_b32 v38, v95, v96 offset0:24 offset1:90
	ds_write2_b32 v38, v99, v100 offset0:156 offset1:222
	ds_write2_b32 v39, v103, v104 offset0:32 offset1:98
	ds_write2_b32 v39, v107, v108 offset0:164 offset1:230
	ds_write2_b32 v40, v111, v112 offset0:40 offset1:106
	ds_write2_b32 v40, v115, v116 offset0:172 offset1:238
	ds_write2_b32 v41, v119, v120 offset0:48 offset1:114
	ds_write2_b32 v41, v123, v75 offset0:180 offset1:246
	ds_write2_b32 v42, v29, v25 offset0:56 offset1:122
	ds_write2_b32 v42, v24, v2 offset0:188 offset1:254
	s_waitcnt lgkmcnt(0)
	ds_read2_b32 v[28:29], v32 offset1:8
	ds_read2_b32 v[76:77], v32 offset0:33 offset1:41
	ds_read2_b32 v[78:79], v32 offset0:66 offset1:74
	ds_read2_b32 v[80:81], v32 offset0:99 offset1:107
	ds_read2_b32 v[82:83], v32 offset0:132 offset1:140
	s_waitcnt lgkmcnt(4)
	v_bfe_u32 v2, v28, 16, 1
	v_add3_u32 v2, v28, v2, s58
	s_waitcnt lgkmcnt(3)
	v_bfe_u32 v23, v76, 16, 1
	v_lshrrev_b32_e32 v2, 16, v2
	v_add3_u32 v23, v76, v23, s58
	ds_read2_b32 v[84:85], v32 offset0:165 offset1:173
	v_and_or_b32 v24, v23, s59, v2
	s_waitcnt lgkmcnt(3)
	v_bfe_u32 v2, v78, 16, 1
	v_add3_u32 v2, v78, v2, s58
	s_waitcnt lgkmcnt(2)
	v_bfe_u32 v23, v80, 16, 1
	ds_read2_b32 v[86:87], v32 offset0:198 offset1:206
	v_lshrrev_b32_e32 v2, 16, v2
	v_add3_u32 v23, v80, v23, s58
	ds_read2_b32 v[88:89], v32 offset0:231 offset1:239
	v_and_or_b32 v25, v23, s59, v2
	s_waitcnt lgkmcnt(3)
	v_bfe_u32 v2, v82, 16, 1
	v_add3_u32 v2, v82, v2, s58
	s_waitcnt lgkmcnt(2)
	v_bfe_u32 v23, v84, 16, 1
	v_lshrrev_b32_e32 v2, 16, v2
	v_add3_u32 v23, v84, v23, s58
	v_and_or_b32 v26, v23, s59, v2
	s_waitcnt lgkmcnt(1)
	v_bfe_u32 v2, v86, 16, 1
	v_add3_u32 v2, v86, v2, s58
	s_waitcnt lgkmcnt(0)
	v_bfe_u32 v23, v88, 16, 1
	v_lshrrev_b32_e32 v2, 16, v2
	v_add3_u32 v23, v88, v23, s58
	s_lshl_b32 s12, s5, 1
	v_and_or_b32 v27, v23, s59, v2
	v_or_b32_e32 v2, s4, v31
	v_lshl_add_u64 v[74:75], v[16:17], 0, s[12:13]
	v_lshlrev_b32_e32 v2, 11, v2
	v_lshl_add_u64 v[90:91], v[74:75], 0, v[2:3]
	v_bfe_u32 v2, v29, 16, 1
	v_add3_u32 v2, v29, v2, s58
	v_bfe_u32 v23, v77, 16, 1
	v_lshrrev_b32_e32 v2, 16, v2
	v_add3_u32 v23, v77, v23, s58
	global_store_dwordx4 v[90:91], v[24:27], off sc1
	ds_read2_b32 v[28:29], v32 offset0:16 offset1:24
	s_nop 0
	v_and_or_b32 v24, v23, s59, v2
	v_bfe_u32 v2, v79, 16, 1
	v_add3_u32 v2, v79, v2, s58
	v_bfe_u32 v23, v81, 16, 1
	v_lshrrev_b32_e32 v2, 16, v2
	v_add3_u32 v23, v81, v23, s58
	v_and_or_b32 v25, v23, s59, v2
	v_bfe_u32 v2, v83, 16, 1
	v_add3_u32 v2, v83, v2, s58
	v_bfe_u32 v23, v85, 16, 1
	v_lshrrev_b32_e32 v2, 16, v2
	v_add3_u32 v23, v85, v23, s58
	v_and_or_b32 v26, v23, s59, v2
	v_bfe_u32 v2, v87, 16, 1
	v_add3_u32 v2, v87, v2, s58
	v_bfe_u32 v23, v89, 16, 1
	v_lshrrev_b32_e32 v2, 16, v2
	v_add3_u32 v23, v89, v23, s58
	v_and_or_b32 v27, v23, s59, v2
	v_or_b32_e32 v2, s4, v33
	v_lshlrev_b32_e32 v2, 11, v2
	v_lshl_add_u64 v[76:77], v[74:75], 0, v[2:3]
	global_store_dwordx4 v[76:77], v[24:27], off sc1
	ds_read2_b32 v[76:77], v32 offset0:49 offset1:57
	ds_read2_b32 v[78:79], v32 offset0:82 offset1:90
	ds_read2_b32 v[80:81], v32 offset0:115 offset1:123
	s_waitcnt lgkmcnt(3)
	v_bfe_u32 v2, v28, 16, 1
	v_add3_u32 v2, v28, v2, s58
	s_waitcnt lgkmcnt(2)
	v_bfe_u32 v23, v76, 16, 1
	ds_read2_b32 v[82:83], v32 offset0:148 offset1:156
	v_lshrrev_b32_e32 v2, 16, v2
	v_add3_u32 v23, v76, v23, s58
	ds_read2_b32 v[84:85], v32 offset0:181 offset1:189
	v_and_or_b32 v24, v23, s59, v2
	s_waitcnt lgkmcnt(3)
	v_bfe_u32 v2, v78, 16, 1
	v_add3_u32 v2, v78, v2, s58
	s_waitcnt lgkmcnt(2)
	v_bfe_u32 v23, v80, 16, 1
	ds_read2_b32 v[86:87], v32 offset0:214 offset1:222
	v_lshrrev_b32_e32 v2, 16, v2
	v_add3_u32 v23, v80, v23, s58
	ds_read2_b32 v[88:89], v32 offset0:247 offset1:255
	v_and_or_b32 v25, v23, s59, v2
	s_waitcnt lgkmcnt(3)
	v_bfe_u32 v2, v82, 16, 1
	v_add3_u32 v2, v82, v2, s58
	s_waitcnt lgkmcnt(2)
	v_bfe_u32 v23, v84, 16, 1
	v_lshrrev_b32_e32 v2, 16, v2
	v_add3_u32 v23, v84, v23, s58
	v_and_or_b32 v26, v23, s59, v2
	s_waitcnt lgkmcnt(1)
	v_bfe_u32 v2, v86, 16, 1
	v_add3_u32 v2, v86, v2, s58
	s_waitcnt lgkmcnt(0)
	v_bfe_u32 v23, v88, 16, 1
	v_lshrrev_b32_e32 v2, 16, v2
	v_add3_u32 v23, v88, v23, s58
	v_and_or_b32 v27, v23, s59, v2
	v_or_b32_e32 v2, s4, v34
	v_lshlrev_b32_e32 v2, 11, v2
	v_lshl_add_u64 v[90:91], v[74:75], 0, v[2:3]
	v_bfe_u32 v2, v29, 16, 1
	v_add3_u32 v2, v29, v2, s58
	v_bfe_u32 v23, v77, 16, 1
	v_lshrrev_b32_e32 v2, 16, v2
	v_add3_u32 v23, v77, v23, s58
	global_store_dwordx4 v[90:91], v[24:27], off sc1
	s_nop 1
	v_and_or_b32 v24, v23, s59, v2
	v_bfe_u32 v2, v79, 16, 1
	v_add3_u32 v2, v79, v2, s58
	v_bfe_u32 v23, v81, 16, 1
	v_lshrrev_b32_e32 v2, 16, v2
	v_add3_u32 v23, v81, v23, s58
	v_and_or_b32 v25, v23, s59, v2
	v_bfe_u32 v2, v83, 16, 1
	v_add3_u32 v2, v83, v2, s58
	v_bfe_u32 v23, v85, 16, 1
	v_lshrrev_b32_e32 v2, 16, v2
	v_add3_u32 v23, v85, v23, s58
	v_and_or_b32 v26, v23, s59, v2
	v_bfe_u32 v2, v87, 16, 1
	v_add3_u32 v2, v87, v2, s58
	v_bfe_u32 v23, v89, 16, 1
	v_lshrrev_b32_e32 v2, 16, v2
	v_add3_u32 v23, v89, v23, s58
	v_and_or_b32 v27, v23, s59, v2
	v_or_b32_e32 v2, s4, v35
	v_lshlrev_b32_e32 v2, 11, v2
	v_lshl_add_u64 v[28:29], v[74:75], 0, v[2:3]
	global_store_dwordx4 v[28:29], v[24:27], off sc1
	s_waitcnt lgkmcnt(0)

.LBB0_229:
	s_andn2_b64 vcc, exec, s[0:1]
	s_cbranch_vccnz .LBB0_231
	s_load_dwordx2 s[4:5], s[92:93], 0x48
	s_add_i32 s0, s16, 0x4640
	s_and_b32 s1, s0, 0x1ffc0
	s_and_b32 s0, s14, 0x3e0
	s_lshl_b32 s6, s0, 2
	s_waitcnt lgkmcnt(0)
	s_add_u32 s4, s4, s6
	v_or_b32_e32 v2, s1, v1
	s_addc_u32 s5, s5, 0
	v_mov_b32_e32 v23, v3
	v_lshl_add_u64 v[24:25], s[4:5], 0, v[22:23]
	v_lshlrev_b32_e32 v2, 12, v2
	v_lshl_add_u64 v[24:25], v[24:25], 0, v[2:3]
	v_add_co_u32_e32 v26, vcc, s20, v24
	s_lshl_b32 s12, s1, 1
	s_nop 0
	v_addc_co_u32_e32 v27, vcc, 0, v25, vcc
	v_add_co_u32_e32 v28, vcc, s21, v24
	s_nop 1
	v_addc_co_u32_e32 v29, vcc, 0, v25, vcc
	v_add_co_u32_e32 v74, vcc, s22, v24
	s_nop 1
	v_addc_co_u32_e32 v75, vcc, 0, v25, vcc
	v_add_co_u32_e32 v76, vcc, s23, v24
	s_nop 1
	v_addc_co_u32_e32 v77, vcc, 0, v25, vcc
	v_add_co_u32_e32 v78, vcc, s30, v24
	s_nop 1
	v_addc_co_u32_e32 v79, vcc, 0, v25, vcc
	v_add_co_u32_e32 v80, vcc, s31, v24
	s_nop 1
	v_addc_co_u32_e32 v81, vcc, 0, v25, vcc
	v_add_co_u32_e32 v82, vcc, s33, v24
	s_nop 1
	v_addc_co_u32_e32 v83, vcc, 0, v25, vcc
	global_load_dword v2, v[24:25], off
	global_load_dword v23, v[26:27], off
	global_load_dword v86, v[28:29], off
	global_load_dword v87, v[74:75], off
	global_load_dword v88, v[76:77], off
	global_load_dword v89, v[78:79], off
	global_load_dword v90, v[80:81], off
	global_load_dword v91, v[82:83], off
	v_add_co_u32_e32 v26, vcc, s34, v24
	s_nop 1
	v_addc_co_u32_e32 v27, vcc, 0, v25, vcc
	v_add_co_u32_e32 v28, vcc, s35, v24
	s_nop 1
	v_addc_co_u32_e32 v29, vcc, 0, v25, vcc
	v_add_co_u32_e32 v74, vcc, s36, v24
	s_nop 1
	v_addc_co_u32_e32 v75, vcc, 0, v25, vcc
	v_add_co_u32_e32 v76, vcc, s37, v24
	s_nop 1
	v_addc_co_u32_e32 v77, vcc, 0, v25, vcc
	v_add_co_u32_e32 v78, vcc, s38, v24
	s_nop 1
	v_addc_co_u32_e32 v79, vcc, 0, v25, vcc
	v_add_co_u32_e32 v80, vcc, s39, v24
	s_nop 1
	v_addc_co_u32_e32 v81, vcc, 0, v25, vcc
	v_add_co_u32_e32 v82, vcc, s40, v24
	s_nop 1
	v_addc_co_u32_e32 v83, vcc, 0, v25, vcc
	v_add_co_u32_e32 v84, vcc, s41, v24
	s_nop 1
	v_addc_co_u32_e32 v85, vcc, 0, v25, vcc
	global_load_dword v92, v[26:27], off
	global_load_dword v93, v[28:29], off
	global_load_dword v94, v[74:75], off
	global_load_dword v95, v[76:77], off
	global_load_dword v96, v[78:79], off
	global_load_dword v97, v[80:81], off
	global_load_dword v98, v[82:83], off
	global_load_dword v99, v[84:85], off
	v_add_co_u32_e32 v26, vcc, s42, v24
	s_nop 1
	v_addc_co_u32_e32 v27, vcc, 0, v25, vcc
	v_add_co_u32_e32 v28, vcc, s43, v24
	s_nop 1
	v_addc_co_u32_e32 v29, vcc, 0, v25, vcc
	v_add_co_u32_e32 v74, vcc, s44, v24
	s_nop 1
	v_addc_co_u32_e32 v75, vcc, 0, v25, vcc
	v_add_co_u32_e32 v76, vcc, s45, v24
	s_nop 1
	v_addc_co_u32_e32 v77, vcc, 0, v25, vcc
	v_add_co_u32_e32 v78, vcc, s46, v24
	s_nop 1
	v_addc_co_u32_e32 v79, vcc, 0, v25, vcc
	v_add_co_u32_e32 v80, vcc, s47, v24
	s_nop 1
	v_addc_co_u32_e32 v81, vcc, 0, v25, vcc
	v_add_co_u32_e32 v82, vcc, s48, v24
	s_nop 1
	v_addc_co_u32_e32 v83, vcc, 0, v25, vcc
	v_add_co_u32_e32 v84, vcc, s49, v24
	s_nop 1
	v_addc_co_u32_e32 v85, vcc, 0, v25, vcc
	global_load_dword v100, v[26:27], off
	global_load_dword v101, v[28:29], off
	global_load_dword v102, v[74:75], off
	global_load_dword v103, v[76:77], off
	global_load_dword v104, v[78:79], off
	global_load_dword v105, v[80:81], off
	global_load_dword v106, v[82:83], off
	s_nop 0
	global_load_dword v84, v[84:85], off
	v_add_co_u32_e32 v26, vcc, s50, v24
	s_nop 1
	v_addc_co_u32_e32 v27, vcc, 0, v25, vcc
	v_add_co_u32_e32 v28, vcc, s51, v24
	s_nop 1
	v_addc_co_u32_e32 v29, vcc, 0, v25, vcc
	v_add_co_u32_e32 v74, vcc, s52, v24
	s_nop 1
	v_addc_co_u32_e32 v75, vcc, 0, v25, vcc
	v_add_co_u32_e32 v76, vcc, s53, v24
	s_nop 1
	v_addc_co_u32_e32 v77, vcc, 0, v25, vcc
	v_add_co_u32_e32 v78, vcc, s54, v24
	s_nop 1
	v_addc_co_u32_e32 v79, vcc, 0, v25, vcc
	v_add_co_u32_e32 v80, vcc, s55, v24
	s_nop 1
	v_addc_co_u32_e32 v81, vcc, 0, v25, vcc
	v_add_co_u32_e32 v82, vcc, s56, v24
	s_nop 1
	v_addc_co_u32_e32 v83, vcc, 0, v25, vcc
	v_add_co_u32_e32 v24, vcc, s57, v24
	s_nop 1
	v_addc_co_u32_e32 v25, vcc, 0, v25, vcc
	global_load_dword v26, v[26:27], off
	s_nop 0
	global_load_dword v27, v[28:29], off
	s_nop 0
	global_load_dword v28, v[74:75], off
	global_load_dword v29, v[76:77], off
	s_nop 0
	global_load_dword v74, v[78:79], off
	global_load_dword v75, v[80:81], off
	global_load_dword v76, v[82:83], off
	s_nop 0
	global_load_dword v24, v[24:25], off
	s_waitcnt vmcnt(30)
	ds_write2_b32 v30, v2, v23 offset1:66
	s_waitcnt vmcnt(28)
	ds_write2_b32 v30, v86, v87 offset0:132 offset1:198
	s_waitcnt vmcnt(26)
	ds_write2_b32 v36, v88, v89 offset0:8 offset1:74
	s_waitcnt vmcnt(24)
	ds_write2_b32 v36, v90, v91 offset0:140 offset1:206
	s_waitcnt vmcnt(22)
	ds_write2_b32 v37, v92, v93 offset0:16 offset1:82
	s_waitcnt vmcnt(20)
	ds_write2_b32 v37, v94, v95 offset0:148 offset1:214
	s_waitcnt vmcnt(18)
	ds_write2_b32 v38, v96, v97 offset0:24 offset1:90
	s_waitcnt vmcnt(16)
	ds_write2_b32 v38, v98, v99 offset0:156 offset1:222
	s_waitcnt vmcnt(14)
	ds_write2_b32 v39, v100, v101 offset0:32 offset1:98
	s_waitcnt vmcnt(12)
	ds_write2_b32 v39, v102, v103 offset0:164 offset1:230
	s_waitcnt vmcnt(10)
	ds_write2_b32 v40, v104, v105 offset0:40 offset1:106
	s_waitcnt vmcnt(8)
	ds_write2_b32 v40, v106, v84 offset0:172 offset1:238
	s_waitcnt vmcnt(6)
	ds_write2_b32 v41, v26, v27 offset0:48 offset1:114
	s_waitcnt vmcnt(4)
	ds_write2_b32 v41, v28, v29 offset0:180 offset1:246
	s_waitcnt vmcnt(2)
	ds_write2_b32 v42, v74, v75 offset0:56 offset1:122
	s_waitcnt vmcnt(0)
	ds_write2_b32 v42, v76, v24 offset0:188 offset1:254
	s_waitcnt lgkmcnt(0)
	ds_read2_b32 v[28:29], v32 offset1:8
	ds_read2_b32 v[76:77], v32 offset0:33 offset1:41
	ds_read2_b32 v[78:79], v32 offset0:66 offset1:74
	ds_read2_b32 v[80:81], v32 offset0:99 offset1:107
	ds_read2_b32 v[82:83], v32 offset0:132 offset1:140
	s_waitcnt lgkmcnt(4)
	v_bfe_u32 v2, v28, 16, 1
	v_add3_u32 v2, v28, v2, s58
	s_waitcnt lgkmcnt(3)
	v_bfe_u32 v23, v76, 16, 1
	v_lshrrev_b32_e32 v2, 16, v2
	v_add3_u32 v23, v76, v23, s58
	ds_read2_b32 v[84:85], v32 offset0:165 offset1:173
	v_and_or_b32 v24, v23, s59, v2
	s_waitcnt lgkmcnt(3)
	v_bfe_u32 v2, v78, 16, 1
	v_add3_u32 v2, v78, v2, s58
	s_waitcnt lgkmcnt(2)
	v_bfe_u32 v23, v80, 16, 1
	ds_read2_b32 v[86:87], v32 offset0:198 offset1:206
	v_lshrrev_b32_e32 v2, 16, v2
	v_add3_u32 v23, v80, v23, s58
	ds_read2_b32 v[88:89], v32 offset0:231 offset1:239
	v_and_or_b32 v25, v23, s59, v2
	s_waitcnt lgkmcnt(3)
	v_bfe_u32 v2, v82, 16, 1
	v_add3_u32 v2, v82, v2, s58
	s_waitcnt lgkmcnt(2)
	v_bfe_u32 v23, v84, 16, 1
	v_lshrrev_b32_e32 v2, 16, v2
	v_add3_u32 v23, v84, v23, s58
	v_and_or_b32 v26, v23, s59, v2
	s_waitcnt lgkmcnt(1)
	v_bfe_u32 v2, v86, 16, 1
	v_add3_u32 v2, v86, v2, s58
	s_waitcnt lgkmcnt(0)
	v_bfe_u32 v23, v88, 16, 1
	v_lshrrev_b32_e32 v2, 16, v2
	v_add3_u32 v23, v88, v23, s58
	v_and_or_b32 v27, v23, s59, v2
	v_or_b32_e32 v2, s0, v31
	v_lshl_add_u64 v[74:75], v[18:19], 0, s[12:13]
	v_lshlrev_b32_e32 v2, 11, v2
	v_lshl_add_u64 v[90:91], v[74:75], 0, v[2:3]
	v_bfe_u32 v2, v29, 16, 1
	v_add3_u32 v2, v29, v2, s58
	v_bfe_u32 v23, v77, 16, 1
	v_lshrrev_b32_e32 v2, 16, v2
	v_add3_u32 v23, v77, v23, s58
	global_store_dwordx4 v[90:91], v[24:27], off sc1
	ds_read2_b32 v[28:29], v32 offset0:16 offset1:24
	s_nop 0
	v_and_or_b32 v24, v23, s59, v2
	v_bfe_u32 v2, v79, 16, 1
	v_add3_u32 v2, v79, v2, s58
	v_bfe_u32 v23, v81, 16, 1
	v_lshrrev_b32_e32 v2, 16, v2
	v_add3_u32 v23, v81, v23, s58
	v_and_or_b32 v25, v23, s59, v2
	v_bfe_u32 v2, v83, 16, 1
	v_add3_u32 v2, v83, v2, s58
	v_bfe_u32 v23, v85, 16, 1
	v_lshrrev_b32_e32 v2, 16, v2
	v_add3_u32 v23, v85, v23, s58
	v_and_or_b32 v26, v23, s59, v2
	v_bfe_u32 v2, v87, 16, 1
	v_add3_u32 v2, v87, v2, s58
	v_bfe_u32 v23, v89, 16, 1
	v_lshrrev_b32_e32 v2, 16, v2
	v_add3_u32 v23, v89, v23, s58
	v_and_or_b32 v27, v23, s59, v2
	v_or_b32_e32 v2, s0, v33
	v_lshlrev_b32_e32 v2, 11, v2
	v_lshl_add_u64 v[76:77], v[74:75], 0, v[2:3]
	global_store_dwordx4 v[76:77], v[24:27], off sc1
	ds_read2_b32 v[76:77], v32 offset0:49 offset1:57
	ds_read2_b32 v[78:79], v32 offset0:82 offset1:90
	ds_read2_b32 v[80:81], v32 offset0:115 offset1:123
	s_waitcnt lgkmcnt(3)
	v_bfe_u32 v2, v28, 16, 1
	v_add3_u32 v2, v28, v2, s58
	s_waitcnt lgkmcnt(2)
	v_bfe_u32 v23, v76, 16, 1
	ds_read2_b32 v[82:83], v32 offset0:148 offset1:156
	v_lshrrev_b32_e32 v2, 16, v2
	v_add3_u32 v23, v76, v23, s58
	ds_read2_b32 v[84:85], v32 offset0:181 offset1:189
	v_and_or_b32 v24, v23, s59, v2
	s_waitcnt lgkmcnt(3)
	v_bfe_u32 v2, v78, 16, 1
	v_add3_u32 v2, v78, v2, s58
	s_waitcnt lgkmcnt(2)
	v_bfe_u32 v23, v80, 16, 1
	ds_read2_b32 v[86:87], v32 offset0:214 offset1:222
	v_lshrrev_b32_e32 v2, 16, v2
	v_add3_u32 v23, v80, v23, s58
	ds_read2_b32 v[88:89], v32 offset0:247 offset1:255
	v_and_or_b32 v25, v23, s59, v2
	s_waitcnt lgkmcnt(3)
	v_bfe_u32 v2, v82, 16, 1
	v_add3_u32 v2, v82, v2, s58
	s_waitcnt lgkmcnt(2)
	v_bfe_u32 v23, v84, 16, 1
	v_lshrrev_b32_e32 v2, 16, v2
	v_add3_u32 v23, v84, v23, s58
	v_and_or_b32 v26, v23, s59, v2
	s_waitcnt lgkmcnt(1)
	v_bfe_u32 v2, v86, 16, 1
	v_add3_u32 v2, v86, v2, s58
	s_waitcnt lgkmcnt(0)
	v_bfe_u32 v23, v88, 16, 1
	v_lshrrev_b32_e32 v2, 16, v2
	v_add3_u32 v23, v88, v23, s58
	v_and_or_b32 v27, v23, s59, v2
	v_or_b32_e32 v2, s0, v34
	v_lshlrev_b32_e32 v2, 11, v2
	v_lshl_add_u64 v[90:91], v[74:75], 0, v[2:3]
	v_bfe_u32 v2, v29, 16, 1
	v_add3_u32 v2, v29, v2, s58
	v_bfe_u32 v23, v77, 16, 1
	v_lshrrev_b32_e32 v2, 16, v2
	v_add3_u32 v23, v77, v23, s58
	global_store_dwordx4 v[90:91], v[24:27], off sc1
	s_nop 1
	v_and_or_b32 v24, v23, s59, v2
	v_bfe_u32 v2, v79, 16, 1
	v_add3_u32 v2, v79, v2, s58
	v_bfe_u32 v23, v81, 16, 1
	v_lshrrev_b32_e32 v2, 16, v2
	v_add3_u32 v23, v81, v23, s58
	v_and_or_b32 v25, v23, s59, v2
	v_bfe_u32 v2, v83, 16, 1
	v_add3_u32 v2, v83, v2, s58
	v_bfe_u32 v23, v85, 16, 1
	v_lshrrev_b32_e32 v2, 16, v2
	v_add3_u32 v23, v85, v23, s58
	v_and_or_b32 v26, v23, s59, v2
	v_bfe_u32 v2, v87, 16, 1
	v_add3_u32 v2, v87, v2, s58
	v_bfe_u32 v23, v89, 16, 1
	v_lshrrev_b32_e32 v2, 16, v2
	v_add3_u32 v23, v89, v23, s58
	v_and_or_b32 v27, v23, s59, v2
	v_or_b32_e32 v2, s0, v35
	v_lshlrev_b32_e32 v2, 11, v2
	v_lshl_add_u64 v[28:29], v[74:75], 0, v[2:3]
	global_store_dwordx4 v[28:29], v[24:27], off sc1
	s_waitcnt lgkmcnt(0)

.LBB0_310:
	v_mul_f32_e32 v175, v159, v159
	s_waitcnt lgkmcnt(0)
	v_mul_f32_e32 v176, v161, v161
	v_fmac_f32_e32 v175, v158, v158
	v_fmac_f32_e32 v176, v160, v160
	v_add_f32_e32 v175, v175, v176
	v_mul_f32_e32 v176, v155, v155
	v_mul_f32_e32 v185, v157, v157
	v_fmac_f32_e32 v176, v154, v154
	v_fmac_f32_e32 v185, v156, v156
	v_add_f32_e32 v176, v176, v185
	v_add_f32_e32 v175, v176, v175
	v_mul_f32_e32 v176, v151, v151
	v_mul_f32_e32 v185, v153, v153
	v_fmac_f32_e32 v176, v150, v150
	v_fmac_f32_e32 v185, v152, v152
	v_add_f32_e32 v176, v176, v185
	v_add_f32_e32 v175, v176, v175
	v_mul_f32_e32 v176, v147, v147
	v_mul_f32_e32 v185, v149, v149
	v_fmac_f32_e32 v176, v146, v146
	v_fmac_f32_e32 v185, v148, v148
	v_add_f32_e32 v176, v176, v185
	v_add_f32_e32 v175, v176, v175
	ds_bpermute_b32 v176, v1, v175
	v_lshl_add_u64 v[186:187], s[28:29], 0, v[166:167]
	s_waitcnt lgkmcnt(0)
	v_add_f32_e32 v175, v175, v176
	ds_bpermute_b32 v176, v171, v175
	s_waitcnt lgkmcnt(0)
	v_add_f32_e32 v175, v175, v176
	ds_bpermute_b32 v176, v177, v175
	s_waitcnt lgkmcnt(0)
	v_add_f32_e32 v175, v175, v176
	ds_bpermute_b32 v176, v178, v175
	s_waitcnt lgkmcnt(0)
	v_add_f32_e32 v175, v175, v176
	ds_bpermute_b32 v176, v179, v175
	s_waitcnt lgkmcnt(0)
	v_add_f32_e32 v175, v175, v176
	ds_bpermute_b32 v176, v180, v175
	s_waitcnt lgkmcnt(0)
	v_add_f32_e32 v175, v175, v176
	v_fmamk_f32 v175, v175, 0x3a800000, v181
	v_rsq_f32_e32 v176, v175
	s_nop 0
	v_pk_mul_f32 v[188:189], v[158:159], v[176:177] op_sel_hi:[1,0]
	v_pk_mul_f32 v[160:161], v[160:161], v[176:177] op_sel_hi:[1,0]
	v_bfe_u32 v158, v188, 16, 1
	v_bfe_u32 v159, v189, 16, 1
	v_bfe_u32 v175, v160, 16, 1
	v_add3_u32 v158, v188, v158, s0
	v_bfe_u32 v185, v161, 16, 1
	v_add3_u32 v159, v189, v159, s0
	v_add3_u32 v175, v160, v175, s0
	v_lshrrev_b32_e32 v158, 16, v158
	v_add3_u32 v185, v161, v185, s0
	v_lshrrev_b32_e32 v175, 16, v175
	v_and_or_b32 v190, v159, s1, v158
	v_add_co_u32_e32 v158, vcc, s33, v186
	v_and_or_b32 v191, v185, s1, v175
	s_nop 0
	v_addc_co_u32_e32 v159, vcc, 0, v187, vcc
	global_store_dwordx2 v[158:159], v[190:191], off sc1
	v_fma_f32 v190, v3, v188, 0
	v_fmac_f32_e32 v190, v11, v189
	v_fmac_f32_e32 v190, v19, v160
	v_fma_f32 v175, v2, v188, 0
	v_fma_f32 v185, v6, v188, 0
	v_fma_f32 v191, v7, v188, 0
	v_fma_f32 v192, v4, v188, 0
	v_fma_f32 v193, v8, v188, 0
	v_fma_f32 v194, v5, v188, 0
	v_fma_f32 v195, v9, v188, 0
	v_fmac_f32_e32 v190, v161, v27
	v_pk_mul_f32 v[154:155], v[154:155], v[176:177] op_sel_hi:[1,0]
	v_fmac_f32_e32 v175, v10, v189
	v_fmac_f32_e32 v185, v14, v189
	v_fmac_f32_e32 v191, v15, v189
	v_fmac_f32_e32 v192, v12, v189
	v_fmac_f32_e32 v193, v16, v189
	v_fmac_f32_e32 v194, v13, v189
	v_fmac_f32_e32 v195, v17, v189
	v_fmac_f32_e32 v190, v154, v35
	v_fmac_f32_e32 v175, v18, v160
	v_fmac_f32_e32 v185, v22, v160
	v_fmac_f32_e32 v191, v23, v160
	v_fmac_f32_e32 v192, v20, v160
	v_fmac_f32_e32 v193, v24, v160
	v_fmac_f32_e32 v194, v21, v160
	v_fmac_f32_e32 v195, v25, v160
	v_pk_mul_f32 v[156:157], v[156:157], v[176:177] op_sel_hi:[1,0]
	v_bfe_u32 v160, v154, 16, 1
	v_fmac_f32_e32 v190, v155, v43
	v_fmac_f32_e32 v175, v161, v26
	v_fmac_f32_e32 v185, v161, v30
	v_fmac_f32_e32 v191, v161, v31
	v_fmac_f32_e32 v192, v161, v28
	v_fmac_f32_e32 v193, v161, v32
	v_fmac_f32_e32 v194, v161, v29
	v_fmac_f32_e32 v195, v161, v33
	v_add3_u32 v160, v154, v160, s0
	v_bfe_u32 v161, v155, 16, 1
	v_fmac_f32_e32 v190, v156, v51
	v_lshrrev_b32_e32 v160, 16, v160
	v_add3_u32 v161, v155, v161, s0
	v_fmac_f32_e32 v190, v157, v59
	v_pk_mul_f32 v[150:151], v[150:151], v[176:177] op_sel_hi:[1,0]
	v_and_or_b32 v160, v161, s1, v160
	v_bfe_u32 v161, v156, 16, 1
	v_fmac_f32_e32 v190, v150, v67
	v_add3_u32 v161, v156, v161, s0
	v_bfe_u32 v186, v157, 16, 1
	v_pk_mul_f32 v[152:153], v[152:153], v[176:177] op_sel_hi:[1,0]
	v_fmac_f32_e32 v190, v151, v75
	v_lshrrev_b32_e32 v161, 16, v161
	v_add3_u32 v186, v157, v186, s0
	v_fmac_f32_e32 v190, v152, v83
	v_pk_mul_f32 v[146:147], v[146:147], v[176:177] op_sel_hi:[1,0]
	v_and_or_b32 v161, v186, s1, v161
	v_fmac_f32_e32 v190, v153, v91
	v_pk_mul_f32 v[186:187], v[148:149], v[176:177] op_sel_hi:[1,0]
	v_bfe_u32 v148, v146, 16, 1
	v_add3_u32 v148, v146, v148, s0
	v_bfe_u32 v149, v147, 16, 1
	v_fmac_f32_e32 v190, v146, v99
	v_lshrrev_b32_e32 v148, 16, v148
	v_add3_u32 v149, v147, v149, s0
	v_fmac_f32_e32 v190, v147, v107
	v_and_or_b32 v188, v149, s1, v148
	v_bfe_u32 v148, v186, 16, 1
	v_fmac_f32_e32 v190, v186, v115
	v_fmac_f32_e32 v192, v154, v36
	v_add3_u32 v148, v186, v148, s0
	v_fmac_f32_e32 v190, v187, v123
	v_fmac_f32_e32 v192, v155, v44
	v_lshrrev_b32_e32 v189, 16, v148
	ds_bpermute_b32 v148, v1, v190
	v_fmac_f32_e32 v192, v156, v52
	v_fmac_f32_e32 v192, v157, v60
	v_fmac_f32_e32 v192, v150, v68
	v_fmac_f32_e32 v192, v151, v76
	v_fmac_f32_e32 v192, v152, v84
	s_waitcnt lgkmcnt(0)
	v_add_f32_e32 v148, v190, v148
	v_fmac_f32_e32 v192, v153, v92
	ds_bpermute_b32 v149, v171, v148
	v_fmac_f32_e32 v175, v154, v34
	v_fmac_f32_e32 v185, v154, v38
	v_fmac_f32_e32 v191, v154, v39
	v_fmac_f32_e32 v193, v154, v40
	v_fmac_f32_e32 v194, v154, v37
	v_fmac_f32_e32 v195, v154, v41
	v_fmac_f32_e32 v192, v146, v100
	v_fmac_f32_e32 v175, v155, v42
	v_fmac_f32_e32 v185, v155, v46
	v_fmac_f32_e32 v191, v155, v47
	v_fmac_f32_e32 v193, v155, v48
	v_fmac_f32_e32 v194, v155, v45
	v_fmac_f32_e32 v195, v155, v49
	v_fmac_f32_e32 v192, v147, v108
	v_fmac_f32_e32 v175, v156, v50
	v_fmac_f32_e32 v185, v156, v54
	v_fmac_f32_e32 v191, v156, v55
	v_fmac_f32_e32 v193, v156, v56
	v_fmac_f32_e32 v194, v156, v53
	v_fmac_f32_e32 v195, v156, v57
	v_fmac_f32_e32 v192, v186, v116
	v_fmac_f32_e32 v175, v157, v58
	v_fmac_f32_e32 v185, v157, v62
	v_fmac_f32_e32 v191, v157, v63
	v_fmac_f32_e32 v193, v157, v64
	v_fmac_f32_e32 v194, v157, v61
	v_fmac_f32_e32 v195, v157, v65
	v_bfe_u32 v154, v150, 16, 1
	v_fmac_f32_e32 v192, v187, v124
	v_add3_u32 v154, v150, v154, s0
	v_fmac_f32_e32 v175, v150, v66
	v_fmac_f32_e32 v185, v150, v70
	v_fmac_f32_e32 v191, v150, v71
	v_fmac_f32_e32 v193, v150, v72
	v_fmac_f32_e32 v194, v150, v69
	v_fmac_f32_e32 v195, v150, v73
	s_waitcnt lgkmcnt(0)
	v_add_f32_e32 v148, v148, v149
	ds_bpermute_b32 v150, v1, v192
	ds_bpermute_b32 v149, v177, v148
	v_bfe_u32 v155, v151, 16, 1
	v_fmac_f32_e32 v185, v151, v78
	v_fmac_f32_e32 v194, v151, v77
	s_waitcnt lgkmcnt(1)
	v_add_f32_e32 v150, v192, v150
	v_add3_u32 v155, v151, v155, s0
	v_fmac_f32_e32 v175, v151, v74
	v_fmac_f32_e32 v191, v151, v79
	v_fmac_f32_e32 v193, v151, v80
	v_fmac_f32_e32 v195, v151, v81
	v_fmac_f32_e32 v185, v152, v86
	v_fmac_f32_e32 v194, v152, v85
	s_waitcnt lgkmcnt(0)
	v_add_f32_e32 v148, v148, v149
	ds_bpermute_b32 v151, v171, v150
	v_fmac_f32_e32 v185, v153, v94
	v_fmac_f32_e32 v194, v153, v93
	ds_bpermute_b32 v149, v178, v148
	v_fmac_f32_e32 v185, v146, v102
	v_fmac_f32_e32 v194, v146, v101
	v_fmac_f32_e32 v185, v147, v110
	v_fmac_f32_e32 v194, v147, v109
	v_lshrrev_b32_e32 v154, 16, v154
	v_fmac_f32_e32 v185, v186, v118
	v_fmac_f32_e32 v194, v186, v117
	v_and_or_b32 v154, v155, s1, v154
	v_bfe_u32 v155, v152, 16, 1
	v_fmac_f32_e32 v185, v187, v126
	v_fmac_f32_e32 v194, v187, v125
	s_waitcnt lgkmcnt(1)
	v_add_f32_e32 v150, v150, v151
	v_add3_u32 v155, v152, v155, s0
	v_fmac_f32_e32 v175, v152, v82
	v_fmac_f32_e32 v191, v152, v87
	v_fmac_f32_e32 v193, v152, v88
	v_fmac_f32_e32 v195, v152, v89
	s_waitcnt lgkmcnt(0)
	v_add_f32_e32 v148, v148, v149
	ds_bpermute_b32 v149, v1, v194
	ds_bpermute_b32 v151, v177, v150
	ds_bpermute_b32 v152, v1, v185
	v_bfe_u32 v156, v153, 16, 1
	v_lshrrev_b32_e32 v155, 16, v155
	v_add3_u32 v156, v153, v156, s0
	v_and_or_b32 v155, v156, s1, v155
	s_waitcnt lgkmcnt(2)
	v_add_f32_e32 v149, v194, v149
	s_waitcnt lgkmcnt(1)
	v_add_f32_e32 v150, v150, v151
	s_waitcnt lgkmcnt(0)
	v_add_f32_e32 v151, v185, v152
	global_store_dwordx2 v[158:159], v[154:155], off offset:1024 sc1
	ds_bpermute_b32 v154, v171, v149
	ds_bpermute_b32 v152, v171, v151
	v_fmac_f32_e32 v175, v153, v90
	v_fmac_f32_e32 v191, v153, v95
	v_fmac_f32_e32 v193, v153, v96
	s_waitcnt lgkmcnt(1)
	v_add_f32_e32 v149, v149, v154
	s_waitcnt lgkmcnt(0)
	v_add_f32_e32 v151, v151, v152
	v_fmac_f32_e32 v195, v153, v97
	ds_bpermute_b32 v153, v179, v148
	ds_bpermute_b32 v155, v178, v150
	ds_bpermute_b32 v154, v177, v149
	ds_bpermute_b32 v152, v177, v151
	v_fmac_f32_e32 v175, v146, v98
	s_waitcnt lgkmcnt(3)
	v_add_f32_e32 v148, v148, v153
	s_waitcnt lgkmcnt(2)
	v_add_f32_e32 v150, v150, v155
	s_waitcnt lgkmcnt(1)
	v_add_f32_e32 v153, v149, v154
	s_waitcnt lgkmcnt(0)
	v_add_f32_e32 v151, v151, v152
	ds_bpermute_b32 v154, v178, v153
	ds_bpermute_b32 v155, v179, v150
	ds_bpermute_b32 v152, v178, v151
	v_fmac_f32_e32 v191, v146, v103
	v_fmac_f32_e32 v193, v146, v104
	s_waitcnt lgkmcnt(2)
	v_add_f32_e32 v153, v153, v154
	s_waitcnt lgkmcnt(1)
	v_add_f32_e32 v150, v150, v155
	s_waitcnt lgkmcnt(0)
	v_add_f32_e32 v155, v151, v152
	ds_bpermute_b32 v154, v179, v153
	ds_bpermute_b32 v156, v179, v155
	v_fmac_f32_e32 v195, v146, v105
	v_fmac_f32_e32 v175, v147, v106
	v_fmac_f32_e32 v191, v147, v111
	v_fmac_f32_e32 v193, v147, v112
	v_fmac_f32_e32 v195, v147, v113
	v_fmac_f32_e32 v175, v186, v114
	v_fmac_f32_e32 v191, v186, v119
	v_fmac_f32_e32 v193, v186, v120
	v_fmac_f32_e32 v195, v186, v121
	v_fmac_f32_e32 v175, v187, v122
	v_fmac_f32_e32 v191, v187, v127
	v_fmac_f32_e32 v193, v187, v128
	v_fmac_f32_e32 v195, v187, v129
	global_store_dwordx2 v[158:159], v[160:161], off offset:512 sc1
	ds_bpermute_b32 v146, v1, v175
	s_waitcnt lgkmcnt(2)
	v_add_f32_e32 v152, v153, v154
	ds_bpermute_b32 v157, v1, v191
	s_waitcnt lgkmcnt(2)
	v_add_f32_e32 v154, v155, v156
	ds_bpermute_b32 v156, v1, v193
	ds_bpermute_b32 v160, v1, v195
	s_waitcnt lgkmcnt(3)
	v_add_f32_e32 v146, v175, v146
	s_waitcnt lgkmcnt(2)
	v_add_f32_e32 v157, v191, v157
	ds_bpermute_b32 v147, v171, v146
	s_waitcnt lgkmcnt(2)
	v_add_f32_e32 v156, v193, v156
	s_waitcnt lgkmcnt(1)
	v_add_f32_e32 v160, v195, v160
	ds_bpermute_b32 v161, v171, v157
	ds_bpermute_b32 v175, v171, v156
	ds_bpermute_b32 v176, v171, v160
	s_waitcnt lgkmcnt(3)
	v_add_f32_e32 v146, v146, v147
	ds_bpermute_b32 v147, v177, v146
	s_waitcnt lgkmcnt(3)
	v_add_f32_e32 v157, v157, v161
	s_waitcnt lgkmcnt(2)
	v_add_f32_e32 v156, v156, v175
	s_waitcnt lgkmcnt(1)
	v_add_f32_e32 v160, v160, v176
	ds_bpermute_b32 v161, v177, v157
	ds_bpermute_b32 v175, v177, v156
	ds_bpermute_b32 v176, v177, v160
	s_waitcnt lgkmcnt(3)
	v_add_f32_e32 v146, v146, v147
	ds_bpermute_b32 v147, v178, v146
	s_waitcnt lgkmcnt(3)
	v_add_f32_e32 v157, v157, v161
	s_waitcnt lgkmcnt(2)
	v_add_f32_e32 v156, v156, v175
	s_waitcnt lgkmcnt(1)
	v_add_f32_e32 v160, v160, v176
	ds_bpermute_b32 v161, v178, v157
	ds_bpermute_b32 v175, v178, v156
	ds_bpermute_b32 v176, v178, v160
	s_waitcnt lgkmcnt(3)
	v_add_f32_e32 v146, v146, v147
	ds_bpermute_b32 v147, v179, v146
	s_waitcnt lgkmcnt(3)
	v_add_f32_e32 v157, v157, v161
	s_waitcnt lgkmcnt(2)
	v_add_f32_e32 v175, v156, v175
	s_waitcnt lgkmcnt(1)
	v_add_f32_e32 v176, v160, v176
	ds_bpermute_b32 v161, v179, v157
	ds_bpermute_b32 v185, v179, v175
	ds_bpermute_b32 v186, v179, v176
	s_waitcnt lgkmcnt(3)
	v_add_f32_e32 v146, v146, v147
	ds_bpermute_b32 v147, v180, v146
	s_waitcnt lgkmcnt(3)
	v_add_f32_e32 v156, v157, v161
	s_waitcnt lgkmcnt(2)
	v_add_f32_e32 v160, v175, v185
	s_waitcnt lgkmcnt(1)
	v_add_f32_e32 v175, v176, v186
	ds_bpermute_b32 v149, v180, v148
	ds_bpermute_b32 v151, v180, v150
	ds_bpermute_b32 v153, v180, v152
	ds_bpermute_b32 v155, v180, v154
	ds_bpermute_b32 v157, v180, v156
	ds_bpermute_b32 v161, v180, v160
	ds_bpermute_b32 v176, v180, v175
	v_bfe_u32 v185, v187, 16, 1
	v_add3_u32 v185, v187, v185, s0
	v_and_or_b32 v189, v185, s1, v189
	global_store_dwordx2 v[158:159], v[188:189], off offset:1536 sc1
	s_and_saveexec_b64 s[38:39], s[6:7]
	s_cbranch_execz .LBB0_307
	s_load_dwordx2 s[40:41], s[92:93], 0x28
	s_waitcnt lgkmcnt(0)
	v_add_f32_e32 v146, v146, v147
	v_add_f32_e32 v148, v148, v149
	v_cndmask_b32_e64 v146, 0, v146, s[22:23]
	v_add_f32_e32 v150, v150, v151
	global_load_dword v158, v182, s[40:41]
	v_cndmask_b32_e64 v146, v146, v148, s[20:21]
	v_add_f32_e32 v152, v152, v153
	v_cndmask_b32_e64 v146, v146, v150, s[18:19]
	v_add_f32_e32 v154, v154, v155
	v_cndmask_b32_e64 v146, v146, v152, s[16:17]
	v_add_f32_e32 v156, v156, v157
	v_cndmask_b32_e64 v146, v146, v154, s[14:15]
	v_add_f32_e32 v160, v160, v161
	v_cndmask_b32_e64 v146, v146, v156, s[12:13]
	v_add_f32_e32 v159, v175, v176
	v_cndmask_b32_e64 v146, v146, v160, s[10:11]
	v_cndmask_b32_e64 v146, v146, v159, s[8:9]
	s_waitcnt vmcnt(0)
	v_add_f32_e32 v146, v146, v158
	v_cmp_nlt_f32_e32 vcc, s42, v146
	s_and_saveexec_b64 s[40:41], vcc
	s_cbranch_execz .LBB0_306
	v_mul_f32_e32 v147, 0x3fb8aa3b, v146
	v_rndne_f32_e32 v148, v147
	v_sub_f32_e32 v149, v147, v148
	v_fma_f32 v147, v146, s43, -v147
	v_fmac_f32_e32 v147, 0x32a5705f, v146
	v_add_f32_e32 v147, v149, v147
	v_cvt_i32_f32_e32 v148, v148
	v_exp_f32_e32 v147, v147
	v_cmp_ngt_f32_e32 vcc, s44, v146
	v_ldexp_f32 v147, v147, v148
	s_nop 0
	v_cndmask_b32_e32 v147, 0, v147, vcc
	v_cmp_nlt_f32_e32 vcc, s45, v146
	s_nop 1
	v_cndmask_b32_e32 v160, v184, v147, vcc
	v_add_f32_e32 v148, 1.0, v160
	v_add_f32_e32 v146, -1.0, v148
	v_sub_f32_e32 v147, v146, v148
	v_add_f32_e32 v147, 1.0, v147
	v_sub_f32_e32 v146, v160, v146
	v_add_f32_e32 v149, v146, v147
	v_frexp_mant_f32_e32 v150, v148
	v_cvt_f64_f32_e32 v[146:147], v148
	v_frexp_exp_i32_f64_e32 v146, v[146:147]
	v_cmp_gt_f32_e32 vcc, s47, v150
	s_nop 1
	v_subbrev_co_u32_e32 v154, vcc, 0, v146, vcc
	v_sub_u32_e32 v146, 0, v154
	v_ldexp_f32 v147, v148, v146
	v_add_f32_e32 v148, -1.0, v147
	v_add_f32_e32 v150, 1.0, v147
	v_ldexp_f32 v146, v149, v146
	v_add_f32_e32 v149, 1.0, v148
	v_add_f32_e32 v151, -1.0, v150
	v_sub_f32_e32 v149, v147, v149
	v_sub_f32_e32 v147, v147, v151
	v_add_f32_e32 v149, v146, v149
	v_add_f32_e32 v146, v146, v147
	v_add_f32_e32 v155, v150, v146
	v_rcp_f32_e32 v157, v155
	v_sub_f32_e32 v147, v150, v155
	v_add_f32_e32 v156, v146, v147
	v_add_f32_e32 v147, v148, v149
	v_mul_f32_e32 v159, v147, v157
	v_sub_f32_e32 v146, v148, v147
	v_mul_f32_e32 v148, v155, v159
	v_fma_f32 v150, v159, v155, -v148
	v_fmac_f32_e32 v150, v159, v156
	v_add_f32_e32 v158, v149, v146
	v_add_f32_e32 v146, v148, v150
	v_sub_f32_e32 v149, v147, v146
	v_pk_add_f32 v[152:153], v[146:147], v[148:149] neg_lo:[0,1] neg_hi:[0,1]
	v_mov_b32_e32 v151, v146
	v_pk_add_f32 v[146:147], v[152:153], v[150:151] neg_lo:[0,1] neg_hi:[0,1]
	v_cmp_neq_f32_e32 vcc, s46, v160
	v_add_f32_e32 v147, v158, v147
	v_add_f32_e32 v146, v146, v147
	v_add_f32_e32 v147, v149, v146
	v_mul_f32_e32 v158, v157, v147
	v_mul_f32_e32 v148, v155, v158
	v_fma_f32 v150, v158, v155, -v148
	v_fmac_f32_e32 v150, v158, v156
	v_sub_f32_e32 v149, v149, v147
	v_add_f32_e32 v155, v146, v149
	v_add_f32_e32 v146, v148, v150
	v_sub_f32_e32 v149, v147, v146
	v_pk_add_f32 v[152:153], v[146:147], v[148:149] neg_lo:[0,1] neg_hi:[0,1]
	v_mov_b32_e32 v151, v146
	v_pk_add_f32 v[146:147], v[152:153], v[150:151] neg_lo:[0,1] neg_hi:[0,1]
	s_nop 0
	v_add_f32_e32 v147, v155, v147
	v_add_f32_e32 v146, v146, v147
	v_add_f32_e32 v147, v159, v158
	v_add_f32_e32 v146, v149, v146
	v_sub_f32_e32 v148, v147, v159
	v_mul_f32_e32 v146, v157, v146
	v_sub_f32_e32 v148, v158, v148
	v_add_f32_e32 v148, v148, v146
	v_add_f32_e32 v150, v147, v148
	v_mul_f32_e32 v151, v150, v150
	v_fmamk_f32 v146, v151, 0x3e9b6dac, v183
	v_fmaak_f32 v175, v151, v146, 0x3f2aaada
	v_cvt_f32_i32_e32 v146, v154
	v_sub_f32_e32 v147, v150, v147
	v_sub_f32_e32 v147, v148, v147
	v_ldexp_f32 v152, v147, 1
	v_mul_f32_e32 v147, v150, v151
	v_ldexp_f32 v149, v150, 1
	v_pk_mul_f32 v[150:151], v[146:147], v[174:175]
	s_nop 0
	v_fma_f32 v148, v146, s48, -v150
	v_fmac_f32_e32 v148, 0xb102e308, v146
	v_pk_add_f32 v[146:147], v[150:151], v[148:149]
	s_nop 0
	v_sub_f32_e32 v149, v147, v149
	v_sub_f32_e32 v149, v151, v149
	v_add_f32_e32 v153, v152, v149
	v_mov_b32_e32 v152, v150
	v_pk_add_f32 v[150:151], v[146:147], v[150:151] neg_lo:[0,1] neg_hi:[0,1]
	v_pk_add_f32 v[154:155], v[146:147], v[152:153]
	v_mov_b32_e32 v149, v146
	v_mov_b32_e32 v151, v155
	v_pk_add_f32 v[156:157], v[148:149], v[150:151] neg_lo:[0,1] neg_hi:[0,1]
	v_pk_add_f32 v[148:149], v[148:149], v[150:151]
	v_mov_b32_e32 v152, v153
	v_pk_add_f32 v[150:151], v[148:149], v[146:147] op_sel:[1,0] op_sel_hi:[0,1] neg_lo:[0,1] neg_hi:[0,1]
	v_pk_add_f32 v[158:159], v[154:155], v[150:151] op_sel_hi:[1,0] neg_lo:[0,1] neg_hi:[0,1]
	v_mov_b32_e32 v154, v155
	v_mov_b32_e32 v155, v149
	v_pk_mov_b32 v[150:151], v[146:147], v[150:151] op_sel:[1,0]
	v_mov_b32_e32 v153, v146
	v_pk_add_f32 v[150:151], v[154:155], v[150:151] neg_lo:[0,1] neg_hi:[0,1]
	v_mov_b32_e32 v158, v156
	v_pk_add_f32 v[146:147], v[152:153], v[150:151] neg_lo:[0,1] neg_hi:[0,1]
	v_mov_b32_e32 v157, v149
	v_pk_add_f32 v[150:151], v[158:159], v[146:147]
	s_nop 0
	v_pk_add_f32 v[152:153], v[150:151], v[150:151] op_sel:[0,1] op_sel_hi:[1,0]
	s_nop 0
	v_pk_add_f32 v[148:149], v[148:149], v[152:153] op_sel:[1,0] op_sel_hi:[0,1]
	v_mov_b32_e32 v151, v148
	v_pk_add_f32 v[154:155], v[150:151], v[156:157] neg_lo:[0,1] neg_hi:[0,1]
	v_mov_b32_e32 v147, v152
	v_sub_f32_e32 v149, v150, v154
	v_pk_add_f32 v[146:147], v[146:147], v[154:155] neg_lo:[0,1] neg_hi:[0,1]
	v_sub_f32_e32 v149, v156, v149
	v_add_f32_e32 v146, v146, v149
	v_add_f32_e32 v146, v146, v147
	v_add_f32_e32 v146, v148, v146
	v_cndmask_b32_e32 v146, v184, v146, vcc
	v_cmp_lt_f32_e64 vcc, |v160|, s49
	s_nop 1
	v_cndmask_b32_e32 v146, v146, v160, vcc
	s_branch .LBB0_306

.LBB0_2576:
	global_load_dwordx4 v[140:143], v[152:153], off
	global_load_dwordx4 v[136:139], v[152:153], off offset:16
	global_load_dwordx4 v[132:135], v[152:153], off offset:512
	global_load_dwordx4 v[128:131], v[152:153], off offset:528
	v_lshl_add_u32 v166, s30, 8, v160
	v_ashrrev_i32_e32 v167, 31, v166
	v_or_b32_e32 v172, 16, v166
	v_or_b32_e32 v174, 32, v166
	v_or_b32_e32 v176, 48, v166
	v_lshlrev_b64 v[166:167], 11, v[166:167]
	v_ashrrev_i32_e32 v173, 31, v172
	v_ashrrev_i32_e32 v175, 31, v174
	v_ashrrev_i32_e32 v177, 31, v176
	v_lshl_add_u64 v[166:167], v[154:155], 0, v[166:167]
	v_lshlrev_b64 v[172:173], 11, v[172:173]
	v_lshlrev_b64 v[174:175], 11, v[174:175]
	v_lshlrev_b64 v[176:177], 11, v[176:177]
	v_lshl_add_u64 v[172:173], v[154:155], 0, v[172:173]
	v_lshl_add_u64 v[174:175], v[154:155], 0, v[174:175]
	v_lshl_add_u64 v[176:177], v[154:155], 0, v[176:177]
	s_andn2_b64 vcc, exec, s[6:7]
	s_mov_b64 s[0:1], -1
	s_waitcnt vmcnt(0)
	v_pk_add_f32 v[126:127], v[126:127], v[142:143]
	v_pk_add_f32 v[124:125], v[124:125], v[140:141]
	v_pk_add_f32 v[122:123], v[122:123], v[138:139]
	v_pk_add_f32 v[120:121], v[120:121], v[136:137]
	v_pk_add_f32 v[106:107], v[106:107], v[134:135]
	v_pk_add_f32 v[104:105], v[104:105], v[132:133]
	v_pk_add_f32 v[98:99], v[98:99], v[130:131]
	v_pk_add_f32 v[96:97], v[96:97], v[128:129]
	v_pk_add_f32 v[118:119], v[118:119], v[142:143]
	v_pk_add_f32 v[116:117], v[116:117], v[140:141]
	v_pk_add_f32 v[114:115], v[114:115], v[138:139]
	v_pk_add_f32 v[112:113], v[112:113], v[136:137]
	v_pk_add_f32 v[90:91], v[90:91], v[134:135]
	v_pk_add_f32 v[88:89], v[88:89], v[132:133]
	v_pk_add_f32 v[178:179], v[82:83], v[130:131]
	v_pk_add_f32 v[180:181], v[80:81], v[128:129]
	v_pk_add_f32 v[110:111], v[110:111], v[142:143]
	v_pk_add_f32 v[108:109], v[108:109], v[140:141]
	v_pk_add_f32 v[102:103], v[102:103], v[138:139]
	v_pk_add_f32 v[100:101], v[100:101], v[136:137]
	v_pk_add_f32 v[182:183], v[78:79], v[134:135]
	v_pk_add_f32 v[184:185], v[76:77], v[132:133]
	v_pk_add_f32 v[186:187], v[74:75], v[130:131]
	v_pk_add_f32 v[188:189], v[72:73], v[128:129]
	v_pk_add_f32 v[190:191], v[94:95], v[142:143]
	v_pk_add_f32 v[192:193], v[92:93], v[140:141]
	v_pk_add_f32 v[194:195], v[86:87], v[138:139]
	v_pk_add_f32 v[196:197], v[84:85], v[136:137]
	v_cvt_pk_bf16_f32 v72, v124, v125
	v_cvt_pk_bf16_f32 v73, v126, v127
	v_cvt_pk_bf16_f32 v74, v120, v121
	v_cvt_pk_bf16_f32 v75, v122, v123
	v_cvt_pk_bf16_f32 v76, v104, v105
	v_cvt_pk_bf16_f32 v77, v106, v107
	v_cvt_pk_bf16_f32 v78, v96, v97
	v_cvt_pk_bf16_f32 v79, v98, v99
	v_cvt_pk_bf16_f32 v80, v116, v117
	v_cvt_pk_bf16_f32 v81, v118, v119
	v_cvt_pk_bf16_f32 v82, v112, v113
	v_cvt_pk_bf16_f32 v83, v114, v115
	v_cvt_pk_bf16_f32 v84, v88, v89
	v_cvt_pk_bf16_f32 v85, v90, v91
	v_cvt_pk_bf16_f32 v86, v180, v181
	v_cvt_pk_bf16_f32 v87, v178, v179
	v_cvt_pk_bf16_f32 v88, v108, v109
	v_cvt_pk_bf16_f32 v89, v110, v111
	v_cvt_pk_bf16_f32 v90, v100, v101
	v_cvt_pk_bf16_f32 v91, v102, v103
	v_cvt_pk_bf16_f32 v92, v184, v185
	v_cvt_pk_bf16_f32 v93, v182, v183
	v_cvt_pk_bf16_f32 v94, v188, v189
	v_cvt_pk_bf16_f32 v95, v186, v187
	v_cvt_pk_bf16_f32 v96, v192, v193
	v_cvt_pk_bf16_f32 v97, v190, v191
	v_cvt_pk_bf16_f32 v98, v196, v197
	v_cvt_pk_bf16_f32 v99, v194, v195
	global_store_dwordx4 v[166:167], v[72:75], off offset:1536 sc1
	global_store_dwordx4 v[166:167], v[76:79], off offset:1792 sc1
	global_store_dwordx4 v[172:173], v[80:83], off offset:1536 sc1
	global_store_dwordx4 v[172:173], v[84:87], off offset:1792 sc1
	global_store_dwordx4 v[174:175], v[88:91], off offset:1536 sc1
	global_store_dwordx4 v[174:175], v[92:95], off offset:1792 sc1
	global_store_dwordx4 v[176:177], v[96:99], off offset:1536 sc1
	v_pk_add_f32 v[70:71], v[70:71], v[134:135]
	v_pk_add_f32 v[68:69], v[68:69], v[132:133]
	v_pk_add_f32 v[72:73], v[66:67], v[130:131]
	v_pk_add_f32 v[66:67], v[64:65], v[128:129]
	v_cvt_pk_bf16_f32 v64, v68, v69
	v_cvt_pk_bf16_f32 v65, v70, v71
	v_cvt_pk_bf16_f32 v66, v66, v67
	v_cvt_pk_bf16_f32 v67, v72, v73
	global_store_dwordx4 v[176:177], v[64:67], off offset:1792 sc1
	v_pk_add_f32 v[62:63], v[62:63], v[142:143]
	v_pk_add_f32 v[60:61], v[60:61], v[140:141]
	v_pk_add_f32 v[66:67], v[58:59], v[138:139]
	v_pk_add_f32 v[58:59], v[56:57], v[136:137]
	v_lshl_add_u64 v[64:65], v[166:167], 0, s[20:21]
	v_cvt_pk_bf16_f32 v56, v60, v61
	v_cvt_pk_bf16_f32 v57, v62, v63
	v_cvt_pk_bf16_f32 v58, v58, v59
	v_cvt_pk_bf16_f32 v59, v66, v67
	global_store_dwordx4 v[64:65], v[56:59], off offset:1536 sc1
	v_pk_add_f32 v[50:51], v[50:51], v[134:135]
	v_pk_add_f32 v[48:49], v[48:49], v[132:133]
	v_pk_add_f32 v[56:57], v[42:43], v[130:131]
	v_pk_add_f32 v[42:43], v[40:41], v[128:129]
	v_cvt_pk_bf16_f32 v40, v48, v49
	v_cvt_pk_bf16_f32 v41, v50, v51
	v_cvt_pk_bf16_f32 v42, v42, v43
	v_cvt_pk_bf16_f32 v43, v56, v57
	global_store_dwordx4 v[64:65], v[40:43], off offset:1792 sc1
	v_pk_add_f32 v[46:47], v[46:47], v[138:139]
	v_pk_add_f32 v[44:45], v[44:45], v[136:137]
	v_pk_add_f32 v[42:43], v[54:55], v[142:143]
	v_pk_add_f32 v[40:41], v[52:53], v[140:141]
	v_lshl_add_u64 v[48:49], v[166:167], 0, s[22:23]
	v_cvt_pk_bf16_f32 v40, v40, v41
	v_cvt_pk_bf16_f32 v41, v42, v43
	v_cvt_pk_bf16_f32 v42, v44, v45
	v_cvt_pk_bf16_f32 v43, v46, v47
	global_store_dwordx4 v[48:49], v[40:43], off offset:1536 sc1
	v_pk_add_f32 v[34:35], v[34:35], v[134:135]
	v_pk_add_f32 v[32:33], v[32:33], v[132:133]
	v_pk_add_f32 v[40:41], v[26:27], v[130:131]
	v_pk_add_f32 v[26:27], v[24:25], v[128:129]
	v_cvt_pk_bf16_f32 v24, v32, v33
	v_cvt_pk_bf16_f32 v25, v34, v35
	v_cvt_pk_bf16_f32 v26, v26, v27
	v_cvt_pk_bf16_f32 v27, v40, v41
	global_store_dwordx4 v[48:49], v[24:27], off offset:1792 sc1
	v_pk_add_f32 v[30:31], v[30:31], v[138:139]
	v_pk_add_f32 v[28:29], v[28:29], v[136:137]
	v_pk_add_f32 v[26:27], v[38:39], v[142:143]
	v_pk_add_f32 v[24:25], v[36:37], v[140:141]
	v_lshl_add_u64 v[32:33], v[166:167], 0, s[24:25]
	v_cvt_pk_bf16_f32 v24, v24, v25
	v_cvt_pk_bf16_f32 v25, v26, v27
	v_cvt_pk_bf16_f32 v26, v28, v29
	v_cvt_pk_bf16_f32 v27, v30, v31
	global_store_dwordx4 v[32:33], v[24:27], off offset:1536 sc1
	v_pk_add_f32 v[18:19], v[18:19], v[134:135]
	v_pk_add_f32 v[16:17], v[16:17], v[132:133]
	v_pk_add_f32 v[24:25], v[10:11], v[130:131]
	v_pk_add_f32 v[10:11], v[8:9], v[128:129]
	v_cvt_pk_bf16_f32 v8, v16, v17
	v_cvt_pk_bf16_f32 v9, v18, v19
	v_cvt_pk_bf16_f32 v10, v10, v11
	v_cvt_pk_bf16_f32 v11, v24, v25
	global_store_dwordx4 v[32:33], v[8:11], off offset:1792 sc1
	v_pk_add_f32 v[14:15], v[14:15], v[138:139]
	v_pk_add_f32 v[12:13], v[12:13], v[136:137]
	v_pk_add_f32 v[10:11], v[22:23], v[142:143]
	v_pk_add_f32 v[8:9], v[20:21], v[140:141]
	v_lshl_add_u64 v[16:17], v[166:167], 0, s[26:27]
	v_cvt_pk_bf16_f32 v8, v8, v9
	v_cvt_pk_bf16_f32 v9, v10, v11
	v_cvt_pk_bf16_f32 v10, v12, v13
	v_cvt_pk_bf16_f32 v11, v14, v15
	global_store_dwordx4 v[16:17], v[8:11], off offset:1536 sc1
	v_pk_add_f32 v[6:7], v[6:7], v[134:135]
	v_pk_add_f32 v[4:5], v[4:5], v[132:133]
	v_pk_add_f32 v[8:9], v[2:3], v[130:131]
	v_pk_add_f32 v[2:3], v[0:1], v[128:129]
	v_cvt_pk_bf16_f32 v0, v4, v5
	v_cvt_pk_bf16_f32 v1, v6, v7
	v_cvt_pk_bf16_f32 v2, v2, v3
	v_cvt_pk_bf16_f32 v3, v8, v9
	global_store_dwordx4 v[16:17], v[0:3], off offset:1792 sc1
	s_cbranch_vccnz .LBB0_2565
	s_andn2_b64 vcc, exec, s[12:13]
	s_cbranch_vccnz .LBB0_2564
	s_barrier
	s_branch .LBB0_2564

.LBB0_2588:
	global_load_dwordx4 v[12:15], v[6:7], off
	global_load_dwordx4 v[16:19], v[8:9], off
	v_add_u32_e32 v11, 0x200, v11
	v_cmp_lt_u32_e32 vcc, s17, v11
	s_or_b64 s[12:13], vcc, s[12:13]
	v_lshl_add_u64 v[8:9], v[8:9], 0, s[10:11]
	s_waitcnt vmcnt(1)
	v_lshlrev_b32_e32 v20, 16, v12
	v_and_b32_e32 v21, 0xffff0000, v12
	v_lshlrev_b32_e32 v22, 16, v13
	v_lshlrev_b32_e32 v24, 16, v14
	v_and_b32_e32 v25, 0xffff0000, v14
	v_lshlrev_b32_e32 v26, 16, v15
	v_and_b32_e32 v23, 0xffff0000, v13
	v_and_b32_e32 v27, 0xffff0000, v15
	v_mul_f32_e32 v20, 0xbfb8aa3b, v20
	v_mul_f32_e32 v21, 0xbfb8aa3b, v21
	v_mul_f32_e32 v22, 0xbfb8aa3b, v22
	v_mul_f32_e32 v24, 0xbfb8aa3b, v24
	v_mul_f32_e32 v25, 0xbfb8aa3b, v25
	v_mul_f32_e32 v26, 0xbfb8aa3b, v26
	v_mul_f32_e32 v23, 0xbfb8aa3b, v23
	v_mul_f32_e32 v27, 0xbfb8aa3b, v27
	v_exp_f32_e32 v20, v20
	v_exp_f32_e32 v21, v21
	v_exp_f32_e32 v22, v22
	v_exp_f32_e32 v24, v24
	v_exp_f32_e32 v25, v25
	v_exp_f32_e32 v26, v26
	v_exp_f32_e32 v23, v23
	v_exp_f32_e32 v27, v27
	v_add_f32_e32 v20, 1.0, v20
	v_add_f32_e32 v21, 1.0, v21
	v_add_f32_e32 v28, 1.0, v22
	v_add_f32_e32 v24, 1.0, v24
	v_add_f32_e32 v25, 1.0, v25
	v_add_f32_e32 v29, 1.0, v26
	v_add_f32_e32 v23, 1.0, v23
	v_add_f32_e32 v27, 1.0, v27
	v_rcp_f32_e32 v20, v20
	v_rcp_f32_e32 v22, v21
	v_rcp_f32_e32 v21, v28
	v_rcp_f32_e32 v24, v24
	v_rcp_f32_e32 v26, v25
	v_rcp_f32_e32 v25, v29
	v_rcp_f32_e32 v23, v23
	v_rcp_f32_e32 v27, v27
	s_waitcnt vmcnt(0)
	v_lshlrev_b32_e32 v13, 16, v17
	v_lshlrev_b32_e32 v12, 16, v16
	v_lshlrev_b32_e32 v15, 16, v19
	v_lshlrev_b32_e32 v14, 16, v18
	v_and_b32_e32 v17, 0xffff0000, v17
	v_and_b32_e32 v16, 0xffff0000, v16
	v_and_b32_e32 v19, 0xffff0000, v19
	v_and_b32_e32 v18, 0xffff0000, v18
	v_pk_mul_f32 v[12:13], v[20:21], v[12:13]
	v_pk_mul_f32 v[14:15], v[24:25], v[14:15]
	v_pk_mul_f32 v[16:17], v[22:23], v[16:17]
	v_pk_mul_f32 v[18:19], v[26:27], v[18:19]
	v_bfe_u32 v24, v12, 16, 1
	v_bfe_u32 v25, v13, 16, 1
	v_bfe_u32 v26, v14, 16, 1
	v_bfe_u32 v27, v15, 16, 1
	v_bfe_u32 v20, v19, 16, 1
	v_bfe_u32 v21, v18, 16, 1
	v_bfe_u32 v22, v17, 16, 1
	v_bfe_u32 v23, v16, 16, 1
	v_add3_u32 v15, v15, v27, s16
	v_add3_u32 v14, v14, v26, s16
	v_add3_u32 v13, v13, v25, s16
	v_add3_u32 v12, v12, v24, s16
	v_add3_u32 v16, v16, v23, s16
	v_add3_u32 v17, v17, v22, s16
	v_add3_u32 v18, v18, v21, s16
	v_add3_u32 v19, v19, v20, s16
	v_lshrrev_b32_e32 v12, 16, v12
	v_lshrrev_b32_e32 v13, 16, v13
	v_lshrrev_b32_e32 v14, 16, v14
	v_lshrrev_b32_e32 v15, 16, v15
	v_and_or_b32 v15, v19, s15, v15
	v_and_or_b32 v14, v18, s15, v14
	v_and_or_b32 v13, v17, s15, v13
	v_and_or_b32 v12, v16, s15, v12
	global_store_dwordx4 v[6:7], v[12:15], off sc1
	v_lshl_add_u64 v[6:7], v[6:7], 0, s[6:7]
	s_andn2_b64 exec, exec, s[12:13]
	s_cbranch_execnz .LBB0_2588
	s_or_b64 exec, exec, s[12:13]
	s_add_i32 s14, s14, 1
	s_mov_b64 s[12:13], 0
	s_branch .LBB0_2581

.LBB0_2592:
	s_ashr_i64 s[10:11], s[4:5], 3
	s_bfe_u32 s14, s4, 0x20001
	s_mul_i32 s16, s11, 0xaaaaaaab
	s_mul_hi_u32 s17, s10, 0xaaaaaaab
	s_mul_hi_u32 s15, s11, 0xaaaaaaab
	s_add_u32 s16, s16, s17
	s_mul_i32 s13, s10, 0x2aaaaaaa
	s_addc_u32 s15, s15, 0
	s_mul_hi_u32 s12, s10, 0x2aaaaaaa
	s_add_u32 s13, s13, s16
	s_addc_u32 s12, s12, 0
	s_add_u32 s12, s15, s12
	s_mul_hi_u32 s18, s11, 0x2aaaaaaa
	s_mul_i32 s11, s11, 0x2aaaaaaa
	s_addc_u32 s13, 0, 0
	s_add_u32 s11, s11, s12
	s_addc_u32 s12, s18, s13
	s_ashr_i32 s13, s5, 31
	s_mul_i32 s15, s13, 0x2aaaaaaa
	s_mul_hi_u32 s16, s13, 0xaaaaaaab
	s_mul_i32 s13, s13, 0xaaaaaaab
	s_add_i32 s15, s16, s15
	s_add_i32 s15, s15, s13
	s_add_u32 s11, s11, s13
	s_addc_u32 s13, s12, s15
	s_lshr_b32 s12, s13, 31
	s_add_u32 s12, s11, s12
	v_lshl_or_b32 v0, s14, 4, v36
	s_addc_u32 s13, s13, 0
	s_mul_i32 s11, s12, 6
	s_lshl_b32 s14, s14, 2
	v_lshrrev_b32_e32 v0, 3, v0
	s_sub_i32 s10, s10, s11
	s_lshl_b64 s[24:25], s[12:13], 6
	s_or_b32 s11, s14, s1
	v_or_b32_e32 v0, s24, v0
	s_lshl_b32 s20, s10, 7
	s_or_b32 s24, s24, s11
	s_mul_i32 s31, s25, 0x1a00
	s_ashr_i32 s21, s20, 31
	s_mul_hi_u32 s10, s24, 0x1a00
	v_mad_u64_u32 v[0:1], s[34:35], v0, s3, v[14:15]
	s_mul_i32 s12, s24, 0x1a00
	s_lshl_b64 s[20:21], s[20:21], 1
	s_add_i32 s10, s10, s31
	v_add_u32_e32 v1, s31, v1
	s_add_u32 s12, s6, s12
	v_lshl_add_u64 v[0:1], v[0:1], 0, s[20:21]
	s_addc_u32 s10, s7, s10
	v_lshl_add_u64 v[0:1], v[0:1], 0, v[10:11]
	s_add_u32 s34, s12, s20
	v_lshl_add_u64 v[22:23], v[0:1], 0, s[8:9]
	s_addc_u32 s35, s10, s21
	s_or_b32 s26, s24, 1
	global_load_dwordx4 v[0:3], v[22:23], off
	global_load_dwordx4 v[4:7], v[22:23], off offset:32
	v_lshl_add_u64 v[22:23], s[34:35], 0, v[16:17]
	s_mul_hi_u32 s10, s26, 0x1a00
	s_mul_i32 s12, s26, 0x1a00
	v_add_co_u32_e32 v22, vcc, s28, v22
	s_add_i32 s10, s10, s31
	s_nop 0
	v_addc_co_u32_e32 v23, vcc, 0, v23, vcc
	s_add_u32 s12, s6, s12
	global_load_dword v52, v[22:23], off offset:512
	s_addc_u32 s10, s7, s10
	s_add_u32 s34, s12, s20
	s_addc_u32 s35, s10, s21
	s_or_b32 s22, s24, 2
	s_mul_hi_u32 s10, s22, 0x1a00
	v_lshl_add_u64 v[22:23], s[34:35], 0, v[16:17]
	s_mul_i32 s12, s22, 0x1a00
	s_add_i32 s10, s10, s31
	v_add_co_u32_e32 v22, vcc, s28, v22
	s_add_u32 s12, s6, s12
	s_nop 0
	v_addc_co_u32_e32 v23, vcc, 0, v23, vcc
	s_addc_u32 s10, s7, s10
	global_load_dword v49, v[22:23], off offset:512
	s_add_u32 s34, s12, s20
	s_addc_u32 s35, s10, s21
	s_or_b32 s18, s24, 3
	s_mul_hi_u32 s10, s18, 0x1a00
	v_lshl_add_u64 v[22:23], s[34:35], 0, v[16:17]
	s_mul_i32 s12, s18, 0x1a00
	s_add_i32 s10, s10, s31
	v_add_co_u32_e32 v22, vcc, s28, v22
	s_add_u32 s12, s6, s12
	s_nop 0
	v_addc_co_u32_e32 v23, vcc, 0, v23, vcc
	s_addc_u32 s10, s7, s10
	global_load_dword v48, v[22:23], off offset:512
	s_add_u32 s34, s12, s20
	s_addc_u32 s35, s10, s21
	s_or_b32 s16, s24, 16
	s_mul_hi_u32 s10, s16, 0x1a00
	s_mul_i32 s12, s16, 0x1a00
	s_add_i32 s10, s10, s31
	v_lshl_add_u64 v[22:23], s[34:35], 0, v[16:17]
	s_add_u32 s12, s6, s12
	v_add_co_u32_e32 v22, vcc, s28, v22
	s_addc_u32 s10, s7, s10
	s_nop 0
	v_addc_co_u32_e32 v23, vcc, 0, v23, vcc
	s_add_u32 s34, s12, s20
	global_load_dword v47, v[22:23], off offset:512
	s_addc_u32 s35, s10, s21
	s_or_b32 s14, s24, 17
	s_mul_hi_u32 s10, s14, 0x1a00
	s_mul_i32 s12, s14, 0x1a00
	s_add_i32 s10, s10, s31
	v_lshl_add_u64 v[22:23], s[34:35], 0, v[16:17]
	s_add_u32 s12, s6, s12
	v_add_co_u32_e32 v22, vcc, s28, v22
	s_addc_u32 s10, s7, s10
	s_nop 0
	v_addc_co_u32_e32 v23, vcc, 0, v23, vcc
	s_add_u32 s34, s12, s20
	global_load_dword v46, v[22:23], off offset:512
	s_addc_u32 s35, s10, s21
	s_or_b32 s12, s24, 18
	s_mul_hi_u32 s10, s12, 0x1a00
	v_lshl_add_u64 v[22:23], s[34:35], 0, v[16:17]
	s_mul_i32 s33, s12, 0x1a00
	s_add_i32 s10, s10, s31
	v_add_co_u32_e32 v22, vcc, s28, v22
	s_add_u32 s33, s6, s33
	s_nop 0
	v_addc_co_u32_e32 v23, vcc, 0, v23, vcc
	s_addc_u32 s10, s7, s10
	global_load_dword v45, v[22:23], off offset:512
	s_add_u32 s34, s33, s20
	s_addc_u32 s35, s10, s21
	s_or_b32 s10, s24, 19
	v_lshl_add_u64 v[22:23], s[34:35], 0, v[16:17]
	s_mul_hi_u32 s33, s10, 0x1a00
	s_mul_i32 s34, s10, 0x1a00
	v_add_co_u32_e32 v22, vcc, s28, v22
	s_add_i32 s33, s33, s31
	s_nop 0
	v_addc_co_u32_e32 v23, vcc, 0, v23, vcc
	s_add_u32 s31, s6, s34
	global_load_dword v44, v[22:23], off offset:512
	s_addc_u32 s33, s7, s33
	v_lshl_add_u64 v[20:21], v[12:13], 0, s[20:21]
	s_add_u32 s20, s31, s20
	s_addc_u32 s21, s33, s21
	v_lshl_add_u64 v[50:51], s[20:21], 0, v[16:17]
	v_add_co_u32_e32 v50, vcc, s28, v50
	s_waitcnt vmcnt(7)
	v_lshlrev_b32_e32 v53, 16, v4
	v_addc_co_u32_e32 v51, vcc, 0, v51, vcc
	global_load_dword v50, v[50:51], off offset:512
	v_and_b32_e32 v4, 0xffff0000, v4
	v_lshlrev_b32_e32 v55, 16, v5
	v_lshlrev_b32_e32 v57, 16, v6
	v_and_b32_e32 v6, 0xffff0000, v6
	v_lshlrev_b32_e32 v51, 16, v0
	v_and_b32_e32 v0, 0xffff0000, v0
	v_lshlrev_b32_e32 v54, 16, v1
	v_and_b32_e32 v5, 0xffff0000, v5
	v_lshlrev_b32_e32 v56, 16, v2
	v_and_b32_e32 v2, 0xffff0000, v2
	v_lshlrev_b32_e32 v59, 16, v7
	v_mul_f32_e32 v60, v53, v53
	v_mul_f32_e32 v61, v4, v4
	v_mul_f32_e32 v62, v55, v55
	v_mul_f32_e32 v65, v6, v6
	v_and_b32_e32 v1, 0xffff0000, v1
	v_lshlrev_b32_e32 v58, 16, v3
	v_and_b32_e32 v7, 0xffff0000, v7
	v_mul_f32_e32 v63, v5, v5
	v_mul_f32_e32 v64, v57, v57
	v_mul_f32_e32 v66, v59, v59
	v_fmac_f32_e32 v60, v51, v51
	v_fmac_f32_e32 v61, v0, v0
	v_fmac_f32_e32 v62, v54, v54
	v_fmac_f32_e32 v65, v2, v2
	v_and_b32_e32 v3, 0xffff0000, v3
	v_mul_f32_e32 v67, v7, v7
	v_fmac_f32_e32 v63, v1, v1
	v_fmac_f32_e32 v64, v56, v56
	v_fmac_f32_e32 v66, v58, v58
	ds_bpermute_b32 v68, v37, v60
	s_waitcnt vmcnt(7)
	v_lshlrev_b32_e32 v69, 16, v52
	ds_bpermute_b32 v70, v37, v61
	ds_bpermute_b32 v71, v37, v62
	ds_bpermute_b32 v74, v37, v65
	v_fmac_f32_e32 v67, v3, v3
	v_and_b32_e32 v52, 0xffff0000, v52
	ds_bpermute_b32 v72, v37, v63
	ds_bpermute_b32 v73, v37, v64
	ds_bpermute_b32 v75, v37, v66
	v_mul_f32_e32 v77, 0xbfb8aa3b, v69
	ds_bpermute_b32 v76, v37, v67
	v_mul_f32_e32 v78, 0xbfb8aa3b, v52
	v_exp_f32_e32 v77, v77
	v_exp_f32_e32 v78, v78
	s_waitcnt lgkmcnt(7)
	v_add_f32_e32 v60, v60, v68
	s_waitcnt lgkmcnt(6)
	v_add_f32_e32 v61, v61, v70
	s_waitcnt lgkmcnt(5)
	v_add_f32_e32 v62, v62, v71
	s_waitcnt lgkmcnt(4)
	v_add_f32_e32 v65, v65, v74
	s_waitcnt lgkmcnt(3)
	v_add_f32_e32 v63, v63, v72
	s_waitcnt lgkmcnt(2)
	v_add_f32_e32 v64, v64, v73
	s_waitcnt lgkmcnt(1)
	v_add_f32_e32 v66, v66, v75
	ds_bpermute_b32 v68, v38, v60
	v_add_f32_e32 v70, 1.0, v77
	ds_bpermute_b32 v72, v38, v61
	ds_bpermute_b32 v74, v38, v62
	ds_bpermute_b32 v77, v38, v65
	s_waitcnt lgkmcnt(4)
	v_add_f32_e32 v67, v67, v76
	v_add_f32_e32 v71, 1.0, v78
	s_waitcnt vmcnt(6)
	v_lshlrev_b32_e32 v73, 16, v49
	v_and_b32_e32 v49, 0xffff0000, v49
	ds_bpermute_b32 v75, v38, v63
	ds_bpermute_b32 v76, v38, v64
	ds_bpermute_b32 v78, v38, v66
	ds_bpermute_b32 v79, v38, v67
	v_rcp_f32_e32 v70, v70
	v_mul_f32_e32 v80, 0xbfb8aa3b, v73
	v_mul_f32_e32 v81, 0xbfb8aa3b, v49
	v_rcp_f32_e32 v71, v71
	v_exp_f32_e32 v80, v80
	v_exp_f32_e32 v81, v81
	s_waitcnt lgkmcnt(7)
	v_add_f32_e32 v60, v60, v68
	s_waitcnt lgkmcnt(6)
	v_add_f32_e32 v61, v61, v72
	s_waitcnt lgkmcnt(5)
	v_add_f32_e32 v62, v62, v74
	s_waitcnt lgkmcnt(4)
	v_add_f32_e32 v65, v65, v77
	v_mul_f32_e32 v68, v70, v69
	s_waitcnt lgkmcnt(3)
	v_add_f32_e32 v63, v63, v75
	s_waitcnt lgkmcnt(2)
	v_add_f32_e32 v64, v64, v76
	s_waitcnt lgkmcnt(1)
	v_add_f32_e32 v66, v66, v78
	ds_bpermute_b32 v69, v39, v60
	ds_bpermute_b32 v70, v39, v61
	ds_bpermute_b32 v74, v39, v62
	ds_bpermute_b32 v78, v39, v65
	v_mul_f32_e32 v52, v71, v52
	s_waitcnt lgkmcnt(4)
	v_add_f32_e32 v67, v67, v79
	v_add_f32_e32 v71, 1.0, v80
	v_add_f32_e32 v72, 1.0, v81
	s_waitcnt vmcnt(5)
	v_lshlrev_b32_e32 v75, 16, v48
	ds_bpermute_b32 v76, v39, v63
	ds_bpermute_b32 v77, v39, v64
	ds_bpermute_b32 v79, v39, v66
	v_and_b32_e32 v48, 0xffff0000, v48
	ds_bpermute_b32 v80, v39, v67
	v_rcp_f32_e32 v71, v71
	v_rcp_f32_e32 v72, v72
	v_mul_f32_e32 v81, 0xbfb8aa3b, v75
	v_mul_f32_e32 v82, 0xbfb8aa3b, v48
	v_exp_f32_e32 v81, v81
	v_exp_f32_e32 v82, v82
	s_waitcnt lgkmcnt(7)
	v_add_f32_e32 v60, v60, v69
	s_waitcnt lgkmcnt(6)
	v_add_f32_e32 v61, v61, v70
	s_waitcnt lgkmcnt(5)
	v_add_f32_e32 v62, v62, v74
	s_waitcnt lgkmcnt(4)
	v_add_f32_e32 v65, v65, v78
	v_mul_f32_e32 v69, v71, v73
	v_mul_f32_e32 v49, v72, v49
	s_waitcnt lgkmcnt(3)
	v_add_f32_e32 v63, v63, v76
	s_waitcnt lgkmcnt(2)
	v_add_f32_e32 v64, v64, v77
	s_waitcnt lgkmcnt(1)
	v_add_f32_e32 v66, v66, v79
	ds_bpermute_b32 v70, v40, v60
	ds_bpermute_b32 v71, v40, v61
	ds_bpermute_b32 v72, v40, v62
	ds_bpermute_b32 v79, v40, v65
	s_waitcnt lgkmcnt(4)
	v_add_f32_e32 v67, v67, v80
	v_add_f32_e32 v73, 1.0, v81
	ds_bpermute_b32 v76, v40, v63
	ds_bpermute_b32 v78, v40, v64
	ds_bpermute_b32 v80, v40, v66
	v_add_f32_e32 v74, 1.0, v82
	s_waitcnt vmcnt(4)
	v_lshlrev_b32_e32 v77, 16, v47
	v_and_b32_e32 v47, 0xffff0000, v47
	v_rcp_f32_e32 v73, v73
	ds_bpermute_b32 v81, v40, v67
	v_rcp_f32_e32 v74, v74
	v_mul_f32_e32 v82, 0xbfb8aa3b, v77
	v_mul_f32_e32 v83, 0xbfb8aa3b, v47
	v_exp_f32_e32 v82, v82
	v_exp_f32_e32 v83, v83
	s_waitcnt lgkmcnt(7)
	v_add_f32_e32 v60, v60, v70
	s_waitcnt lgkmcnt(6)
	v_add_f32_e32 v61, v61, v71
	s_waitcnt lgkmcnt(5)
	v_add_f32_e32 v62, v62, v72
	s_waitcnt lgkmcnt(4)
	v_add_f32_e32 v65, v65, v79
	v_mul_f32_e32 v70, v73, v75
	s_waitcnt lgkmcnt(3)
	v_add_f32_e32 v63, v63, v76
	s_waitcnt lgkmcnt(2)
	v_add_f32_e32 v64, v64, v78
	s_waitcnt lgkmcnt(1)
	v_add_f32_e32 v66, v66, v80
	ds_bpermute_b32 v71, v41, v60
	ds_bpermute_b32 v72, v41, v61
	ds_bpermute_b32 v73, v41, v62
	ds_bpermute_b32 v80, v41, v65
	v_mul_f32_e32 v48, v74, v48
	ds_bpermute_b32 v74, v41, v63
	ds_bpermute_b32 v78, v41, v64
	s_waitcnt lgkmcnt(6)
	v_add_f32_e32 v67, v67, v81
	v_add_f32_e32 v75, 1.0, v82
	v_add_f32_e32 v76, 1.0, v83
	s_waitcnt vmcnt(3)
	v_lshlrev_b32_e32 v79, 16, v46
	v_and_b32_e32 v46, 0xffff0000, v46
	ds_bpermute_b32 v81, v41, v66
	v_rcp_f32_e32 v75, v75
	v_rcp_f32_e32 v76, v76
	v_mul_f32_e32 v84, 0xbfb8aa3b, v46
	ds_bpermute_b32 v82, v41, v67
	v_mul_f32_e32 v83, 0xbfb8aa3b, v79
	v_exp_f32_e32 v84, v84
	v_exp_f32_e32 v83, v83
	s_waitcnt lgkmcnt(7)
	v_add_f32_e32 v60, v60, v71
	s_waitcnt lgkmcnt(6)
	v_add_f32_e32 v61, v61, v72
	s_waitcnt lgkmcnt(5)
	v_add_f32_e32 v62, v62, v73
	s_waitcnt lgkmcnt(4)
	v_add_f32_e32 v65, v65, v80
	s_waitcnt lgkmcnt(3)
	v_add_f32_e32 v63, v63, v74
	s_waitcnt lgkmcnt(2)
	v_add_f32_e32 v64, v64, v78
	ds_bpermute_b32 v72, v42, v60
	ds_bpermute_b32 v73, v42, v61
	ds_bpermute_b32 v74, v42, v62
	ds_bpermute_b32 v80, v42, v65
	v_mul_f32_e32 v71, v75, v77
	v_mul_f32_e32 v47, v76, v47
	s_waitcnt lgkmcnt(5)
	v_add_f32_e32 v66, v66, v81
	ds_bpermute_b32 v75, v42, v63
	ds_bpermute_b32 v76, v42, v64
	s_waitcnt vmcnt(2)
	v_lshlrev_b32_e32 v81, 16, v45
	v_and_b32_e32 v45, 0xffff0000, v45
	v_add_f32_e32 v78, 1.0, v84
	v_mul_f32_e32 v84, 0xbfb8aa3b, v81
	v_mul_f32_e32 v85, 0xbfb8aa3b, v45
	s_waitcnt lgkmcnt(6)
	v_add_f32_e32 v67, v67, v82
	v_add_f32_e32 v77, 1.0, v83
	v_exp_f32_e32 v84, v84
	v_exp_f32_e32 v85, v85
	ds_bpermute_b32 v83, v42, v67
	v_rcp_f32_e32 v77, v77
	ds_bpermute_b32 v82, v42, v66
	s_waitcnt lgkmcnt(7)
	v_add_f32_e32 v60, v60, v72
	s_waitcnt lgkmcnt(6)
	v_add_f32_e32 v61, v61, v73
	s_waitcnt lgkmcnt(5)
	v_add_f32_e32 v62, v62, v74
	s_waitcnt lgkmcnt(4)
	v_add_f32_e32 v65, v65, v80
	s_waitcnt lgkmcnt(3)
	v_add_f32_e32 v63, v63, v75
	s_waitcnt lgkmcnt(2)
	v_add_f32_e32 v64, v64, v76
	v_fmamk_f32 v60, v60, 0x3c000000, v43
	v_fmamk_f32 v61, v61, 0x3c000000, v43
	v_fmamk_f32 v62, v62, 0x3c000000, v43
	v_fmamk_f32 v65, v65, 0x3c000000, v43
	s_waitcnt vmcnt(1)
	v_lshlrev_b32_e32 v75, 16, v44
	v_fmamk_f32 v63, v63, 0x3c000000, v43
	v_fmamk_f32 v64, v64, 0x3c000000, v43
	v_add_f32_e32 v73, 1.0, v84
	v_add_f32_e32 v74, 1.0, v85
	v_and_b32_e32 v44, 0xffff0000, v44
	v_rsq_f32_e32 v60, v60
	v_rsq_f32_e32 v61, v61
	v_rsq_f32_e32 v62, v62
	v_rsq_f32_e32 v65, v65
	v_mul_f32_e32 v76, 0xbfb8aa3b, v75
	v_mul_f32_e32 v72, v77, v79
	v_rsq_f32_e32 v63, v63
	v_rsq_f32_e32 v64, v64
	v_rcp_f32_e32 v73, v73
	v_rcp_f32_e32 v74, v74
	v_mul_f32_e32 v77, 0xbfb8aa3b, v44
	v_exp_f32_e32 v76, v76
	s_waitcnt lgkmcnt(1)
	v_add_f32_e32 v67, v67, v83
	v_exp_f32_e32 v77, v77
	v_rcp_f32_e32 v78, v78
	s_waitcnt lgkmcnt(0)
	v_add_f32_e32 v66, v66, v82
	v_fmamk_f32 v67, v67, 0x3c000000, v43
	v_fmamk_f32 v66, v66, 0x3c000000, v43
	v_rsq_f32_e32 v67, v67
	v_mul_f32_e32 v51, v60, v51
	v_mul_f32_e32 v0, v61, v0
	v_mul_f32_e32 v4, v61, v4
	v_mul_f32_e32 v54, v62, v54
	v_mul_f32_e32 v2, v65, v2
	v_mul_f32_e32 v6, v65, v6
	v_rsq_f32_e32 v66, v66
	v_mul_f32_e32 v53, v60, v53
	v_mul_f32_e32 v55, v62, v55
	v_mul_f32_e32 v1, v63, v1
	v_mul_f32_e32 v5, v63, v5
	v_mul_f32_e32 v56, v64, v56
	v_mul_f32_e32 v60, v73, v81
	v_mul_f32_e32 v45, v74, v45
	v_mul_f32_e32 v51, v8, v51
	v_mul_f32_e32 v0, v8, v0
	v_mul_f32_e32 v4, v9, v4
	v_mul_f32_e32 v54, v8, v54
	v_mul_f32_e32 v2, v8, v2
	v_mul_f32_e32 v6, v9, v6
	v_add_f32_e32 v61, 1.0, v76
	s_waitcnt vmcnt(0)
	v_lshlrev_b32_e32 v63, 16, v50
	v_mul_f32_e32 v57, v64, v57
	v_mul_f32_e32 v53, v9, v53
	v_mul_f32_e32 v55, v9, v55
	v_mul_f32_e32 v1, v8, v1
	v_mul_f32_e32 v5, v9, v5
	v_mul_f32_e32 v56, v8, v56
	v_add_f32_e32 v62, 1.0, v77
	v_and_b32_e32 v50, 0xffff0000, v50
	v_mul_f32_e32 v51, v68, v51
	v_mul_f32_e32 v0, v69, v0
	v_mul_f32_e32 v4, v49, v4
	v_mul_f32_e32 v49, v70, v54
	v_mul_f32_e32 v2, v60, v2
	v_mul_f32_e32 v6, v45, v6
	v_rcp_f32_e32 v45, v61
	v_mul_f32_e32 v54, 0xbfb8aa3b, v63
	v_mul_f32_e32 v46, v78, v46
	v_mul_f32_e32 v57, v9, v57
	v_mul_f32_e32 v52, v52, v53
	v_mul_f32_e32 v48, v48, v55
	v_mul_f32_e32 v1, v71, v1
	v_mul_f32_e32 v5, v47, v5
	v_mul_f32_e32 v47, v72, v56
	v_rcp_f32_e32 v53, v62
	v_mul_f32_e32 v55, 0xbfb8aa3b, v50
	v_bfe_u32 v56, v51, 16, 1
	v_bfe_u32 v60, v0, 16, 1
	v_bfe_u32 v69, v2, 16, 1
	v_exp_f32_e32 v54, v54
	v_mul_f32_e32 v3, v67, v3
	v_mul_f32_e32 v7, v67, v7
	v_mul_f32_e32 v46, v46, v57
	v_bfe_u32 v57, v52, 16, 1
	v_bfe_u32 v61, v4, 16, 1
	v_bfe_u32 v62, v49, 16, 1
	v_bfe_u32 v65, v1, 16, 1
	v_bfe_u32 v67, v47, 16, 1
	v_bfe_u32 v70, v6, 16, 1
	v_exp_f32_e32 v55, v55
	v_add3_u32 v51, v51, v56, s30
	v_add3_u32 v0, v0, v60, s30
	v_add3_u32 v2, v2, v69, s30
	s_mov_b32 s27, s25
	s_mov_b32 s23, s25
	s_mov_b32 s19, s25
	s_mov_b32 s17, s25
	s_mov_b32 s15, s25
	s_mov_b32 s13, s25
	s_mov_b32 s11, s25
	s_lshl_b64 s[24:25], s[24:25], 11
	v_mul_f32_e32 v58, v66, v58
	v_mul_f32_e32 v59, v66, v59
	v_bfe_u32 v64, v48, 16, 1
	v_bfe_u32 v66, v5, 16, 1
	v_bfe_u32 v68, v46, 16, 1
	v_add3_u32 v52, v52, v57, s30
	v_add3_u32 v4, v4, v61, s30
	v_add3_u32 v49, v49, v62, s30
	v_add3_u32 v1, v1, v65, s30
	v_add3_u32 v47, v47, v67, s30
	v_add3_u32 v6, v6, v70, s30
	v_lshrrev_b32_e32 v51, 16, v51
	v_lshrrev_b32_e32 v0, 16, v0
	v_lshrrev_b32_e32 v2, 16, v2
	s_lshl_b64 s[26:27], s[26:27], 11
	s_lshl_b64 s[22:23], s[22:23], 11
	s_lshl_b64 s[18:19], s[18:19], 11
	s_lshl_b64 s[16:17], s[16:17], 11
	s_lshl_b64 s[14:15], s[14:15], 11
	v_lshl_add_u64 v[24:25], v[20:21], 0, s[24:25]
	v_mul_f32_e32 v58, v8, v58
	v_add3_u32 v48, v48, v64, s30
	v_add3_u32 v5, v5, v66, s30
	v_add3_u32 v46, v46, v68, s30
	v_lshrrev_b32_e32 v49, 16, v49
	v_lshrrev_b32_e32 v1, 16, v1
	v_lshrrev_b32_e32 v47, 16, v47
	v_and_or_b32 v51, v52, s29, v51
	v_and_or_b32 v0, v4, s29, v0
	v_and_or_b32 v2, v6, s29, v2
	v_mul_f32_e32 v6, v45, v75
	v_lshl_add_u64 v[26:27], v[20:21], 0, s[26:27]
	v_lshl_add_u64 v[28:29], v[20:21], 0, s[22:23]
	v_lshl_add_u64 v[30:31], v[20:21], 0, s[18:19]
	v_lshl_add_u64 v[32:33], v[20:21], 0, s[16:17]
	v_lshl_add_u64 v[34:35], v[20:21], 0, s[14:15]
	v_mul_f32_e32 v59, v9, v59
	v_and_or_b32 v4, v48, s29, v49
	v_and_or_b32 v1, v5, s29, v1
	v_and_or_b32 v5, v46, s29, v47
	v_mul_f32_e32 v44, v53, v44
	global_store_dword v[24:25], v51, off sc1
	global_store_dword v[26:27], v0, off sc1
	global_store_dword v[28:29], v4, off sc1
	global_store_dword v[30:31], v1, off sc1
	global_store_dword v[32:33], v5, off sc1
	global_store_dword v[34:35], v2, off sc1
	v_mul_f32_e32 v0, v6, v58
	v_add_f32_e32 v2, 1.0, v54
	v_mul_f32_e32 v1, v44, v59
	v_add_f32_e32 v4, 1.0, v55
	v_bfe_u32 v5, v0, 16, 1
	v_rcp_f32_e32 v2, v2
	v_bfe_u32 v6, v1, 16, 1
	v_rcp_f32_e32 v4, v4
	v_add3_u32 v0, v0, v5, s30
	s_lshl_b64 s[12:13], s[12:13], 11
	v_add3_u32 v1, v1, v6, s30
	v_lshrrev_b32_e32 v0, 16, v0
	v_lshl_add_u64 v[22:23], v[20:21], 0, s[12:13]
	v_and_or_b32 v0, v1, s29, v0
	v_mul_f32_e32 v3, v8, v3
	global_store_dword v[22:23], v0, off sc1
	v_mul_f32_e32 v0, v2, v63
	s_lshl_b64 s[10:11], s[10:11], 11
	v_mul_f32_e32 v7, v9, v7
	v_mul_f32_e32 v1, v4, v50
	v_mul_f32_e32 v0, v0, v3
	s_add_u32 s4, s4, s78
	v_mul_f32_e32 v1, v1, v7
	v_bfe_u32 v2, v0, 16, 1
	s_addc_u32 s5, s5, s0
	v_bfe_u32 v3, v1, 16, 1
	v_add3_u32 v0, v0, v2, s30
	v_cmp_lt_i64_e32 vcc, s[4:5], v[18:19]
	v_add3_u32 v1, v1, v3, s30
	v_lshrrev_b32_e32 v0, 16, v0
	v_lshl_add_u64 v[20:21], v[20:21], 0, s[10:11]
	v_and_or_b32 v0, v1, s29, v0
	global_store_dword v[20:21], v0, off sc1
	s_cbranch_vccnz .LBB0_2592
